# t8 + balanced LDS-DMA staging in all MT=5 K-loops too (5/4 pieces per load segment, row groups rb0-3/rb4-5/rb6-9 re-owned by wave half)
# baseline (speedup 1.0000x reference)
.LBB0_650:
	v_add_u32_e32 v174, 0x14000, v223
	v_add_u32_e32 v190, 0x18000, v223
	ds_read_b128 v[162:165], v174
	ds_read_b128 v[166:169], v174 offset:1024
	ds_read_b128 v[170:173], v174 offset:2048
	ds_read_b128 v[174:177], v174 offset:3072
	ds_read_b128 v[178:181], v190
	ds_read_b128 v[182:185], v190 offset:1024
	ds_read_b128 v[186:189], v190 offset:2048
	ds_read_b128 v[190:193], v190 offset:3072
	s_add_u32 s6, s4, 0xffe52080
	s_addc_u32 s7, s5, -1
	s_cmpk_eq_i32 s84, 0x52
	s_cselect_b32 s6, s22, s6
	s_cselect_b32 s7, s23, s7
	s_cselect_b32 s12, s24, s70
	s_cselect_b32 s13, s25, s72
	ds_read_b128 v[194:197], v221
	ds_read_b128 v[198:201], v221 offset:1024
	ds_read_b128 v[202:205], v221 offset:2048
	ds_read_b128 v[206:209], v221 offset:3072
	ds_read_b128 v[210:213], v221 offset:4096
	ds_read_b128 v[214:217], v221 offset:5120
	ds_read_b128 v[228:231], v221 offset:6144
	ds_read_b128 v[238:241], v221 offset:7168
	ds_read_b128 v[242:245], v221 offset:8192
	ds_read_b128 v[246:249], v221 offset:9216
	s_add_u32 s74, s6, 0xfffaa000
	s_addc_u32 s75, s7, -1
	s_add_i32 m0, s28, 0xfffff000
	s_nop 0
	global_load_lds_dwordx4 v0, s[74:75]
	s_mov_b32 s74, s6
	s_mov_b32 s75, s7
	s_mov_b32 m0, s28
	s_nop 0
	global_load_lds_dwordx4 v0, s[74:75]
	s_add_u32 s74, s4, 0xac000
	s_addc_u32 s75, s5, 0
	s_add_i32 m0, s28, 0x11000
	s_nop 0
	global_load_lds_dwordx4 v0, s[74:75]
	s_add_u32 s74, s4, 0x102000
	s_addc_u32 s75, s5, 0
	s_add_i32 m0, s28, 0x12000
	s_nop 0
	global_load_lds_dwordx4 v0, s[74:75]
	s_add_u32 s74, s4, 0x56000
	s_addc_u32 s75, s5, 0
	s_add_i32 m0, s28, 0x10000
	s_nop 0
	global_load_lds_dwordx4 v0, s[74:75]
	s_waitcnt vmcnt(9)
	s_waitcnt lgkmcnt(0)
	s_barrier
	v_mfma_f32_16x16x32_bf16 v[158:161], v[162:165], v[194:197], v[158:161]
	v_mfma_f32_16x16x32_bf16 v[154:157], v[170:173], v[194:197], v[154:157]
	v_mfma_f32_16x16x32_bf16 v[142:145], v[162:165], v[202:205], v[142:145]
	v_mfma_f32_16x16x32_bf16 v[138:141], v[170:173], v[202:205], v[138:141]
	v_mfma_f32_16x16x32_bf16 v[126:129], v[162:165], v[210:213], v[126:129]
	v_mfma_f32_16x16x32_bf16 v[122:125], v[170:173], v[210:213], v[122:125]
	v_mfma_f32_16x16x32_bf16 v[110:113], v[162:165], v[228:231], v[110:113]
	v_mfma_f32_16x16x32_bf16 v[106:109], v[170:173], v[228:231], v[106:109]
	v_mfma_f32_16x16x32_bf16 v[94:97], v[162:165], v[242:245], v[94:97]
	v_mfma_f32_16x16x32_bf16 v[90:93], v[170:173], v[242:245], v[90:93]
	v_mfma_f32_16x16x32_bf16 v[158:161], v[166:169], v[198:201], v[158:161]
	v_mfma_f32_16x16x32_bf16 v[154:157], v[174:177], v[198:201], v[154:157]
	v_mfma_f32_16x16x32_bf16 v[142:145], v[166:169], v[206:209], v[142:145]
	v_mfma_f32_16x16x32_bf16 v[138:141], v[174:177], v[206:209], v[138:141]
	v_mfma_f32_16x16x32_bf16 v[126:129], v[166:169], v[214:217], v[126:129]
	v_mfma_f32_16x16x32_bf16 v[122:125], v[174:177], v[214:217], v[122:125]
	v_mfma_f32_16x16x32_bf16 v[110:113], v[166:169], v[238:241], v[110:113]
	v_mfma_f32_16x16x32_bf16 v[106:109], v[174:177], v[238:241], v[106:109]
	v_mfma_f32_16x16x32_bf16 v[94:97], v[166:169], v[246:249], v[94:97]
	v_mfma_f32_16x16x32_bf16 v[90:93], v[174:177], v[246:249], v[90:93]
	v_mfma_f32_16x16x32_bf16 v[150:153], v[178:181], v[194:197], v[150:153]
	v_mfma_f32_16x16x32_bf16 v[146:149], v[186:189], v[194:197], v[146:149]
	v_mfma_f32_16x16x32_bf16 v[134:137], v[178:181], v[202:205], v[134:137]
	v_mfma_f32_16x16x32_bf16 v[130:133], v[186:189], v[202:205], v[130:133]
	v_mfma_f32_16x16x32_bf16 v[118:121], v[178:181], v[210:213], v[118:121]
	v_mfma_f32_16x16x32_bf16 v[114:117], v[186:189], v[210:213], v[114:117]
	v_mfma_f32_16x16x32_bf16 v[102:105], v[178:181], v[228:231], v[102:105]
	v_mfma_f32_16x16x32_bf16 v[98:101], v[186:189], v[228:231], v[98:101]
	v_mfma_f32_16x16x32_bf16 v[86:89], v[178:181], v[242:245], v[86:89]
	v_mfma_f32_16x16x32_bf16 v[82:85], v[186:189], v[242:245], v[82:85]
	v_mfma_f32_16x16x32_bf16 v[150:153], v[182:185], v[198:201], v[150:153]
	v_mfma_f32_16x16x32_bf16 v[146:149], v[190:193], v[198:201], v[146:149]
	v_mfma_f32_16x16x32_bf16 v[134:137], v[182:185], v[206:209], v[134:137]
	v_mfma_f32_16x16x32_bf16 v[130:133], v[190:193], v[206:209], v[130:133]
	v_mfma_f32_16x16x32_bf16 v[118:121], v[182:185], v[214:217], v[118:121]
	v_mfma_f32_16x16x32_bf16 v[114:117], v[190:193], v[214:217], v[114:117]
	v_mfma_f32_16x16x32_bf16 v[102:105], v[182:185], v[238:241], v[102:105]
	v_mfma_f32_16x16x32_bf16 v[98:101], v[190:193], v[238:241], v[98:101]
	v_mfma_f32_16x16x32_bf16 v[86:89], v[182:185], v[246:249], v[86:89]
	v_mfma_f32_16x16x32_bf16 v[82:85], v[190:193], v[246:249], v[82:85]
	s_barrier
	ds_read_b128 v[194:197], v221 offset:20480
	ds_read_b128 v[198:201], v221 offset:21504
	ds_read_b128 v[202:205], v221 offset:22528
	ds_read_b128 v[206:209], v221 offset:23552
	ds_read_b128 v[210:213], v221 offset:24576
	ds_read_b128 v[214:217], v221 offset:25600
	ds_read_b128 v[228:231], v221 offset:26624
	ds_read_b128 v[238:241], v221 offset:27648
	ds_read_b128 v[242:245], v221 offset:28672
	ds_read_b128 v[246:249], v221 offset:29696
	s_add_u32 s74, s12, 0x102000
	s_addc_u32 s75, s13, 0
	s_add_i32 m0, s28, 0x17000
	s_nop 0
	global_load_lds_dwordx4 v220, s[74:75]
	s_add_u32 s74, s12, 0x158000
	s_addc_u32 s75, s13, 0
	s_add_i32 m0, s28, 0x18000
	s_nop 0
	global_load_lds_dwordx4 v220, s[74:75]
	s_add_u32 s74, s12, 0x1ae000
	s_addc_u32 s75, s13, 0
	s_add_i32 m0, s28, 0x19000
	s_nop 0
	global_load_lds_dwordx4 v220, s[74:75]
	s_add_u32 s74, s12, 0x204000
	s_addc_u32 s75, s13, 0
	s_add_i32 m0, s28, 0x1a000
	s_nop 0
	global_load_lds_dwordx4 v220, s[74:75]
	s_waitcnt vmcnt(9)
	s_waitcnt lgkmcnt(0)
	s_barrier
	v_mfma_f32_16x16x32_bf16 v[78:81], v[162:165], v[194:197], v[78:81]
	v_mfma_f32_16x16x32_bf16 v[74:77], v[170:173], v[194:197], v[74:77]
	v_mfma_f32_16x16x32_bf16 v[62:65], v[162:165], v[202:205], v[62:65]
	v_mfma_f32_16x16x32_bf16 v[58:61], v[170:173], v[202:205], v[58:61]
	v_mfma_f32_16x16x32_bf16 v[46:49], v[162:165], v[210:213], v[46:49]
	v_mfma_f32_16x16x32_bf16 v[42:45], v[170:173], v[210:213], v[42:45]
	v_mfma_f32_16x16x32_bf16 v[30:33], v[162:165], v[228:231], v[30:33]
	v_mfma_f32_16x16x32_bf16 v[26:29], v[170:173], v[228:231], v[26:29]
	v_mfma_f32_16x16x32_bf16 v[14:17], v[162:165], v[242:245], v[14:17]
	v_mfma_f32_16x16x32_bf16 v[10:13], v[170:173], v[242:245], v[10:13]
	v_mfma_f32_16x16x32_bf16 v[78:81], v[166:169], v[198:201], v[78:81]
	v_mfma_f32_16x16x32_bf16 v[74:77], v[174:177], v[198:201], v[74:77]
	v_mfma_f32_16x16x32_bf16 v[62:65], v[166:169], v[206:209], v[62:65]
	v_mfma_f32_16x16x32_bf16 v[58:61], v[174:177], v[206:209], v[58:61]
	v_mfma_f32_16x16x32_bf16 v[46:49], v[166:169], v[214:217], v[46:49]
	v_mfma_f32_16x16x32_bf16 v[42:45], v[174:177], v[214:217], v[42:45]
	v_mfma_f32_16x16x32_bf16 v[30:33], v[166:169], v[238:241], v[30:33]
	v_mfma_f32_16x16x32_bf16 v[26:29], v[174:177], v[238:241], v[26:29]
	v_mfma_f32_16x16x32_bf16 v[14:17], v[166:169], v[246:249], v[14:17]
	v_mfma_f32_16x16x32_bf16 v[10:13], v[174:177], v[246:249], v[10:13]
	v_mfma_f32_16x16x32_bf16 v[70:73], v[178:181], v[194:197], v[70:73]
	v_mfma_f32_16x16x32_bf16 v[66:69], v[186:189], v[194:197], v[66:69]
	v_mfma_f32_16x16x32_bf16 v[54:57], v[178:181], v[202:205], v[54:57]
	v_mfma_f32_16x16x32_bf16 v[50:53], v[186:189], v[202:205], v[50:53]
	v_mfma_f32_16x16x32_bf16 v[38:41], v[178:181], v[210:213], v[38:41]
	v_mfma_f32_16x16x32_bf16 v[34:37], v[186:189], v[210:213], v[34:37]
	v_mfma_f32_16x16x32_bf16 v[22:25], v[178:181], v[228:231], v[22:25]
	v_mfma_f32_16x16x32_bf16 v[18:21], v[186:189], v[228:231], v[18:21]
	v_mfma_f32_16x16x32_bf16 v[6:9], v[178:181], v[242:245], v[6:9]
	v_mfma_f32_16x16x32_bf16 v[2:5], v[186:189], v[242:245], v[2:5]
	v_mfma_f32_16x16x32_bf16 v[70:73], v[182:185], v[198:201], v[70:73]
	v_mfma_f32_16x16x32_bf16 v[66:69], v[190:193], v[198:201], v[66:69]
	v_mfma_f32_16x16x32_bf16 v[54:57], v[182:185], v[206:209], v[54:57]
	v_mfma_f32_16x16x32_bf16 v[50:53], v[190:193], v[206:209], v[50:53]
	v_mfma_f32_16x16x32_bf16 v[38:41], v[182:185], v[214:217], v[38:41]
	v_mfma_f32_16x16x32_bf16 v[34:37], v[190:193], v[214:217], v[34:37]
	v_mfma_f32_16x16x32_bf16 v[22:25], v[182:185], v[238:241], v[22:25]
	v_mfma_f32_16x16x32_bf16 v[18:21], v[190:193], v[238:241], v[18:21]
	v_mfma_f32_16x16x32_bf16 v[6:9], v[182:185], v[246:249], v[6:9]
	v_mfma_f32_16x16x32_bf16 v[2:5], v[190:193], v[246:249], v[2:5]
	s_barrier
	v_add_u32_e32 v174, 0x1c000, v223
	v_add_u32_e32 v190, 0x20000, v223
	ds_read_b128 v[162:165], v174
	ds_read_b128 v[166:169], v174 offset:1024
	ds_read_b128 v[170:173], v174 offset:2048
	ds_read_b128 v[174:177], v174 offset:3072
	ds_read_b128 v[178:181], v190
	ds_read_b128 v[182:185], v190 offset:1024
	ds_read_b128 v[186:189], v190 offset:2048
	ds_read_b128 v[190:193], v190 offset:3072
	ds_read_b128 v[194:197], v221 offset:40960
	ds_read_b128 v[198:201], v221 offset:41984
	ds_read_b128 v[202:205], v221 offset:43008
	ds_read_b128 v[206:209], v221 offset:44032
	ds_read_b128 v[210:213], v221 offset:45056
	ds_read_b128 v[214:217], v221 offset:46080
	ds_read_b128 v[228:231], v221 offset:47104
	ds_read_b128 v[238:241], v221 offset:48128
	ds_read_b128 v[242:245], v221 offset:49152
	ds_read_b128 v[246:249], v221 offset:50176
	s_add_u32 s74, s6, 0xfffaa080
	s_addc_u32 s75, s7, -1
	s_add_i32 m0, s28, 0x9000
	s_nop 0
	global_load_lds_dwordx4 v0, s[74:75]
	s_add_u32 s74, s6, 0x80
	s_addc_u32 s75, s7, 0
	s_add_i32 m0, s28, 0xa000
	s_nop 0
	global_load_lds_dwordx4 v0, s[74:75]
	s_add_u32 s74, s6, 0x25a000
	s_addc_u32 s75, s7, 0
	s_add_i32 m0, s28, 0x7000
	s_nop 0
	global_load_lds_dwordx4 v0, s[74:75]
	s_add_u32 s74, s6, 0x2b0000
	s_addc_u32 s75, s7, 0
	s_add_i32 m0, s28, 0x8000
	s_nop 0
	global_load_lds_dwordx4 v0, s[74:75]
	s_add_u32 s74, s6, 0x204000
	s_addc_u32 s75, s7, 0
	s_add_i32 m0, s28, 0x6000
	s_nop 0
	global_load_lds_dwordx4 v0, s[74:75]
	s_waitcnt vmcnt(9)
	s_waitcnt lgkmcnt(0)
	s_barrier
	v_mfma_f32_16x16x32_bf16 v[158:161], v[162:165], v[194:197], v[158:161]
	v_mfma_f32_16x16x32_bf16 v[154:157], v[170:173], v[194:197], v[154:157]
	v_mfma_f32_16x16x32_bf16 v[142:145], v[162:165], v[202:205], v[142:145]
	v_mfma_f32_16x16x32_bf16 v[138:141], v[170:173], v[202:205], v[138:141]
	v_mfma_f32_16x16x32_bf16 v[126:129], v[162:165], v[210:213], v[126:129]
	v_mfma_f32_16x16x32_bf16 v[122:125], v[170:173], v[210:213], v[122:125]
	v_mfma_f32_16x16x32_bf16 v[110:113], v[162:165], v[228:231], v[110:113]
	v_mfma_f32_16x16x32_bf16 v[106:109], v[170:173], v[228:231], v[106:109]
	v_mfma_f32_16x16x32_bf16 v[94:97], v[162:165], v[242:245], v[94:97]
	v_mfma_f32_16x16x32_bf16 v[90:93], v[170:173], v[242:245], v[90:93]
	v_mfma_f32_16x16x32_bf16 v[158:161], v[166:169], v[198:201], v[158:161]
	v_mfma_f32_16x16x32_bf16 v[154:157], v[174:177], v[198:201], v[154:157]
	v_mfma_f32_16x16x32_bf16 v[142:145], v[166:169], v[206:209], v[142:145]
	v_mfma_f32_16x16x32_bf16 v[138:141], v[174:177], v[206:209], v[138:141]
	v_mfma_f32_16x16x32_bf16 v[126:129], v[166:169], v[214:217], v[126:129]
	v_mfma_f32_16x16x32_bf16 v[122:125], v[174:177], v[214:217], v[122:125]
	v_mfma_f32_16x16x32_bf16 v[110:113], v[166:169], v[238:241], v[110:113]
	v_mfma_f32_16x16x32_bf16 v[106:109], v[174:177], v[238:241], v[106:109]
	v_mfma_f32_16x16x32_bf16 v[94:97], v[166:169], v[246:249], v[94:97]
	v_mfma_f32_16x16x32_bf16 v[90:93], v[174:177], v[246:249], v[90:93]
	v_mfma_f32_16x16x32_bf16 v[150:153], v[178:181], v[194:197], v[150:153]
	v_mfma_f32_16x16x32_bf16 v[146:149], v[186:189], v[194:197], v[146:149]
	v_mfma_f32_16x16x32_bf16 v[134:137], v[178:181], v[202:205], v[134:137]
	v_mfma_f32_16x16x32_bf16 v[130:133], v[186:189], v[202:205], v[130:133]
	v_mfma_f32_16x16x32_bf16 v[118:121], v[178:181], v[210:213], v[118:121]
	v_mfma_f32_16x16x32_bf16 v[114:117], v[186:189], v[210:213], v[114:117]
	v_mfma_f32_16x16x32_bf16 v[102:105], v[178:181], v[228:231], v[102:105]
	v_mfma_f32_16x16x32_bf16 v[98:101], v[186:189], v[228:231], v[98:101]
	v_mfma_f32_16x16x32_bf16 v[86:89], v[178:181], v[242:245], v[86:89]
	v_mfma_f32_16x16x32_bf16 v[82:85], v[186:189], v[242:245], v[82:85]
	v_mfma_f32_16x16x32_bf16 v[150:153], v[182:185], v[198:201], v[150:153]
	v_mfma_f32_16x16x32_bf16 v[146:149], v[190:193], v[198:201], v[146:149]
	v_mfma_f32_16x16x32_bf16 v[134:137], v[182:185], v[206:209], v[134:137]
	v_mfma_f32_16x16x32_bf16 v[130:133], v[190:193], v[206:209], v[130:133]
	v_mfma_f32_16x16x32_bf16 v[118:121], v[182:185], v[214:217], v[118:121]
	v_mfma_f32_16x16x32_bf16 v[114:117], v[190:193], v[214:217], v[114:117]
	v_mfma_f32_16x16x32_bf16 v[102:105], v[182:185], v[238:241], v[102:105]
	v_mfma_f32_16x16x32_bf16 v[98:101], v[190:193], v[238:241], v[98:101]
	v_mfma_f32_16x16x32_bf16 v[86:89], v[182:185], v[246:249], v[86:89]
	v_mfma_f32_16x16x32_bf16 v[82:85], v[190:193], v[246:249], v[82:85]
	s_barrier
	ds_read_b128 v[194:197], v221 offset:61440
	ds_read_b128 v[198:201], v221 offset:62464
	ds_read_b128 v[202:205], v221 offset:63488
	ds_read_b128 v[206:209], v221 offset:64512
	ds_read_b128 v[210:213], v222 offset:4096
	ds_read_b128 v[214:217], v222 offset:5120
	ds_read_b128 v[228:231], v222 offset:6144
	ds_read_b128 v[238:241], v222 offset:7168
	ds_read_b128 v[242:245], v222 offset:8192
	ds_read_b128 v[246:249], v222 offset:9216
	s_add_u32 s74, s12, 0x102080
	s_addc_u32 s75, s13, 0
	s_add_i32 m0, s28, 0x1f000
	s_nop 0
	global_load_lds_dwordx4 v220, s[74:75]
	s_add_u32 s74, s12, 0x158080
	s_addc_u32 s75, s13, 0
	s_add_i32 m0, s28, 0x20000
	s_nop 0
	global_load_lds_dwordx4 v220, s[74:75]
	s_add_u32 s74, s12, 0x1ae080
	s_addc_u32 s75, s13, 0
	s_add_i32 m0, s28, 0x21000
	s_nop 0
	global_load_lds_dwordx4 v220, s[74:75]
	s_add_u32 s74, s12, 0x204080
	s_addc_u32 s75, s13, 0
	s_add_i32 m0, s28, 0x22000
	s_nop 0
	global_load_lds_dwordx4 v220, s[74:75]
	s_waitcnt vmcnt(9)
	s_waitcnt lgkmcnt(0)
	s_barrier
	v_mfma_f32_16x16x32_bf16 v[78:81], v[162:165], v[194:197], v[78:81]
	v_mfma_f32_16x16x32_bf16 v[74:77], v[170:173], v[194:197], v[74:77]
	v_mfma_f32_16x16x32_bf16 v[62:65], v[162:165], v[202:205], v[62:65]
	v_mfma_f32_16x16x32_bf16 v[58:61], v[170:173], v[202:205], v[58:61]
	v_mfma_f32_16x16x32_bf16 v[46:49], v[162:165], v[210:213], v[46:49]
	v_mfma_f32_16x16x32_bf16 v[42:45], v[170:173], v[210:213], v[42:45]
	v_mfma_f32_16x16x32_bf16 v[30:33], v[162:165], v[228:231], v[30:33]
	v_mfma_f32_16x16x32_bf16 v[26:29], v[170:173], v[228:231], v[26:29]
	v_mfma_f32_16x16x32_bf16 v[14:17], v[162:165], v[242:245], v[14:17]
	v_mfma_f32_16x16x32_bf16 v[10:13], v[170:173], v[242:245], v[10:13]
	v_mfma_f32_16x16x32_bf16 v[78:81], v[166:169], v[198:201], v[78:81]
	v_mfma_f32_16x16x32_bf16 v[74:77], v[174:177], v[198:201], v[74:77]
	v_mfma_f32_16x16x32_bf16 v[62:65], v[166:169], v[206:209], v[62:65]
	v_mfma_f32_16x16x32_bf16 v[58:61], v[174:177], v[206:209], v[58:61]
	v_mfma_f32_16x16x32_bf16 v[46:49], v[166:169], v[214:217], v[46:49]
	v_mfma_f32_16x16x32_bf16 v[42:45], v[174:177], v[214:217], v[42:45]
	v_mfma_f32_16x16x32_bf16 v[30:33], v[166:169], v[238:241], v[30:33]
	v_mfma_f32_16x16x32_bf16 v[26:29], v[174:177], v[238:241], v[26:29]
	v_mfma_f32_16x16x32_bf16 v[14:17], v[166:169], v[246:249], v[14:17]
	v_mfma_f32_16x16x32_bf16 v[10:13], v[174:177], v[246:249], v[10:13]
	v_mfma_f32_16x16x32_bf16 v[70:73], v[178:181], v[194:197], v[70:73]
	v_mfma_f32_16x16x32_bf16 v[66:69], v[186:189], v[194:197], v[66:69]
	v_mfma_f32_16x16x32_bf16 v[54:57], v[178:181], v[202:205], v[54:57]
	v_mfma_f32_16x16x32_bf16 v[50:53], v[186:189], v[202:205], v[50:53]
	v_mfma_f32_16x16x32_bf16 v[38:41], v[178:181], v[210:213], v[38:41]
	v_mfma_f32_16x16x32_bf16 v[34:37], v[186:189], v[210:213], v[34:37]
	v_mfma_f32_16x16x32_bf16 v[22:25], v[178:181], v[228:231], v[22:25]
	v_mfma_f32_16x16x32_bf16 v[18:21], v[186:189], v[228:231], v[18:21]
	v_mfma_f32_16x16x32_bf16 v[6:9], v[178:181], v[242:245], v[6:9]
	v_mfma_f32_16x16x32_bf16 v[2:5], v[186:189], v[242:245], v[2:5]
	v_mfma_f32_16x16x32_bf16 v[70:73], v[182:185], v[198:201], v[70:73]
	v_mfma_f32_16x16x32_bf16 v[66:69], v[190:193], v[198:201], v[66:69]
	v_mfma_f32_16x16x32_bf16 v[54:57], v[182:185], v[206:209], v[54:57]
	v_mfma_f32_16x16x32_bf16 v[50:53], v[190:193], v[206:209], v[50:53]
	v_mfma_f32_16x16x32_bf16 v[38:41], v[182:185], v[214:217], v[38:41]
	v_mfma_f32_16x16x32_bf16 v[34:37], v[190:193], v[214:217], v[34:37]
	v_mfma_f32_16x16x32_bf16 v[22:25], v[182:185], v[238:241], v[22:25]
	v_mfma_f32_16x16x32_bf16 v[18:21], v[190:193], v[238:241], v[18:21]
	v_mfma_f32_16x16x32_bf16 v[6:9], v[182:185], v[246:249], v[6:9]
	v_mfma_f32_16x16x32_bf16 v[2:5], v[190:193], v[246:249], v[2:5]
	s_barrier
	s_add_i32 s84, s84, 2
	s_add_u32 s4, s4, 0x100
	s_addc_u32 s5, s5, 0
	s_add_u32 s70, s70, 0x100
	s_addc_u32 s72, s72, 0
	s_cmpk_gt_u32 s84, 0x53
	s_cbranch_scc0 .LBB0_650
	s_and_b64 vcc, exec, s[20:21]
	s_cbranch_vccz .LBB0_653
	s_barrier

.LBB0_716:
	v_add_u32_e32 v174, 0x14000, v223
	v_add_u32_e32 v190, 0x18000, v223
	ds_read_b128 v[162:165], v174
	ds_read_b128 v[166:169], v174 offset:1024
	ds_read_b128 v[170:173], v174 offset:2048
	ds_read_b128 v[174:177], v174 offset:3072
	ds_read_b128 v[178:181], v190
	ds_read_b128 v[182:185], v190 offset:1024
	ds_read_b128 v[186:189], v190 offset:2048
	ds_read_b128 v[190:193], v190 offset:3072
	s_add_u32 s6, s4, 0xffe52080
	s_addc_u32 s7, s5, -1
	s_cmpk_eq_i32 vcc_hi, 0x52
	s_cselect_b32 s6, s22, s6
	s_cselect_b32 s7, s23, s7
	s_cselect_b32 s12, s24, s97
	s_cselect_b32 s13, s25, vcc_lo
	ds_read_b128 v[194:197], v221
	ds_read_b128 v[198:201], v221 offset:1024
	ds_read_b128 v[210:213], v221 offset:2048
	ds_read_b128 v[214:217], v221 offset:3072
	ds_read_b128 v[242:245], v221 offset:4096
	ds_read_b128 v[246:249], v221 offset:5120
	ds_read_b128 v[238:241], v221 offset:6144
	ds_read_b128 v[202:205], v221 offset:7168
	ds_read_b128 v[206:209], v221 offset:8192
	ds_read_b128 v[228:231], v221 offset:9216
	s_add_u32 s74, s4, 0xfff54000
	s_addc_u32 s75, s5, -1
	s_add_i32 m0, s28, 0xd000
	s_nop 0
	global_load_lds_dwordx4 v0, s[74:75]
	s_add_u32 s74, s4, 0xfffaa000
	s_addc_u32 s75, s5, -1
	s_add_i32 m0, s28, 0xe000
	s_nop 0
	global_load_lds_dwordx4 v0, s[74:75]
	s_mov_b32 s74, s4
	s_mov_b32 s75, s5
	s_add_i32 m0, s28, 0xf000
	s_nop 0
	global_load_lds_dwordx4 v0, s[74:75]
	s_add_u32 s74, s4, 0x56000
	s_addc_u32 s75, s5, 0
	s_add_i32 m0, s28, 0x10000
	s_nop 0
	global_load_lds_dwordx4 v0, s[74:75]
	s_waitcnt vmcnt(9)
	s_waitcnt lgkmcnt(0)
	s_barrier
	v_mfma_f32_16x16x32_bf16 v[158:161], v[162:165], v[194:197], v[158:161]
	v_mfma_f32_16x16x32_bf16 v[154:157], v[170:173], v[194:197], v[154:157]
	v_mfma_f32_16x16x32_bf16 v[142:145], v[162:165], v[210:213], v[142:145]
	v_mfma_f32_16x16x32_bf16 v[138:141], v[170:173], v[210:213], v[138:141]
	v_mfma_f32_16x16x32_bf16 v[126:129], v[162:165], v[242:245], v[126:129]
	v_mfma_f32_16x16x32_bf16 v[122:125], v[170:173], v[242:245], v[122:125]
	v_mfma_f32_16x16x32_bf16 v[110:113], v[162:165], v[238:241], v[110:113]
	v_mfma_f32_16x16x32_bf16 v[106:109], v[170:173], v[238:241], v[106:109]
	v_mfma_f32_16x16x32_bf16 v[94:97], v[162:165], v[206:209], v[94:97]
	v_mfma_f32_16x16x32_bf16 v[90:93], v[170:173], v[206:209], v[90:93]
	v_mfma_f32_16x16x32_bf16 v[158:161], v[166:169], v[198:201], v[158:161]
	v_mfma_f32_16x16x32_bf16 v[154:157], v[174:177], v[198:201], v[154:157]
	v_mfma_f32_16x16x32_bf16 v[142:145], v[166:169], v[214:217], v[142:145]
	v_mfma_f32_16x16x32_bf16 v[138:141], v[174:177], v[214:217], v[138:141]
	v_mfma_f32_16x16x32_bf16 v[126:129], v[166:169], v[246:249], v[126:129]
	v_mfma_f32_16x16x32_bf16 v[122:125], v[174:177], v[246:249], v[122:125]
	v_mfma_f32_16x16x32_bf16 v[110:113], v[166:169], v[202:205], v[110:113]
	v_mfma_f32_16x16x32_bf16 v[106:109], v[174:177], v[202:205], v[106:109]
	v_mfma_f32_16x16x32_bf16 v[94:97], v[166:169], v[228:231], v[94:97]
	v_mfma_f32_16x16x32_bf16 v[90:93], v[174:177], v[228:231], v[90:93]
	v_mfma_f32_16x16x32_bf16 v[150:153], v[178:181], v[194:197], v[150:153]
	v_mfma_f32_16x16x32_bf16 v[146:149], v[186:189], v[194:197], v[146:149]
	v_mfma_f32_16x16x32_bf16 v[134:137], v[178:181], v[210:213], v[134:137]
	v_mfma_f32_16x16x32_bf16 v[130:133], v[186:189], v[210:213], v[130:133]
	v_mfma_f32_16x16x32_bf16 v[118:121], v[178:181], v[242:245], v[118:121]
	v_mfma_f32_16x16x32_bf16 v[114:117], v[186:189], v[242:245], v[114:117]
	v_mfma_f32_16x16x32_bf16 v[102:105], v[178:181], v[238:241], v[102:105]
	v_mfma_f32_16x16x32_bf16 v[98:101], v[186:189], v[238:241], v[98:101]
	v_mfma_f32_16x16x32_bf16 v[86:89], v[178:181], v[206:209], v[86:89]
	v_mfma_f32_16x16x32_bf16 v[82:85], v[186:189], v[206:209], v[82:85]
	v_mfma_f32_16x16x32_bf16 v[150:153], v[182:185], v[198:201], v[150:153]
	v_mfma_f32_16x16x32_bf16 v[146:149], v[190:193], v[198:201], v[146:149]
	v_mfma_f32_16x16x32_bf16 v[134:137], v[182:185], v[214:217], v[134:137]
	v_mfma_f32_16x16x32_bf16 v[130:133], v[190:193], v[214:217], v[130:133]
	v_mfma_f32_16x16x32_bf16 v[118:121], v[182:185], v[246:249], v[118:121]
	v_mfma_f32_16x16x32_bf16 v[114:117], v[190:193], v[246:249], v[114:117]
	v_mfma_f32_16x16x32_bf16 v[102:105], v[182:185], v[202:205], v[102:105]
	v_mfma_f32_16x16x32_bf16 v[98:101], v[190:193], v[202:205], v[98:101]
	v_mfma_f32_16x16x32_bf16 v[86:89], v[182:185], v[228:231], v[86:89]
	v_mfma_f32_16x16x32_bf16 v[82:85], v[190:193], v[228:231], v[82:85]
	s_barrier
	ds_read_b128 v[194:197], v221 offset:20480
	ds_read_b128 v[198:201], v221 offset:21504
	ds_read_b128 v[202:205], v221 offset:22528
	ds_read_b128 v[206:209], v221 offset:23552
	ds_read_b128 v[210:213], v221 offset:24576
	ds_read_b128 v[214:217], v221 offset:25600
	ds_read_b128 v[228:231], v221 offset:26624
	ds_read_b128 v[238:241], v221 offset:27648
	ds_read_b128 v[242:245], v221 offset:28672
	ds_read_b128 v[246:249], v221 offset:29696
	s_mov_b32 s74, s12
	s_mov_b32 s75, s13
	s_add_i32 m0, s28, 0x14000
	s_nop 0
	global_load_lds_dwordx4 v220, s[74:75]
	s_add_u32 s74, s12, 0x56000
	s_addc_u32 s75, s13, 0
	s_add_i32 m0, s28, 0x15000
	s_nop 0
	global_load_lds_dwordx4 v220, s[74:75]
	s_add_u32 s74, s12, 0xac000
	s_addc_u32 s75, s13, 0
	s_add_i32 m0, s28, 0x16000
	s_nop 0
	global_load_lds_dwordx4 v220, s[74:75]
	s_add_u32 s74, s12, 0x102000
	s_addc_u32 s75, s13, 0
	s_add_i32 m0, s28, 0x17000
	s_nop 0
	global_load_lds_dwordx4 v220, s[74:75]
	s_add_u32 s74, s6, 0xac000
	s_addc_u32 s75, s7, 0
	s_add_i32 m0, s28, 0x2000
	s_nop 0
	global_load_lds_dwordx4 v0, s[74:75]
	s_waitcnt vmcnt(9)
	s_waitcnt lgkmcnt(0)
	s_barrier
	v_mfma_f32_16x16x32_bf16 v[78:81], v[162:165], v[194:197], v[78:81]
	v_mfma_f32_16x16x32_bf16 v[74:77], v[170:173], v[194:197], v[74:77]
	v_mfma_f32_16x16x32_bf16 v[62:65], v[162:165], v[202:205], v[62:65]
	v_mfma_f32_16x16x32_bf16 v[58:61], v[170:173], v[202:205], v[58:61]
	v_mfma_f32_16x16x32_bf16 v[46:49], v[162:165], v[210:213], v[46:49]
	v_mfma_f32_16x16x32_bf16 v[42:45], v[170:173], v[210:213], v[42:45]
	v_mfma_f32_16x16x32_bf16 v[30:33], v[162:165], v[228:231], v[30:33]
	v_mfma_f32_16x16x32_bf16 v[26:29], v[170:173], v[228:231], v[26:29]
	v_mfma_f32_16x16x32_bf16 v[14:17], v[162:165], v[242:245], v[14:17]
	v_mfma_f32_16x16x32_bf16 v[10:13], v[170:173], v[242:245], v[10:13]
	v_mfma_f32_16x16x32_bf16 v[78:81], v[166:169], v[198:201], v[78:81]
	v_mfma_f32_16x16x32_bf16 v[74:77], v[174:177], v[198:201], v[74:77]
	v_mfma_f32_16x16x32_bf16 v[62:65], v[166:169], v[206:209], v[62:65]
	v_mfma_f32_16x16x32_bf16 v[58:61], v[174:177], v[206:209], v[58:61]
	v_mfma_f32_16x16x32_bf16 v[46:49], v[166:169], v[214:217], v[46:49]
	v_mfma_f32_16x16x32_bf16 v[42:45], v[174:177], v[214:217], v[42:45]
	v_mfma_f32_16x16x32_bf16 v[30:33], v[166:169], v[238:241], v[30:33]
	v_mfma_f32_16x16x32_bf16 v[26:29], v[174:177], v[238:241], v[26:29]
	v_mfma_f32_16x16x32_bf16 v[14:17], v[166:169], v[246:249], v[14:17]
	v_mfma_f32_16x16x32_bf16 v[10:13], v[174:177], v[246:249], v[10:13]
	v_mfma_f32_16x16x32_bf16 v[70:73], v[178:181], v[194:197], v[70:73]
	v_mfma_f32_16x16x32_bf16 v[66:69], v[186:189], v[194:197], v[66:69]
	v_mfma_f32_16x16x32_bf16 v[54:57], v[178:181], v[202:205], v[54:57]
	v_mfma_f32_16x16x32_bf16 v[50:53], v[186:189], v[202:205], v[50:53]
	v_mfma_f32_16x16x32_bf16 v[38:41], v[178:181], v[210:213], v[38:41]
	v_mfma_f32_16x16x32_bf16 v[34:37], v[186:189], v[210:213], v[34:37]
	v_mfma_f32_16x16x32_bf16 v[22:25], v[178:181], v[228:231], v[22:25]
	v_mfma_f32_16x16x32_bf16 v[18:21], v[186:189], v[228:231], v[18:21]
	v_mfma_f32_16x16x32_bf16 v[6:9], v[178:181], v[242:245], v[6:9]
	v_mfma_f32_16x16x32_bf16 v[2:5], v[186:189], v[242:245], v[2:5]
	v_mfma_f32_16x16x32_bf16 v[70:73], v[182:185], v[198:201], v[70:73]
	v_mfma_f32_16x16x32_bf16 v[66:69], v[190:193], v[198:201], v[66:69]
	v_mfma_f32_16x16x32_bf16 v[54:57], v[182:185], v[206:209], v[54:57]
	v_mfma_f32_16x16x32_bf16 v[50:53], v[190:193], v[206:209], v[50:53]
	v_mfma_f32_16x16x32_bf16 v[38:41], v[182:185], v[214:217], v[38:41]
	v_mfma_f32_16x16x32_bf16 v[34:37], v[190:193], v[214:217], v[34:37]
	v_mfma_f32_16x16x32_bf16 v[22:25], v[182:185], v[238:241], v[22:25]
	v_mfma_f32_16x16x32_bf16 v[18:21], v[190:193], v[238:241], v[18:21]
	v_mfma_f32_16x16x32_bf16 v[6:9], v[182:185], v[246:249], v[6:9]
	v_mfma_f32_16x16x32_bf16 v[2:5], v[190:193], v[246:249], v[2:5]
	s_barrier
	v_add_u32_e32 v174, 0x1c000, v223
	v_add_u32_e32 v190, 0x20000, v223
	ds_read_b128 v[162:165], v174
	ds_read_b128 v[166:169], v174 offset:1024
	ds_read_b128 v[170:173], v174 offset:2048
	ds_read_b128 v[174:177], v174 offset:3072
	ds_read_b128 v[178:181], v190
	ds_read_b128 v[182:185], v190 offset:1024
	ds_read_b128 v[186:189], v190 offset:2048
	ds_read_b128 v[190:193], v190 offset:3072
	ds_read_b128 v[194:197], v221 offset:40960
	ds_read_b128 v[198:201], v221 offset:41984
	ds_read_b128 v[202:205], v221 offset:43008
	ds_read_b128 v[206:209], v221 offset:44032
	ds_read_b128 v[210:213], v221 offset:45056
	ds_read_b128 v[214:217], v221 offset:46080
	ds_read_b128 v[228:231], v221 offset:47104
	ds_read_b128 v[238:241], v221 offset:48128
	ds_read_b128 v[242:245], v221 offset:49152
	ds_read_b128 v[246:249], v221 offset:50176
	s_add_u32 s74, s6, 0x102000
	s_addc_u32 s75, s7, 0
	s_add_i32 m0, s28, 0x3000
	s_nop 0
	global_load_lds_dwordx4 v0, s[74:75]
	s_add_u32 s74, s6, 0x158000
	s_addc_u32 s75, s7, 0
	s_add_i32 m0, s28, 0x4000
	s_nop 0
	global_load_lds_dwordx4 v0, s[74:75]
	s_add_u32 s74, s6, 0x1ae000
	s_addc_u32 s75, s7, 0
	s_add_i32 m0, s28, 0x5000
	s_nop 0
	global_load_lds_dwordx4 v0, s[74:75]
	s_add_u32 s74, s6, 0x204000
	s_addc_u32 s75, s7, 0
	s_add_i32 m0, s28, 0x6000
	s_nop 0
	global_load_lds_dwordx4 v0, s[74:75]
	s_waitcnt vmcnt(9)
	s_waitcnt lgkmcnt(0)
	s_barrier
	v_mfma_f32_16x16x32_bf16 v[158:161], v[162:165], v[194:197], v[158:161]
	v_mfma_f32_16x16x32_bf16 v[154:157], v[170:173], v[194:197], v[154:157]
	v_mfma_f32_16x16x32_bf16 v[142:145], v[162:165], v[202:205], v[142:145]
	v_mfma_f32_16x16x32_bf16 v[138:141], v[170:173], v[202:205], v[138:141]
	v_mfma_f32_16x16x32_bf16 v[126:129], v[162:165], v[210:213], v[126:129]
	v_mfma_f32_16x16x32_bf16 v[122:125], v[170:173], v[210:213], v[122:125]
	v_mfma_f32_16x16x32_bf16 v[110:113], v[162:165], v[228:231], v[110:113]
	v_mfma_f32_16x16x32_bf16 v[106:109], v[170:173], v[228:231], v[106:109]
	v_mfma_f32_16x16x32_bf16 v[94:97], v[162:165], v[242:245], v[94:97]
	v_mfma_f32_16x16x32_bf16 v[90:93], v[170:173], v[242:245], v[90:93]
	v_mfma_f32_16x16x32_bf16 v[158:161], v[166:169], v[198:201], v[158:161]
	v_mfma_f32_16x16x32_bf16 v[154:157], v[174:177], v[198:201], v[154:157]
	v_mfma_f32_16x16x32_bf16 v[142:145], v[166:169], v[206:209], v[142:145]
	v_mfma_f32_16x16x32_bf16 v[138:141], v[174:177], v[206:209], v[138:141]
	v_mfma_f32_16x16x32_bf16 v[126:129], v[166:169], v[214:217], v[126:129]
	v_mfma_f32_16x16x32_bf16 v[122:125], v[174:177], v[214:217], v[122:125]
	v_mfma_f32_16x16x32_bf16 v[110:113], v[166:169], v[238:241], v[110:113]
	v_mfma_f32_16x16x32_bf16 v[106:109], v[174:177], v[238:241], v[106:109]
	v_mfma_f32_16x16x32_bf16 v[94:97], v[166:169], v[246:249], v[94:97]
	v_mfma_f32_16x16x32_bf16 v[90:93], v[174:177], v[246:249], v[90:93]
	v_mfma_f32_16x16x32_bf16 v[150:153], v[178:181], v[194:197], v[150:153]
	v_mfma_f32_16x16x32_bf16 v[146:149], v[186:189], v[194:197], v[146:149]
	v_mfma_f32_16x16x32_bf16 v[134:137], v[178:181], v[202:205], v[134:137]
	v_mfma_f32_16x16x32_bf16 v[130:133], v[186:189], v[202:205], v[130:133]
	v_mfma_f32_16x16x32_bf16 v[118:121], v[178:181], v[210:213], v[118:121]
	v_mfma_f32_16x16x32_bf16 v[114:117], v[186:189], v[210:213], v[114:117]
	v_mfma_f32_16x16x32_bf16 v[102:105], v[178:181], v[228:231], v[102:105]
	v_mfma_f32_16x16x32_bf16 v[98:101], v[186:189], v[228:231], v[98:101]
	v_mfma_f32_16x16x32_bf16 v[86:89], v[178:181], v[242:245], v[86:89]
	v_mfma_f32_16x16x32_bf16 v[82:85], v[186:189], v[242:245], v[82:85]
	v_mfma_f32_16x16x32_bf16 v[150:153], v[182:185], v[198:201], v[150:153]
	v_mfma_f32_16x16x32_bf16 v[146:149], v[190:193], v[198:201], v[146:149]
	v_mfma_f32_16x16x32_bf16 v[134:137], v[182:185], v[206:209], v[134:137]
	v_mfma_f32_16x16x32_bf16 v[130:133], v[190:193], v[206:209], v[130:133]
	v_mfma_f32_16x16x32_bf16 v[118:121], v[182:185], v[214:217], v[118:121]
	v_mfma_f32_16x16x32_bf16 v[114:117], v[190:193], v[214:217], v[114:117]
	v_mfma_f32_16x16x32_bf16 v[102:105], v[182:185], v[238:241], v[102:105]
	v_mfma_f32_16x16x32_bf16 v[98:101], v[190:193], v[238:241], v[98:101]
	v_mfma_f32_16x16x32_bf16 v[86:89], v[182:185], v[246:249], v[86:89]
	v_mfma_f32_16x16x32_bf16 v[82:85], v[190:193], v[246:249], v[82:85]
	s_barrier
	ds_read_b128 v[194:197], v221 offset:61440
	ds_read_b128 v[198:201], v221 offset:62464
	ds_read_b128 v[202:205], v221 offset:63488
	ds_read_b128 v[206:209], v221 offset:64512
	ds_read_b128 v[210:213], v222 offset:4096
	ds_read_b128 v[214:217], v222 offset:5120
	ds_read_b128 v[228:231], v222 offset:6144
	ds_read_b128 v[238:241], v222 offset:7168
	ds_read_b128 v[242:245], v222 offset:8192
	ds_read_b128 v[246:249], v222 offset:9216
	s_add_u32 s74, s12, 0x80
	s_addc_u32 s75, s13, 0
	s_add_i32 m0, s28, 0x1c000
	s_nop 0
	global_load_lds_dwordx4 v220, s[74:75]
	s_add_u32 s74, s12, 0x56080
	s_addc_u32 s75, s13, 0
	s_add_i32 m0, s28, 0x1d000
	s_nop 0
	global_load_lds_dwordx4 v220, s[74:75]
	s_add_u32 s74, s12, 0xac080
	s_addc_u32 s75, s13, 0
	s_add_i32 m0, s28, 0x1e000
	s_nop 0
	global_load_lds_dwordx4 v220, s[74:75]
	s_add_u32 s74, s12, 0x102080
	s_addc_u32 s75, s13, 0
	s_add_i32 m0, s28, 0x1f000
	s_nop 0
	global_load_lds_dwordx4 v220, s[74:75]
	s_add_u32 s74, s6, 0xac080
	s_addc_u32 s75, s7, 0
	s_add_i32 m0, s28, 0xc000
	s_nop 0
	global_load_lds_dwordx4 v0, s[74:75]
	s_waitcnt vmcnt(9)
	s_waitcnt lgkmcnt(0)
	s_barrier
	v_mfma_f32_16x16x32_bf16 v[78:81], v[162:165], v[194:197], v[78:81]
	v_mfma_f32_16x16x32_bf16 v[74:77], v[170:173], v[194:197], v[74:77]
	v_mfma_f32_16x16x32_bf16 v[62:65], v[162:165], v[202:205], v[62:65]
	v_mfma_f32_16x16x32_bf16 v[58:61], v[170:173], v[202:205], v[58:61]
	v_mfma_f32_16x16x32_bf16 v[46:49], v[162:165], v[210:213], v[46:49]
	v_mfma_f32_16x16x32_bf16 v[42:45], v[170:173], v[210:213], v[42:45]
	v_mfma_f32_16x16x32_bf16 v[30:33], v[162:165], v[228:231], v[30:33]
	v_mfma_f32_16x16x32_bf16 v[26:29], v[170:173], v[228:231], v[26:29]
	v_mfma_f32_16x16x32_bf16 v[14:17], v[162:165], v[242:245], v[14:17]
	v_mfma_f32_16x16x32_bf16 v[10:13], v[170:173], v[242:245], v[10:13]
	v_mfma_f32_16x16x32_bf16 v[78:81], v[166:169], v[198:201], v[78:81]
	v_mfma_f32_16x16x32_bf16 v[74:77], v[174:177], v[198:201], v[74:77]
	v_mfma_f32_16x16x32_bf16 v[62:65], v[166:169], v[206:209], v[62:65]
	v_mfma_f32_16x16x32_bf16 v[58:61], v[174:177], v[206:209], v[58:61]
	v_mfma_f32_16x16x32_bf16 v[46:49], v[166:169], v[214:217], v[46:49]
	v_mfma_f32_16x16x32_bf16 v[42:45], v[174:177], v[214:217], v[42:45]
	v_mfma_f32_16x16x32_bf16 v[30:33], v[166:169], v[238:241], v[30:33]
	v_mfma_f32_16x16x32_bf16 v[26:29], v[174:177], v[238:241], v[26:29]
	v_mfma_f32_16x16x32_bf16 v[14:17], v[166:169], v[246:249], v[14:17]
	v_mfma_f32_16x16x32_bf16 v[10:13], v[174:177], v[246:249], v[10:13]
	v_mfma_f32_16x16x32_bf16 v[70:73], v[178:181], v[194:197], v[70:73]
	v_mfma_f32_16x16x32_bf16 v[66:69], v[186:189], v[194:197], v[66:69]
	v_mfma_f32_16x16x32_bf16 v[54:57], v[178:181], v[202:205], v[54:57]
	v_mfma_f32_16x16x32_bf16 v[50:53], v[186:189], v[202:205], v[50:53]
	v_mfma_f32_16x16x32_bf16 v[38:41], v[178:181], v[210:213], v[38:41]
	v_mfma_f32_16x16x32_bf16 v[34:37], v[186:189], v[210:213], v[34:37]
	v_mfma_f32_16x16x32_bf16 v[22:25], v[178:181], v[228:231], v[22:25]
	v_mfma_f32_16x16x32_bf16 v[18:21], v[186:189], v[228:231], v[18:21]
	v_mfma_f32_16x16x32_bf16 v[6:9], v[178:181], v[242:245], v[6:9]
	v_mfma_f32_16x16x32_bf16 v[2:5], v[186:189], v[242:245], v[2:5]
	v_mfma_f32_16x16x32_bf16 v[70:73], v[182:185], v[198:201], v[70:73]
	v_mfma_f32_16x16x32_bf16 v[66:69], v[190:193], v[198:201], v[66:69]
	v_mfma_f32_16x16x32_bf16 v[54:57], v[182:185], v[206:209], v[54:57]
	v_mfma_f32_16x16x32_bf16 v[50:53], v[190:193], v[206:209], v[50:53]
	v_mfma_f32_16x16x32_bf16 v[38:41], v[182:185], v[214:217], v[38:41]
	v_mfma_f32_16x16x32_bf16 v[34:37], v[190:193], v[214:217], v[34:37]
	v_mfma_f32_16x16x32_bf16 v[22:25], v[182:185], v[238:241], v[22:25]
	v_mfma_f32_16x16x32_bf16 v[18:21], v[190:193], v[238:241], v[18:21]
	v_mfma_f32_16x16x32_bf16 v[6:9], v[182:185], v[246:249], v[6:9]
	v_mfma_f32_16x16x32_bf16 v[2:5], v[190:193], v[246:249], v[2:5]
	s_barrier
	s_add_i32 vcc_hi, vcc_hi, 2
	s_add_u32 s4, s4, 0x100
	s_addc_u32 s5, s5, 0
	s_add_u32 s97, s97, 0x100
	s_addc_u32 vcc_lo, vcc_lo, 0
	s_cmpk_gt_u32 vcc_hi, 0x53
	s_cbranch_scc0 .LBB0_716
	s_and_b64 vcc, exec, s[20:21]
	s_cbranch_vccz .LBB0_719
	s_barrier

.LBB0_897:
	v_add_u32_e32 v174, 0x14000, v223
	v_add_u32_e32 v190, 0x18000, v223
	ds_read_b128 v[162:165], v174
	ds_read_b128 v[166:169], v174 offset:1024
	ds_read_b128 v[170:173], v174 offset:2048
	ds_read_b128 v[174:177], v174 offset:3072
	ds_read_b128 v[178:181], v190
	ds_read_b128 v[182:185], v190 offset:1024
	ds_read_b128 v[186:189], v190 offset:2048
	ds_read_b128 v[190:193], v190 offset:3072
	s_add_u32 s6, s4, 0xfff60080
	s_addc_u32 s7, s5, -1
	s_cmp_eq_u32 s92, 4
	s_cselect_b32 s6, s24, s6
	s_cselect_b32 s7, s25, s7
	s_cselect_b32 s16, s23, s72
	s_cselect_b32 s17, s21, s84
	ds_read_b128 v[194:197], v221
	ds_read_b128 v[198:201], v221 offset:1024
	ds_read_b128 v[202:205], v221 offset:2048
	ds_read_b128 v[206:209], v221 offset:3072
	ds_read_b128 v[210:213], v221 offset:4096
	ds_read_b128 v[214:217], v221 offset:5120
	ds_read_b128 v[228:231], v221 offset:6144
	ds_read_b128 v[238:241], v221 offset:7168
	ds_read_b128 v[242:245], v221 offset:8192
	ds_read_b128 v[246:249], v221 offset:9216
	s_add_u32 s74, s6, 0xfffe0000
	s_addc_u32 s75, s7, -1
	s_add_i32 m0, s34, 0xfffff000
	s_nop 0
	global_load_lds_dwordx4 v0, s[74:75]
	s_mov_b32 s74, s6
	s_mov_b32 s75, s7
	s_mov_b32 m0, s34
	s_nop 0
	global_load_lds_dwordx4 v0, s[74:75]
	s_add_u32 s74, s4, 0x40000
	s_addc_u32 s75, s5, 0
	s_add_i32 m0, s34, 0x11000
	s_nop 0
	global_load_lds_dwordx4 v0, s[74:75]
	s_add_u32 s74, s4, 0x60000
	s_addc_u32 s75, s5, 0
	s_add_i32 m0, s34, 0x12000
	s_nop 0
	global_load_lds_dwordx4 v0, s[74:75]
	s_add_u32 s74, s4, 0x20000
	s_addc_u32 s75, s5, 0
	s_add_i32 m0, s34, 0x10000
	s_nop 0
	global_load_lds_dwordx4 v0, s[74:75]
	s_waitcnt vmcnt(9)
	s_waitcnt lgkmcnt(0)
	s_barrier
	v_mfma_f32_16x16x32_bf16 v[158:161], v[162:165], v[194:197], v[158:161]
	v_mfma_f32_16x16x32_bf16 v[154:157], v[170:173], v[194:197], v[154:157]
	v_mfma_f32_16x16x32_bf16 v[142:145], v[162:165], v[202:205], v[142:145]
	v_mfma_f32_16x16x32_bf16 v[138:141], v[170:173], v[202:205], v[138:141]
	v_mfma_f32_16x16x32_bf16 v[126:129], v[162:165], v[210:213], v[126:129]
	v_mfma_f32_16x16x32_bf16 v[122:125], v[170:173], v[210:213], v[122:125]
	v_mfma_f32_16x16x32_bf16 v[110:113], v[162:165], v[228:231], v[110:113]
	v_mfma_f32_16x16x32_bf16 v[106:109], v[170:173], v[228:231], v[106:109]
	v_mfma_f32_16x16x32_bf16 v[94:97], v[162:165], v[242:245], v[94:97]
	v_mfma_f32_16x16x32_bf16 v[90:93], v[170:173], v[242:245], v[90:93]
	v_mfma_f32_16x16x32_bf16 v[158:161], v[166:169], v[198:201], v[158:161]
	v_mfma_f32_16x16x32_bf16 v[154:157], v[174:177], v[198:201], v[154:157]
	v_mfma_f32_16x16x32_bf16 v[142:145], v[166:169], v[206:209], v[142:145]
	v_mfma_f32_16x16x32_bf16 v[138:141], v[174:177], v[206:209], v[138:141]
	v_mfma_f32_16x16x32_bf16 v[126:129], v[166:169], v[214:217], v[126:129]
	v_mfma_f32_16x16x32_bf16 v[122:125], v[174:177], v[214:217], v[122:125]
	v_mfma_f32_16x16x32_bf16 v[110:113], v[166:169], v[238:241], v[110:113]
	v_mfma_f32_16x16x32_bf16 v[106:109], v[174:177], v[238:241], v[106:109]
	v_mfma_f32_16x16x32_bf16 v[94:97], v[166:169], v[246:249], v[94:97]
	v_mfma_f32_16x16x32_bf16 v[90:93], v[174:177], v[246:249], v[90:93]
	v_mfma_f32_16x16x32_bf16 v[150:153], v[178:181], v[194:197], v[150:153]
	v_mfma_f32_16x16x32_bf16 v[146:149], v[186:189], v[194:197], v[146:149]
	v_mfma_f32_16x16x32_bf16 v[134:137], v[178:181], v[202:205], v[134:137]
	v_mfma_f32_16x16x32_bf16 v[130:133], v[186:189], v[202:205], v[130:133]
	v_mfma_f32_16x16x32_bf16 v[118:121], v[178:181], v[210:213], v[118:121]
	v_mfma_f32_16x16x32_bf16 v[114:117], v[186:189], v[210:213], v[114:117]
	v_mfma_f32_16x16x32_bf16 v[102:105], v[178:181], v[228:231], v[102:105]
	v_mfma_f32_16x16x32_bf16 v[98:101], v[186:189], v[228:231], v[98:101]
	v_mfma_f32_16x16x32_bf16 v[86:89], v[178:181], v[242:245], v[86:89]
	v_mfma_f32_16x16x32_bf16 v[82:85], v[186:189], v[242:245], v[82:85]
	v_mfma_f32_16x16x32_bf16 v[150:153], v[182:185], v[198:201], v[150:153]
	v_mfma_f32_16x16x32_bf16 v[146:149], v[190:193], v[198:201], v[146:149]
	v_mfma_f32_16x16x32_bf16 v[134:137], v[182:185], v[206:209], v[134:137]
	v_mfma_f32_16x16x32_bf16 v[130:133], v[190:193], v[206:209], v[130:133]
	v_mfma_f32_16x16x32_bf16 v[118:121], v[182:185], v[214:217], v[118:121]
	v_mfma_f32_16x16x32_bf16 v[114:117], v[190:193], v[214:217], v[114:117]
	v_mfma_f32_16x16x32_bf16 v[102:105], v[182:185], v[238:241], v[102:105]
	v_mfma_f32_16x16x32_bf16 v[98:101], v[190:193], v[238:241], v[98:101]
	v_mfma_f32_16x16x32_bf16 v[86:89], v[182:185], v[246:249], v[86:89]
	v_mfma_f32_16x16x32_bf16 v[82:85], v[190:193], v[246:249], v[82:85]
	s_barrier
	ds_read_b128 v[194:197], v221 offset:20480
	ds_read_b128 v[198:201], v221 offset:21504
	ds_read_b128 v[202:205], v221 offset:22528
	ds_read_b128 v[206:209], v221 offset:23552
	ds_read_b128 v[210:213], v221 offset:24576
	ds_read_b128 v[214:217], v221 offset:25600
	ds_read_b128 v[228:231], v221 offset:26624
	ds_read_b128 v[238:241], v221 offset:27648
	ds_read_b128 v[242:245], v221 offset:28672
	ds_read_b128 v[246:249], v221 offset:29696
	s_add_u32 s74, s16, 0x18000
	s_addc_u32 s75, s17, 0
	s_add_i32 m0, s34, 0x17000
	s_nop 0
	global_load_lds_dwordx4 v220, s[74:75]
	s_add_u32 s74, s16, 0x20000
	s_addc_u32 s75, s17, 0
	s_add_i32 m0, s34, 0x18000
	s_nop 0
	global_load_lds_dwordx4 v220, s[74:75]
	s_add_u32 s74, s16, 0x28000
	s_addc_u32 s75, s17, 0
	s_add_i32 m0, s34, 0x19000
	s_nop 0
	global_load_lds_dwordx4 v220, s[74:75]
	s_add_u32 s74, s16, 0x30000
	s_addc_u32 s75, s17, 0
	s_add_i32 m0, s34, 0x1a000
	s_nop 0
	global_load_lds_dwordx4 v220, s[74:75]
	s_waitcnt vmcnt(9)
	s_waitcnt lgkmcnt(0)
	s_barrier
	v_mfma_f32_16x16x32_bf16 v[78:81], v[162:165], v[194:197], v[78:81]
	v_mfma_f32_16x16x32_bf16 v[74:77], v[170:173], v[194:197], v[74:77]
	v_mfma_f32_16x16x32_bf16 v[62:65], v[162:165], v[202:205], v[62:65]
	v_mfma_f32_16x16x32_bf16 v[58:61], v[170:173], v[202:205], v[58:61]
	v_mfma_f32_16x16x32_bf16 v[46:49], v[162:165], v[210:213], v[46:49]
	v_mfma_f32_16x16x32_bf16 v[42:45], v[170:173], v[210:213], v[42:45]
	v_mfma_f32_16x16x32_bf16 v[30:33], v[162:165], v[228:231], v[30:33]
	v_mfma_f32_16x16x32_bf16 v[26:29], v[170:173], v[228:231], v[26:29]
	v_mfma_f32_16x16x32_bf16 v[14:17], v[162:165], v[242:245], v[14:17]
	v_mfma_f32_16x16x32_bf16 v[10:13], v[170:173], v[242:245], v[10:13]
	v_mfma_f32_16x16x32_bf16 v[78:81], v[166:169], v[198:201], v[78:81]
	v_mfma_f32_16x16x32_bf16 v[74:77], v[174:177], v[198:201], v[74:77]
	v_mfma_f32_16x16x32_bf16 v[62:65], v[166:169], v[206:209], v[62:65]
	v_mfma_f32_16x16x32_bf16 v[58:61], v[174:177], v[206:209], v[58:61]
	v_mfma_f32_16x16x32_bf16 v[46:49], v[166:169], v[214:217], v[46:49]
	v_mfma_f32_16x16x32_bf16 v[42:45], v[174:177], v[214:217], v[42:45]
	v_mfma_f32_16x16x32_bf16 v[30:33], v[166:169], v[238:241], v[30:33]
	v_mfma_f32_16x16x32_bf16 v[26:29], v[174:177], v[238:241], v[26:29]
	v_mfma_f32_16x16x32_bf16 v[14:17], v[166:169], v[246:249], v[14:17]
	v_mfma_f32_16x16x32_bf16 v[10:13], v[174:177], v[246:249], v[10:13]
	v_mfma_f32_16x16x32_bf16 v[70:73], v[178:181], v[194:197], v[70:73]
	v_mfma_f32_16x16x32_bf16 v[66:69], v[186:189], v[194:197], v[66:69]
	v_mfma_f32_16x16x32_bf16 v[54:57], v[178:181], v[202:205], v[54:57]
	v_mfma_f32_16x16x32_bf16 v[50:53], v[186:189], v[202:205], v[50:53]
	v_mfma_f32_16x16x32_bf16 v[38:41], v[178:181], v[210:213], v[38:41]
	v_mfma_f32_16x16x32_bf16 v[34:37], v[186:189], v[210:213], v[34:37]
	v_mfma_f32_16x16x32_bf16 v[22:25], v[178:181], v[228:231], v[22:25]
	v_mfma_f32_16x16x32_bf16 v[18:21], v[186:189], v[228:231], v[18:21]
	v_mfma_f32_16x16x32_bf16 v[6:9], v[178:181], v[242:245], v[6:9]
	v_mfma_f32_16x16x32_bf16 v[2:5], v[186:189], v[242:245], v[2:5]
	v_mfma_f32_16x16x32_bf16 v[70:73], v[182:185], v[198:201], v[70:73]
	v_mfma_f32_16x16x32_bf16 v[66:69], v[190:193], v[198:201], v[66:69]
	v_mfma_f32_16x16x32_bf16 v[54:57], v[182:185], v[206:209], v[54:57]
	v_mfma_f32_16x16x32_bf16 v[50:53], v[190:193], v[206:209], v[50:53]
	v_mfma_f32_16x16x32_bf16 v[38:41], v[182:185], v[214:217], v[38:41]
	v_mfma_f32_16x16x32_bf16 v[34:37], v[190:193], v[214:217], v[34:37]
	v_mfma_f32_16x16x32_bf16 v[22:25], v[182:185], v[238:241], v[22:25]
	v_mfma_f32_16x16x32_bf16 v[18:21], v[190:193], v[238:241], v[18:21]
	v_mfma_f32_16x16x32_bf16 v[6:9], v[182:185], v[246:249], v[6:9]
	v_mfma_f32_16x16x32_bf16 v[2:5], v[190:193], v[246:249], v[2:5]
	s_barrier
	v_add_u32_e32 v174, 0x1c000, v223
	v_add_u32_e32 v190, 0x20000, v223
	ds_read_b128 v[162:165], v174
	ds_read_b128 v[166:169], v174 offset:1024
	ds_read_b128 v[170:173], v174 offset:2048
	ds_read_b128 v[174:177], v174 offset:3072
	ds_read_b128 v[178:181], v190
	ds_read_b128 v[182:185], v190 offset:1024
	ds_read_b128 v[186:189], v190 offset:2048
	ds_read_b128 v[190:193], v190 offset:3072
	ds_read_b128 v[194:197], v221 offset:40960
	ds_read_b128 v[198:201], v221 offset:41984
	ds_read_b128 v[202:205], v221 offset:43008
	ds_read_b128 v[206:209], v221 offset:44032
	ds_read_b128 v[210:213], v221 offset:45056
	ds_read_b128 v[214:217], v221 offset:46080
	ds_read_b128 v[228:231], v221 offset:47104
	ds_read_b128 v[238:241], v221 offset:48128
	ds_read_b128 v[242:245], v221 offset:49152
	ds_read_b128 v[246:249], v221 offset:50176
	s_add_u32 s74, s6, 0xfffe0080
	s_addc_u32 s75, s7, -1
	s_add_i32 m0, s34, 0x9000
	s_nop 0
	global_load_lds_dwordx4 v0, s[74:75]
	s_add_u32 s74, s6, 0x80
	s_addc_u32 s75, s7, 0
	s_add_i32 m0, s34, 0xa000
	s_nop 0
	global_load_lds_dwordx4 v0, s[74:75]
	s_add_u32 s74, s6, 0xe0000
	s_addc_u32 s75, s7, 0
	s_add_i32 m0, s34, 0x7000
	s_nop 0
	global_load_lds_dwordx4 v0, s[74:75]
	s_add_u32 s74, s6, 0x100000
	s_addc_u32 s75, s7, 0
	s_add_i32 m0, s34, 0x8000
	s_nop 0
	global_load_lds_dwordx4 v0, s[74:75]
	s_add_u32 s74, s6, 0xc0000
	s_addc_u32 s75, s7, 0
	s_add_i32 m0, s34, 0x6000
	s_nop 0
	global_load_lds_dwordx4 v0, s[74:75]
	s_waitcnt vmcnt(9)
	s_waitcnt lgkmcnt(0)
	s_barrier
	v_mfma_f32_16x16x32_bf16 v[158:161], v[162:165], v[194:197], v[158:161]
	v_mfma_f32_16x16x32_bf16 v[154:157], v[170:173], v[194:197], v[154:157]
	v_mfma_f32_16x16x32_bf16 v[142:145], v[162:165], v[202:205], v[142:145]
	v_mfma_f32_16x16x32_bf16 v[138:141], v[170:173], v[202:205], v[138:141]
	v_mfma_f32_16x16x32_bf16 v[126:129], v[162:165], v[210:213], v[126:129]
	v_mfma_f32_16x16x32_bf16 v[122:125], v[170:173], v[210:213], v[122:125]
	v_mfma_f32_16x16x32_bf16 v[110:113], v[162:165], v[228:231], v[110:113]
	v_mfma_f32_16x16x32_bf16 v[106:109], v[170:173], v[228:231], v[106:109]
	v_mfma_f32_16x16x32_bf16 v[94:97], v[162:165], v[242:245], v[94:97]
	v_mfma_f32_16x16x32_bf16 v[90:93], v[170:173], v[242:245], v[90:93]
	v_mfma_f32_16x16x32_bf16 v[158:161], v[166:169], v[198:201], v[158:161]
	v_mfma_f32_16x16x32_bf16 v[154:157], v[174:177], v[198:201], v[154:157]
	v_mfma_f32_16x16x32_bf16 v[142:145], v[166:169], v[206:209], v[142:145]
	v_mfma_f32_16x16x32_bf16 v[138:141], v[174:177], v[206:209], v[138:141]
	v_mfma_f32_16x16x32_bf16 v[126:129], v[166:169], v[214:217], v[126:129]
	v_mfma_f32_16x16x32_bf16 v[122:125], v[174:177], v[214:217], v[122:125]
	v_mfma_f32_16x16x32_bf16 v[110:113], v[166:169], v[238:241], v[110:113]
	v_mfma_f32_16x16x32_bf16 v[106:109], v[174:177], v[238:241], v[106:109]
	v_mfma_f32_16x16x32_bf16 v[94:97], v[166:169], v[246:249], v[94:97]
	v_mfma_f32_16x16x32_bf16 v[90:93], v[174:177], v[246:249], v[90:93]
	v_mfma_f32_16x16x32_bf16 v[150:153], v[178:181], v[194:197], v[150:153]
	v_mfma_f32_16x16x32_bf16 v[146:149], v[186:189], v[194:197], v[146:149]
	v_mfma_f32_16x16x32_bf16 v[134:137], v[178:181], v[202:205], v[134:137]
	v_mfma_f32_16x16x32_bf16 v[130:133], v[186:189], v[202:205], v[130:133]
	v_mfma_f32_16x16x32_bf16 v[118:121], v[178:181], v[210:213], v[118:121]
	v_mfma_f32_16x16x32_bf16 v[114:117], v[186:189], v[210:213], v[114:117]
	v_mfma_f32_16x16x32_bf16 v[102:105], v[178:181], v[228:231], v[102:105]
	v_mfma_f32_16x16x32_bf16 v[98:101], v[186:189], v[228:231], v[98:101]
	v_mfma_f32_16x16x32_bf16 v[86:89], v[178:181], v[242:245], v[86:89]
	v_mfma_f32_16x16x32_bf16 v[82:85], v[186:189], v[242:245], v[82:85]
	v_mfma_f32_16x16x32_bf16 v[150:153], v[182:185], v[198:201], v[150:153]
	v_mfma_f32_16x16x32_bf16 v[146:149], v[190:193], v[198:201], v[146:149]
	v_mfma_f32_16x16x32_bf16 v[134:137], v[182:185], v[206:209], v[134:137]
	v_mfma_f32_16x16x32_bf16 v[130:133], v[190:193], v[206:209], v[130:133]
	v_mfma_f32_16x16x32_bf16 v[118:121], v[182:185], v[214:217], v[118:121]
	v_mfma_f32_16x16x32_bf16 v[114:117], v[190:193], v[214:217], v[114:117]
	v_mfma_f32_16x16x32_bf16 v[102:105], v[182:185], v[238:241], v[102:105]
	v_mfma_f32_16x16x32_bf16 v[98:101], v[190:193], v[238:241], v[98:101]
	v_mfma_f32_16x16x32_bf16 v[86:89], v[182:185], v[246:249], v[86:89]
	v_mfma_f32_16x16x32_bf16 v[82:85], v[190:193], v[246:249], v[82:85]
	s_barrier
	ds_read_b128 v[194:197], v221 offset:61440
	ds_read_b128 v[198:201], v221 offset:62464
	ds_read_b128 v[202:205], v221 offset:63488
	ds_read_b128 v[206:209], v221 offset:64512
	ds_read_b128 v[210:213], v222 offset:4096
	ds_read_b128 v[214:217], v222 offset:5120
	ds_read_b128 v[228:231], v222 offset:6144
	ds_read_b128 v[238:241], v222 offset:7168
	ds_read_b128 v[242:245], v222 offset:8192
	ds_read_b128 v[246:249], v222 offset:9216
	s_add_u32 s74, s16, 0x18080
	s_addc_u32 s75, s17, 0
	s_add_i32 m0, s34, 0x1f000
	s_nop 0
	global_load_lds_dwordx4 v220, s[74:75]
	s_add_u32 s74, s16, 0x20080
	s_addc_u32 s75, s17, 0
	s_add_i32 m0, s34, 0x20000
	s_nop 0
	global_load_lds_dwordx4 v220, s[74:75]
	s_add_u32 s74, s16, 0x28080
	s_addc_u32 s75, s17, 0
	s_add_i32 m0, s34, 0x21000
	s_nop 0
	global_load_lds_dwordx4 v220, s[74:75]
	s_add_u32 s74, s16, 0x30080
	s_addc_u32 s75, s17, 0
	s_add_i32 m0, s34, 0x22000
	s_nop 0
	global_load_lds_dwordx4 v220, s[74:75]
	s_waitcnt vmcnt(9)
	s_waitcnt lgkmcnt(0)
	s_barrier
	v_mfma_f32_16x16x32_bf16 v[78:81], v[162:165], v[194:197], v[78:81]
	v_mfma_f32_16x16x32_bf16 v[74:77], v[170:173], v[194:197], v[74:77]
	v_mfma_f32_16x16x32_bf16 v[62:65], v[162:165], v[202:205], v[62:65]
	v_mfma_f32_16x16x32_bf16 v[58:61], v[170:173], v[202:205], v[58:61]
	v_mfma_f32_16x16x32_bf16 v[46:49], v[162:165], v[210:213], v[46:49]
	v_mfma_f32_16x16x32_bf16 v[42:45], v[170:173], v[210:213], v[42:45]
	v_mfma_f32_16x16x32_bf16 v[30:33], v[162:165], v[228:231], v[30:33]
	v_mfma_f32_16x16x32_bf16 v[26:29], v[170:173], v[228:231], v[26:29]
	v_mfma_f32_16x16x32_bf16 v[14:17], v[162:165], v[242:245], v[14:17]
	v_mfma_f32_16x16x32_bf16 v[10:13], v[170:173], v[242:245], v[10:13]
	v_mfma_f32_16x16x32_bf16 v[78:81], v[166:169], v[198:201], v[78:81]
	v_mfma_f32_16x16x32_bf16 v[74:77], v[174:177], v[198:201], v[74:77]
	v_mfma_f32_16x16x32_bf16 v[62:65], v[166:169], v[206:209], v[62:65]
	v_mfma_f32_16x16x32_bf16 v[58:61], v[174:177], v[206:209], v[58:61]
	v_mfma_f32_16x16x32_bf16 v[46:49], v[166:169], v[214:217], v[46:49]
	v_mfma_f32_16x16x32_bf16 v[42:45], v[174:177], v[214:217], v[42:45]
	v_mfma_f32_16x16x32_bf16 v[30:33], v[166:169], v[238:241], v[30:33]
	v_mfma_f32_16x16x32_bf16 v[26:29], v[174:177], v[238:241], v[26:29]
	v_mfma_f32_16x16x32_bf16 v[14:17], v[166:169], v[246:249], v[14:17]
	v_mfma_f32_16x16x32_bf16 v[10:13], v[174:177], v[246:249], v[10:13]
	v_mfma_f32_16x16x32_bf16 v[70:73], v[178:181], v[194:197], v[70:73]
	v_mfma_f32_16x16x32_bf16 v[66:69], v[186:189], v[194:197], v[66:69]
	v_mfma_f32_16x16x32_bf16 v[54:57], v[178:181], v[202:205], v[54:57]
	v_mfma_f32_16x16x32_bf16 v[50:53], v[186:189], v[202:205], v[50:53]
	v_mfma_f32_16x16x32_bf16 v[38:41], v[178:181], v[210:213], v[38:41]
	v_mfma_f32_16x16x32_bf16 v[34:37], v[186:189], v[210:213], v[34:37]
	v_mfma_f32_16x16x32_bf16 v[22:25], v[178:181], v[228:231], v[22:25]
	v_mfma_f32_16x16x32_bf16 v[18:21], v[186:189], v[228:231], v[18:21]
	v_mfma_f32_16x16x32_bf16 v[6:9], v[178:181], v[242:245], v[6:9]
	v_mfma_f32_16x16x32_bf16 v[2:5], v[186:189], v[242:245], v[2:5]
	v_mfma_f32_16x16x32_bf16 v[70:73], v[182:185], v[198:201], v[70:73]
	v_mfma_f32_16x16x32_bf16 v[66:69], v[190:193], v[198:201], v[66:69]
	v_mfma_f32_16x16x32_bf16 v[54:57], v[182:185], v[206:209], v[54:57]
	v_mfma_f32_16x16x32_bf16 v[50:53], v[190:193], v[206:209], v[50:53]
	v_mfma_f32_16x16x32_bf16 v[38:41], v[182:185], v[214:217], v[38:41]
	v_mfma_f32_16x16x32_bf16 v[34:37], v[190:193], v[214:217], v[34:37]
	v_mfma_f32_16x16x32_bf16 v[22:25], v[182:185], v[238:241], v[22:25]
	v_mfma_f32_16x16x32_bf16 v[18:21], v[190:193], v[238:241], v[18:21]
	v_mfma_f32_16x16x32_bf16 v[6:9], v[182:185], v[246:249], v[6:9]
	v_mfma_f32_16x16x32_bf16 v[2:5], v[190:193], v[246:249], v[2:5]
	s_barrier
	s_add_i32 s92, s92, 2
	s_add_u32 s4, s4, 0x100
	s_addc_u32 s5, s5, 0
	s_add_u32 s72, s72, 0x100
	s_addc_u32 s84, s84, 0
	s_cmp_gt_u32 s92, 5
	s_cbranch_scc0 .LBB0_897
	s_and_b64 vcc, exec, s[18:19]
	s_cbranch_vccz .LBB0_900
	s_barrier

.LBB0_929:
	v_add_u32_e32 v174, 0x14000, v223
	v_add_u32_e32 v190, 0x18000, v223
	ds_read_b128 v[162:165], v174
	ds_read_b128 v[166:169], v174 offset:1024
	ds_read_b128 v[170:173], v174 offset:2048
	ds_read_b128 v[174:177], v174 offset:3072
	ds_read_b128 v[178:181], v190
	ds_read_b128 v[182:185], v190 offset:1024
	ds_read_b128 v[186:189], v190 offset:2048
	ds_read_b128 v[190:193], v190 offset:3072
	s_add_u32 s6, s4, 0xfff60080
	s_addc_u32 s7, s5, -1
	s_cmp_eq_u32 s14, 4
	s_cselect_b32 s6, s24, s6
	s_cselect_b32 s7, s25, s7
	s_cselect_b32 s16, s23, vcc_lo
	s_cselect_b32 s17, s21, vcc_hi
	ds_read_b128 v[194:197], v221
	ds_read_b128 v[198:201], v221 offset:1024
	ds_read_b128 v[202:205], v221 offset:2048
	ds_read_b128 v[206:209], v221 offset:3072
	ds_read_b128 v[210:213], v221 offset:4096
	ds_read_b128 v[214:217], v221 offset:5120
	ds_read_b128 v[228:231], v221 offset:6144
	ds_read_b128 v[238:241], v221 offset:7168
	ds_read_b128 v[242:245], v221 offset:8192
	ds_read_b128 v[246:249], v221 offset:9216
	s_add_u32 s74, s4, 0xfffc0000
	s_addc_u32 s75, s5, -1
	s_add_i32 m0, s34, 0xd000
	s_nop 0
	global_load_lds_dwordx4 v0, s[74:75]
	s_add_u32 s74, s4, 0xfffe0000
	s_addc_u32 s75, s5, -1
	s_add_i32 m0, s34, 0xe000
	s_nop 0
	global_load_lds_dwordx4 v0, s[74:75]
	s_mov_b32 s74, s4
	s_mov_b32 s75, s5
	s_add_i32 m0, s34, 0xf000
	s_nop 0
	global_load_lds_dwordx4 v0, s[74:75]
	s_add_u32 s74, s4, 0x20000
	s_addc_u32 s75, s5, 0
	s_add_i32 m0, s34, 0x10000
	s_nop 0
	global_load_lds_dwordx4 v0, s[74:75]
	s_waitcnt vmcnt(9)
	s_waitcnt lgkmcnt(0)
	s_barrier
	v_mfma_f32_16x16x32_bf16 v[158:161], v[162:165], v[194:197], v[158:161]
	v_mfma_f32_16x16x32_bf16 v[154:157], v[170:173], v[194:197], v[154:157]
	v_mfma_f32_16x16x32_bf16 v[142:145], v[162:165], v[202:205], v[142:145]
	v_mfma_f32_16x16x32_bf16 v[138:141], v[170:173], v[202:205], v[138:141]
	v_mfma_f32_16x16x32_bf16 v[126:129], v[162:165], v[210:213], v[126:129]
	v_mfma_f32_16x16x32_bf16 v[122:125], v[170:173], v[210:213], v[122:125]
	v_mfma_f32_16x16x32_bf16 v[110:113], v[162:165], v[228:231], v[110:113]
	v_mfma_f32_16x16x32_bf16 v[106:109], v[170:173], v[228:231], v[106:109]
	v_mfma_f32_16x16x32_bf16 v[94:97], v[162:165], v[242:245], v[94:97]
	v_mfma_f32_16x16x32_bf16 v[90:93], v[170:173], v[242:245], v[90:93]
	v_mfma_f32_16x16x32_bf16 v[158:161], v[166:169], v[198:201], v[158:161]
	v_mfma_f32_16x16x32_bf16 v[154:157], v[174:177], v[198:201], v[154:157]
	v_mfma_f32_16x16x32_bf16 v[142:145], v[166:169], v[206:209], v[142:145]
	v_mfma_f32_16x16x32_bf16 v[138:141], v[174:177], v[206:209], v[138:141]
	v_mfma_f32_16x16x32_bf16 v[126:129], v[166:169], v[214:217], v[126:129]
	v_mfma_f32_16x16x32_bf16 v[122:125], v[174:177], v[214:217], v[122:125]
	v_mfma_f32_16x16x32_bf16 v[110:113], v[166:169], v[238:241], v[110:113]
	v_mfma_f32_16x16x32_bf16 v[106:109], v[174:177], v[238:241], v[106:109]
	v_mfma_f32_16x16x32_bf16 v[94:97], v[166:169], v[246:249], v[94:97]
	v_mfma_f32_16x16x32_bf16 v[90:93], v[174:177], v[246:249], v[90:93]
	v_mfma_f32_16x16x32_bf16 v[150:153], v[178:181], v[194:197], v[150:153]
	v_mfma_f32_16x16x32_bf16 v[146:149], v[186:189], v[194:197], v[146:149]
	v_mfma_f32_16x16x32_bf16 v[134:137], v[178:181], v[202:205], v[134:137]
	v_mfma_f32_16x16x32_bf16 v[130:133], v[186:189], v[202:205], v[130:133]
	v_mfma_f32_16x16x32_bf16 v[118:121], v[178:181], v[210:213], v[118:121]
	v_mfma_f32_16x16x32_bf16 v[114:117], v[186:189], v[210:213], v[114:117]
	v_mfma_f32_16x16x32_bf16 v[102:105], v[178:181], v[228:231], v[102:105]
	v_mfma_f32_16x16x32_bf16 v[98:101], v[186:189], v[228:231], v[98:101]
	v_mfma_f32_16x16x32_bf16 v[86:89], v[178:181], v[242:245], v[86:89]
	v_mfma_f32_16x16x32_bf16 v[82:85], v[186:189], v[242:245], v[82:85]
	v_mfma_f32_16x16x32_bf16 v[150:153], v[182:185], v[198:201], v[150:153]
	v_mfma_f32_16x16x32_bf16 v[146:149], v[190:193], v[198:201], v[146:149]
	v_mfma_f32_16x16x32_bf16 v[134:137], v[182:185], v[206:209], v[134:137]
	v_mfma_f32_16x16x32_bf16 v[130:133], v[190:193], v[206:209], v[130:133]
	v_mfma_f32_16x16x32_bf16 v[118:121], v[182:185], v[214:217], v[118:121]
	v_mfma_f32_16x16x32_bf16 v[114:117], v[190:193], v[214:217], v[114:117]
	v_mfma_f32_16x16x32_bf16 v[102:105], v[182:185], v[238:241], v[102:105]
	v_mfma_f32_16x16x32_bf16 v[98:101], v[190:193], v[238:241], v[98:101]
	v_mfma_f32_16x16x32_bf16 v[86:89], v[182:185], v[246:249], v[86:89]
	v_mfma_f32_16x16x32_bf16 v[82:85], v[190:193], v[246:249], v[82:85]
	s_barrier
	ds_read_b128 v[194:197], v221 offset:20480
	ds_read_b128 v[198:201], v221 offset:21504
	ds_read_b128 v[202:205], v221 offset:22528
	ds_read_b128 v[206:209], v221 offset:23552
	ds_read_b128 v[210:213], v221 offset:24576
	ds_read_b128 v[214:217], v221 offset:25600
	ds_read_b128 v[228:231], v221 offset:26624
	ds_read_b128 v[238:241], v221 offset:27648
	ds_read_b128 v[242:245], v221 offset:28672
	ds_read_b128 v[246:249], v221 offset:29696
	s_mov_b32 s74, s16
	s_mov_b32 s75, s17
	s_add_i32 m0, s34, 0x14000
	s_nop 0
	global_load_lds_dwordx4 v220, s[74:75]
	s_add_u32 s74, s16, 0x8000
	s_addc_u32 s75, s17, 0
	s_add_i32 m0, s34, 0x15000
	s_nop 0
	global_load_lds_dwordx4 v220, s[74:75]
	s_add_u32 s74, s16, 0x10000
	s_addc_u32 s75, s17, 0
	s_add_i32 m0, s34, 0x16000
	s_nop 0
	global_load_lds_dwordx4 v220, s[74:75]
	s_add_u32 s74, s16, 0x18000
	s_addc_u32 s75, s17, 0
	s_add_i32 m0, s34, 0x17000
	s_nop 0
	global_load_lds_dwordx4 v220, s[74:75]
	s_add_u32 s74, s6, 0x40000
	s_addc_u32 s75, s7, 0
	s_add_i32 m0, s34, 0x2000
	s_nop 0
	global_load_lds_dwordx4 v0, s[74:75]
	s_waitcnt vmcnt(9)
	s_waitcnt lgkmcnt(0)
	s_barrier
	v_mfma_f32_16x16x32_bf16 v[78:81], v[162:165], v[194:197], v[78:81]
	v_mfma_f32_16x16x32_bf16 v[74:77], v[170:173], v[194:197], v[74:77]
	v_mfma_f32_16x16x32_bf16 v[62:65], v[162:165], v[202:205], v[62:65]
	v_mfma_f32_16x16x32_bf16 v[58:61], v[170:173], v[202:205], v[58:61]
	v_mfma_f32_16x16x32_bf16 v[46:49], v[162:165], v[210:213], v[46:49]
	v_mfma_f32_16x16x32_bf16 v[42:45], v[170:173], v[210:213], v[42:45]
	v_mfma_f32_16x16x32_bf16 v[30:33], v[162:165], v[228:231], v[30:33]
	v_mfma_f32_16x16x32_bf16 v[26:29], v[170:173], v[228:231], v[26:29]
	v_mfma_f32_16x16x32_bf16 v[14:17], v[162:165], v[242:245], v[14:17]
	v_mfma_f32_16x16x32_bf16 v[10:13], v[170:173], v[242:245], v[10:13]
	v_mfma_f32_16x16x32_bf16 v[78:81], v[166:169], v[198:201], v[78:81]
	v_mfma_f32_16x16x32_bf16 v[74:77], v[174:177], v[198:201], v[74:77]
	v_mfma_f32_16x16x32_bf16 v[62:65], v[166:169], v[206:209], v[62:65]
	v_mfma_f32_16x16x32_bf16 v[58:61], v[174:177], v[206:209], v[58:61]
	v_mfma_f32_16x16x32_bf16 v[46:49], v[166:169], v[214:217], v[46:49]
	v_mfma_f32_16x16x32_bf16 v[42:45], v[174:177], v[214:217], v[42:45]
	v_mfma_f32_16x16x32_bf16 v[30:33], v[166:169], v[238:241], v[30:33]
	v_mfma_f32_16x16x32_bf16 v[26:29], v[174:177], v[238:241], v[26:29]
	v_mfma_f32_16x16x32_bf16 v[14:17], v[166:169], v[246:249], v[14:17]
	v_mfma_f32_16x16x32_bf16 v[10:13], v[174:177], v[246:249], v[10:13]
	v_mfma_f32_16x16x32_bf16 v[70:73], v[178:181], v[194:197], v[70:73]
	v_mfma_f32_16x16x32_bf16 v[66:69], v[186:189], v[194:197], v[66:69]
	v_mfma_f32_16x16x32_bf16 v[54:57], v[178:181], v[202:205], v[54:57]
	v_mfma_f32_16x16x32_bf16 v[50:53], v[186:189], v[202:205], v[50:53]
	v_mfma_f32_16x16x32_bf16 v[38:41], v[178:181], v[210:213], v[38:41]
	v_mfma_f32_16x16x32_bf16 v[34:37], v[186:189], v[210:213], v[34:37]
	v_mfma_f32_16x16x32_bf16 v[22:25], v[178:181], v[228:231], v[22:25]
	v_mfma_f32_16x16x32_bf16 v[18:21], v[186:189], v[228:231], v[18:21]
	v_mfma_f32_16x16x32_bf16 v[6:9], v[178:181], v[242:245], v[6:9]
	v_mfma_f32_16x16x32_bf16 v[2:5], v[186:189], v[242:245], v[2:5]
	v_mfma_f32_16x16x32_bf16 v[70:73], v[182:185], v[198:201], v[70:73]
	v_mfma_f32_16x16x32_bf16 v[66:69], v[190:193], v[198:201], v[66:69]
	v_mfma_f32_16x16x32_bf16 v[54:57], v[182:185], v[206:209], v[54:57]
	v_mfma_f32_16x16x32_bf16 v[50:53], v[190:193], v[206:209], v[50:53]
	v_mfma_f32_16x16x32_bf16 v[38:41], v[182:185], v[214:217], v[38:41]
	v_mfma_f32_16x16x32_bf16 v[34:37], v[190:193], v[214:217], v[34:37]
	v_mfma_f32_16x16x32_bf16 v[22:25], v[182:185], v[238:241], v[22:25]
	v_mfma_f32_16x16x32_bf16 v[18:21], v[190:193], v[238:241], v[18:21]
	v_mfma_f32_16x16x32_bf16 v[6:9], v[182:185], v[246:249], v[6:9]
	v_mfma_f32_16x16x32_bf16 v[2:5], v[190:193], v[246:249], v[2:5]
	s_barrier
	v_add_u32_e32 v174, 0x1c000, v223
	v_add_u32_e32 v190, 0x20000, v223
	ds_read_b128 v[162:165], v174
	ds_read_b128 v[166:169], v174 offset:1024
	ds_read_b128 v[170:173], v174 offset:2048
	ds_read_b128 v[174:177], v174 offset:3072
	ds_read_b128 v[178:181], v190
	ds_read_b128 v[182:185], v190 offset:1024
	ds_read_b128 v[186:189], v190 offset:2048
	ds_read_b128 v[190:193], v190 offset:3072
	ds_read_b128 v[194:197], v221 offset:40960
	ds_read_b128 v[198:201], v221 offset:41984
	ds_read_b128 v[202:205], v221 offset:43008
	ds_read_b128 v[206:209], v221 offset:44032
	ds_read_b128 v[210:213], v221 offset:45056
	ds_read_b128 v[214:217], v221 offset:46080
	ds_read_b128 v[228:231], v221 offset:47104
	ds_read_b128 v[238:241], v221 offset:48128
	ds_read_b128 v[242:245], v221 offset:49152
	ds_read_b128 v[246:249], v221 offset:50176
	s_add_u32 s74, s6, 0x60000
	s_addc_u32 s75, s7, 0
	s_add_i32 m0, s34, 0x3000
	s_nop 0
	global_load_lds_dwordx4 v0, s[74:75]
	s_add_u32 s74, s6, 0x80000
	s_addc_u32 s75, s7, 0
	s_add_i32 m0, s34, 0x4000
	s_nop 0
	global_load_lds_dwordx4 v0, s[74:75]
	s_add_u32 s74, s6, 0xa0000
	s_addc_u32 s75, s7, 0
	s_add_i32 m0, s34, 0x5000
	s_nop 0
	global_load_lds_dwordx4 v0, s[74:75]
	s_add_u32 s74, s6, 0xc0000
	s_addc_u32 s75, s7, 0
	s_add_i32 m0, s34, 0x6000
	s_nop 0
	global_load_lds_dwordx4 v0, s[74:75]
	s_waitcnt vmcnt(9)
	s_waitcnt lgkmcnt(0)
	s_barrier
	v_mfma_f32_16x16x32_bf16 v[158:161], v[162:165], v[194:197], v[158:161]
	v_mfma_f32_16x16x32_bf16 v[154:157], v[170:173], v[194:197], v[154:157]
	v_mfma_f32_16x16x32_bf16 v[142:145], v[162:165], v[202:205], v[142:145]
	v_mfma_f32_16x16x32_bf16 v[138:141], v[170:173], v[202:205], v[138:141]
	v_mfma_f32_16x16x32_bf16 v[126:129], v[162:165], v[210:213], v[126:129]
	v_mfma_f32_16x16x32_bf16 v[122:125], v[170:173], v[210:213], v[122:125]
	v_mfma_f32_16x16x32_bf16 v[110:113], v[162:165], v[228:231], v[110:113]
	v_mfma_f32_16x16x32_bf16 v[106:109], v[170:173], v[228:231], v[106:109]
	v_mfma_f32_16x16x32_bf16 v[94:97], v[162:165], v[242:245], v[94:97]
	v_mfma_f32_16x16x32_bf16 v[90:93], v[170:173], v[242:245], v[90:93]
	v_mfma_f32_16x16x32_bf16 v[158:161], v[166:169], v[198:201], v[158:161]
	v_mfma_f32_16x16x32_bf16 v[154:157], v[174:177], v[198:201], v[154:157]
	v_mfma_f32_16x16x32_bf16 v[142:145], v[166:169], v[206:209], v[142:145]
	v_mfma_f32_16x16x32_bf16 v[138:141], v[174:177], v[206:209], v[138:141]
	v_mfma_f32_16x16x32_bf16 v[126:129], v[166:169], v[214:217], v[126:129]
	v_mfma_f32_16x16x32_bf16 v[122:125], v[174:177], v[214:217], v[122:125]
	v_mfma_f32_16x16x32_bf16 v[110:113], v[166:169], v[238:241], v[110:113]
	v_mfma_f32_16x16x32_bf16 v[106:109], v[174:177], v[238:241], v[106:109]
	v_mfma_f32_16x16x32_bf16 v[94:97], v[166:169], v[246:249], v[94:97]
	v_mfma_f32_16x16x32_bf16 v[90:93], v[174:177], v[246:249], v[90:93]
	v_mfma_f32_16x16x32_bf16 v[150:153], v[178:181], v[194:197], v[150:153]
	v_mfma_f32_16x16x32_bf16 v[146:149], v[186:189], v[194:197], v[146:149]
	v_mfma_f32_16x16x32_bf16 v[134:137], v[178:181], v[202:205], v[134:137]
	v_mfma_f32_16x16x32_bf16 v[130:133], v[186:189], v[202:205], v[130:133]
	v_mfma_f32_16x16x32_bf16 v[118:121], v[178:181], v[210:213], v[118:121]
	v_mfma_f32_16x16x32_bf16 v[114:117], v[186:189], v[210:213], v[114:117]
	v_mfma_f32_16x16x32_bf16 v[102:105], v[178:181], v[228:231], v[102:105]
	v_mfma_f32_16x16x32_bf16 v[98:101], v[186:189], v[228:231], v[98:101]
	v_mfma_f32_16x16x32_bf16 v[86:89], v[178:181], v[242:245], v[86:89]
	v_mfma_f32_16x16x32_bf16 v[82:85], v[186:189], v[242:245], v[82:85]
	v_mfma_f32_16x16x32_bf16 v[150:153], v[182:185], v[198:201], v[150:153]
	v_mfma_f32_16x16x32_bf16 v[146:149], v[190:193], v[198:201], v[146:149]
	v_mfma_f32_16x16x32_bf16 v[134:137], v[182:185], v[206:209], v[134:137]
	v_mfma_f32_16x16x32_bf16 v[130:133], v[190:193], v[206:209], v[130:133]
	v_mfma_f32_16x16x32_bf16 v[118:121], v[182:185], v[214:217], v[118:121]
	v_mfma_f32_16x16x32_bf16 v[114:117], v[190:193], v[214:217], v[114:117]
	v_mfma_f32_16x16x32_bf16 v[102:105], v[182:185], v[238:241], v[102:105]
	v_mfma_f32_16x16x32_bf16 v[98:101], v[190:193], v[238:241], v[98:101]
	v_mfma_f32_16x16x32_bf16 v[86:89], v[182:185], v[246:249], v[86:89]
	v_mfma_f32_16x16x32_bf16 v[82:85], v[190:193], v[246:249], v[82:85]
	s_barrier
	ds_read_b128 v[194:197], v221 offset:61440
	ds_read_b128 v[198:201], v221 offset:62464
	ds_read_b128 v[202:205], v221 offset:63488
	ds_read_b128 v[206:209], v221 offset:64512
	ds_read_b128 v[210:213], v222 offset:4096
	ds_read_b128 v[214:217], v222 offset:5120
	ds_read_b128 v[228:231], v222 offset:6144
	ds_read_b128 v[238:241], v222 offset:7168
	ds_read_b128 v[242:245], v222 offset:8192
	ds_read_b128 v[246:249], v222 offset:9216
	s_add_u32 s74, s16, 0x80
	s_addc_u32 s75, s17, 0
	s_add_i32 m0, s34, 0x1c000
	s_nop 0
	global_load_lds_dwordx4 v220, s[74:75]
	s_add_u32 s74, s16, 0x8080
	s_addc_u32 s75, s17, 0
	s_add_i32 m0, s34, 0x1d000
	s_nop 0
	global_load_lds_dwordx4 v220, s[74:75]
	s_add_u32 s74, s16, 0x10080
	s_addc_u32 s75, s17, 0
	s_add_i32 m0, s34, 0x1e000
	s_nop 0
	global_load_lds_dwordx4 v220, s[74:75]
	s_add_u32 s74, s16, 0x18080
	s_addc_u32 s75, s17, 0
	s_add_i32 m0, s34, 0x1f000
	s_nop 0
	global_load_lds_dwordx4 v220, s[74:75]
	s_add_u32 s74, s6, 0x40080
	s_addc_u32 s75, s7, 0
	s_add_i32 m0, s34, 0xc000
	s_nop 0
	global_load_lds_dwordx4 v0, s[74:75]
	s_waitcnt vmcnt(9)
	s_waitcnt lgkmcnt(0)
	s_barrier
	v_mfma_f32_16x16x32_bf16 v[78:81], v[162:165], v[194:197], v[78:81]
	v_mfma_f32_16x16x32_bf16 v[74:77], v[170:173], v[194:197], v[74:77]
	v_mfma_f32_16x16x32_bf16 v[62:65], v[162:165], v[202:205], v[62:65]
	v_mfma_f32_16x16x32_bf16 v[58:61], v[170:173], v[202:205], v[58:61]
	v_mfma_f32_16x16x32_bf16 v[46:49], v[162:165], v[210:213], v[46:49]
	v_mfma_f32_16x16x32_bf16 v[42:45], v[170:173], v[210:213], v[42:45]
	v_mfma_f32_16x16x32_bf16 v[30:33], v[162:165], v[228:231], v[30:33]
	v_mfma_f32_16x16x32_bf16 v[26:29], v[170:173], v[228:231], v[26:29]
	v_mfma_f32_16x16x32_bf16 v[14:17], v[162:165], v[242:245], v[14:17]
	v_mfma_f32_16x16x32_bf16 v[10:13], v[170:173], v[242:245], v[10:13]
	v_mfma_f32_16x16x32_bf16 v[78:81], v[166:169], v[198:201], v[78:81]
	v_mfma_f32_16x16x32_bf16 v[74:77], v[174:177], v[198:201], v[74:77]
	v_mfma_f32_16x16x32_bf16 v[62:65], v[166:169], v[206:209], v[62:65]
	v_mfma_f32_16x16x32_bf16 v[58:61], v[174:177], v[206:209], v[58:61]
	v_mfma_f32_16x16x32_bf16 v[46:49], v[166:169], v[214:217], v[46:49]
	v_mfma_f32_16x16x32_bf16 v[42:45], v[174:177], v[214:217], v[42:45]
	v_mfma_f32_16x16x32_bf16 v[30:33], v[166:169], v[238:241], v[30:33]
	v_mfma_f32_16x16x32_bf16 v[26:29], v[174:177], v[238:241], v[26:29]
	v_mfma_f32_16x16x32_bf16 v[14:17], v[166:169], v[246:249], v[14:17]
	v_mfma_f32_16x16x32_bf16 v[10:13], v[174:177], v[246:249], v[10:13]
	v_mfma_f32_16x16x32_bf16 v[70:73], v[178:181], v[194:197], v[70:73]
	v_mfma_f32_16x16x32_bf16 v[66:69], v[186:189], v[194:197], v[66:69]
	v_mfma_f32_16x16x32_bf16 v[54:57], v[178:181], v[202:205], v[54:57]
	v_mfma_f32_16x16x32_bf16 v[50:53], v[186:189], v[202:205], v[50:53]
	v_mfma_f32_16x16x32_bf16 v[38:41], v[178:181], v[210:213], v[38:41]
	v_mfma_f32_16x16x32_bf16 v[34:37], v[186:189], v[210:213], v[34:37]
	v_mfma_f32_16x16x32_bf16 v[22:25], v[178:181], v[228:231], v[22:25]
	v_mfma_f32_16x16x32_bf16 v[18:21], v[186:189], v[228:231], v[18:21]
	v_mfma_f32_16x16x32_bf16 v[6:9], v[178:181], v[242:245], v[6:9]
	v_mfma_f32_16x16x32_bf16 v[2:5], v[186:189], v[242:245], v[2:5]
	v_mfma_f32_16x16x32_bf16 v[70:73], v[182:185], v[198:201], v[70:73]
	v_mfma_f32_16x16x32_bf16 v[66:69], v[190:193], v[198:201], v[66:69]
	v_mfma_f32_16x16x32_bf16 v[54:57], v[182:185], v[206:209], v[54:57]
	v_mfma_f32_16x16x32_bf16 v[50:53], v[190:193], v[206:209], v[50:53]
	v_mfma_f32_16x16x32_bf16 v[38:41], v[182:185], v[214:217], v[38:41]
	v_mfma_f32_16x16x32_bf16 v[34:37], v[190:193], v[214:217], v[34:37]
	v_mfma_f32_16x16x32_bf16 v[22:25], v[182:185], v[238:241], v[22:25]
	v_mfma_f32_16x16x32_bf16 v[18:21], v[190:193], v[238:241], v[18:21]
	v_mfma_f32_16x16x32_bf16 v[6:9], v[182:185], v[246:249], v[6:9]
	v_mfma_f32_16x16x32_bf16 v[2:5], v[190:193], v[246:249], v[2:5]
	s_barrier
	s_add_i32 s14, s14, 2
	s_add_u32 s4, s4, 0x100
	s_addc_u32 s5, s5, 0
	s_add_u32 vcc_lo, vcc_lo, 0x100
	s_addc_u32 vcc_hi, vcc_hi, 0
	s_cmp_gt_u32 s14, 5
	s_cbranch_scc0 .LBB0_929
	s_and_b64 vcc, exec, s[18:19]
	s_cbranch_vccz .LBB0_932
	s_barrier

.LBB0_1522:
	v_add_u32_e32 v154, 0x14000, v223
	v_add_u32_e32 v178, 0x18000, v223
	ds_read_b128 v[138:141], v154
	ds_read_b128 v[142:145], v154 offset:1024
	ds_read_b128 v[146:149], v154 offset:2048
	ds_read_b128 v[154:157], v154 offset:3072
	ds_read_b128 v[162:165], v178
	ds_read_b128 v[170:173], v178 offset:1024
	ds_read_b128 v[174:177], v178 offset:2048
	ds_read_b128 v[178:181], v178 offset:3072
	s_add_u32 s10, s6, 0xfff60080
	s_addc_u32 s11, s7, -1
	s_cmp_eq_u32 s70, 28
	s_cselect_b32 s10, s18, s10
	s_cselect_b32 s11, s19, s11
	s_cselect_b32 s22, s64, s66
	s_cselect_b32 s23, s15, s68
	s_add_u32 s16, s10, 0x80
	s_addc_u32 s17, s11, 0
	ds_read_b128 v[194:197], v221
	ds_read_b128 v[198:201], v221 offset:1024
	ds_read_b128 v[202:205], v221 offset:2048
	ds_read_b128 v[206:209], v221 offset:3072
	ds_read_b128 v[210:213], v221 offset:4096
	ds_read_b128 v[214:217], v221 offset:5120
	ds_read_b128 v[228:231], v221 offset:6144
	ds_read_b128 v[238:241], v221 offset:7168
	ds_read_b128 v[242:245], v221 offset:8192
	ds_read_b128 v[246:249], v221 offset:9216
	s_add_u32 s74, s10, 0xfffe0000
	s_addc_u32 s75, s11, -1
	s_add_i32 m0, s28, 0xfffff000
	s_nop 0
	global_load_lds_dwordx4 v0, s[74:75]
	s_mov_b32 s74, s10
	s_mov_b32 s75, s11
	s_mov_b32 m0, s28
	s_nop 0
	global_load_lds_dwordx4 v0, s[74:75]
	s_add_u32 s74, s6, 0x40000
	s_addc_u32 s75, s7, 0
	s_add_i32 m0, s28, 0x11000
	s_nop 0
	global_load_lds_dwordx4 v0, s[74:75]
	s_add_u32 s74, s6, 0x60000
	s_addc_u32 s75, s7, 0
	s_add_i32 m0, s28, 0x12000
	s_nop 0
	global_load_lds_dwordx4 v0, s[74:75]
	s_add_u32 s74, s6, 0x20000
	s_addc_u32 s75, s7, 0
	s_add_i32 m0, s28, 0x10000
	s_nop 0
	global_load_lds_dwordx4 v0, s[74:75]
	s_waitcnt vmcnt(9)
	s_waitcnt lgkmcnt(0)
	s_barrier
	v_mfma_f32_16x16x32_bf16 v[190:193], v[138:141], v[194:197], v[190:193]
	v_mfma_f32_16x16x32_bf16 v[186:189], v[146:149], v[194:197], v[186:189]
	v_mfma_f32_16x16x32_bf16 v[158:161], v[138:141], v[202:205], v[158:161]
	v_mfma_f32_16x16x32_bf16 v[150:153], v[146:149], v[202:205], v[150:153]
	v_mfma_f32_16x16x32_bf16 v[126:129], v[138:141], v[210:213], v[126:129]
	v_mfma_f32_16x16x32_bf16 v[122:125], v[146:149], v[210:213], v[122:125]
	v_mfma_f32_16x16x32_bf16 v[110:113], v[138:141], v[228:231], v[110:113]
	v_mfma_f32_16x16x32_bf16 v[106:109], v[146:149], v[228:231], v[106:109]
	v_mfma_f32_16x16x32_bf16 v[94:97], v[138:141], v[242:245], v[94:97]
	v_mfma_f32_16x16x32_bf16 v[90:93], v[146:149], v[242:245], v[90:93]
	v_mfma_f32_16x16x32_bf16 v[190:193], v[142:145], v[198:201], v[190:193]
	v_mfma_f32_16x16x32_bf16 v[186:189], v[154:157], v[198:201], v[186:189]
	v_mfma_f32_16x16x32_bf16 v[158:161], v[142:145], v[206:209], v[158:161]
	v_mfma_f32_16x16x32_bf16 v[150:153], v[154:157], v[206:209], v[150:153]
	v_mfma_f32_16x16x32_bf16 v[126:129], v[142:145], v[214:217], v[126:129]
	v_mfma_f32_16x16x32_bf16 v[122:125], v[154:157], v[214:217], v[122:125]
	v_mfma_f32_16x16x32_bf16 v[110:113], v[142:145], v[238:241], v[110:113]
	v_mfma_f32_16x16x32_bf16 v[106:109], v[154:157], v[238:241], v[106:109]
	v_mfma_f32_16x16x32_bf16 v[94:97], v[142:145], v[246:249], v[94:97]
	v_mfma_f32_16x16x32_bf16 v[90:93], v[154:157], v[246:249], v[90:93]
	v_mfma_f32_16x16x32_bf16 v[182:185], v[162:165], v[194:197], v[182:185]
	v_mfma_f32_16x16x32_bf16 v[166:169], v[174:177], v[194:197], v[166:169]
	v_mfma_f32_16x16x32_bf16 v[134:137], v[162:165], v[202:205], v[134:137]
	v_mfma_f32_16x16x32_bf16 v[130:133], v[174:177], v[202:205], v[130:133]
	v_mfma_f32_16x16x32_bf16 v[118:121], v[162:165], v[210:213], v[118:121]
	v_mfma_f32_16x16x32_bf16 v[114:117], v[174:177], v[210:213], v[114:117]
	v_mfma_f32_16x16x32_bf16 v[102:105], v[162:165], v[228:231], v[102:105]
	v_mfma_f32_16x16x32_bf16 v[98:101], v[174:177], v[228:231], v[98:101]
	v_mfma_f32_16x16x32_bf16 v[86:89], v[162:165], v[242:245], v[86:89]
	v_mfma_f32_16x16x32_bf16 v[82:85], v[174:177], v[242:245], v[82:85]
	v_mfma_f32_16x16x32_bf16 v[182:185], v[170:173], v[198:201], v[182:185]
	v_mfma_f32_16x16x32_bf16 v[166:169], v[178:181], v[198:201], v[166:169]
	v_mfma_f32_16x16x32_bf16 v[134:137], v[170:173], v[206:209], v[134:137]
	v_mfma_f32_16x16x32_bf16 v[130:133], v[178:181], v[206:209], v[130:133]
	v_mfma_f32_16x16x32_bf16 v[118:121], v[170:173], v[214:217], v[118:121]
	v_mfma_f32_16x16x32_bf16 v[114:117], v[178:181], v[214:217], v[114:117]
	v_mfma_f32_16x16x32_bf16 v[102:105], v[170:173], v[238:241], v[102:105]
	v_mfma_f32_16x16x32_bf16 v[98:101], v[178:181], v[238:241], v[98:101]
	v_mfma_f32_16x16x32_bf16 v[86:89], v[170:173], v[246:249], v[86:89]
	v_mfma_f32_16x16x32_bf16 v[82:85], v[178:181], v[246:249], v[82:85]
	s_barrier
	ds_read_b128 v[194:197], v221 offset:20480
	ds_read_b128 v[198:201], v221 offset:21504
	ds_read_b128 v[202:205], v221 offset:22528
	ds_read_b128 v[206:209], v221 offset:23552
	ds_read_b128 v[210:213], v221 offset:24576
	ds_read_b128 v[214:217], v221 offset:25600
	ds_read_b128 v[228:231], v221 offset:26624
	ds_read_b128 v[238:241], v221 offset:27648
	ds_read_b128 v[242:245], v221 offset:28672
	ds_read_b128 v[246:249], v221 offset:29696
	s_add_u32 s74, s22, 0x60000
	s_addc_u32 s75, s23, 0
	s_add_i32 m0, s28, 0x17000
	s_nop 0
	global_load_lds_dwordx4 v220, s[74:75]
	s_add_u32 s74, s22, 0x80000
	s_addc_u32 s75, s23, 0
	s_add_i32 m0, s28, 0x18000
	s_nop 0
	global_load_lds_dwordx4 v220, s[74:75]
	s_add_u32 s74, s22, 0xa0000
	s_addc_u32 s75, s23, 0
	s_add_i32 m0, s28, 0x19000
	s_nop 0
	global_load_lds_dwordx4 v220, s[74:75]
	s_add_u32 s74, s22, 0xc0000
	s_addc_u32 s75, s23, 0
	s_add_i32 m0, s28, 0x1a000
	s_nop 0
	global_load_lds_dwordx4 v220, s[74:75]
	s_waitcnt vmcnt(9)
	s_waitcnt lgkmcnt(0)
	s_barrier
	v_mfma_f32_16x16x32_bf16 v[78:81], v[138:141], v[194:197], v[78:81]
	v_mfma_f32_16x16x32_bf16 v[74:77], v[146:149], v[194:197], v[74:77]
	v_mfma_f32_16x16x32_bf16 v[62:65], v[138:141], v[202:205], v[62:65]
	v_mfma_f32_16x16x32_bf16 v[58:61], v[146:149], v[202:205], v[58:61]
	v_mfma_f32_16x16x32_bf16 v[46:49], v[138:141], v[210:213], v[46:49]
	v_mfma_f32_16x16x32_bf16 v[42:45], v[146:149], v[210:213], v[42:45]
	v_mfma_f32_16x16x32_bf16 v[30:33], v[138:141], v[228:231], v[30:33]
	v_mfma_f32_16x16x32_bf16 v[26:29], v[146:149], v[228:231], v[26:29]
	v_mfma_f32_16x16x32_bf16 v[14:17], v[138:141], v[242:245], v[14:17]
	v_mfma_f32_16x16x32_bf16 v[10:13], v[146:149], v[242:245], v[10:13]
	v_mfma_f32_16x16x32_bf16 v[78:81], v[142:145], v[198:201], v[78:81]
	v_mfma_f32_16x16x32_bf16 v[74:77], v[154:157], v[198:201], v[74:77]
	v_mfma_f32_16x16x32_bf16 v[62:65], v[142:145], v[206:209], v[62:65]
	v_mfma_f32_16x16x32_bf16 v[58:61], v[154:157], v[206:209], v[58:61]
	v_mfma_f32_16x16x32_bf16 v[46:49], v[142:145], v[214:217], v[46:49]
	v_mfma_f32_16x16x32_bf16 v[42:45], v[154:157], v[214:217], v[42:45]
	v_mfma_f32_16x16x32_bf16 v[30:33], v[142:145], v[238:241], v[30:33]
	v_mfma_f32_16x16x32_bf16 v[26:29], v[154:157], v[238:241], v[26:29]
	v_mfma_f32_16x16x32_bf16 v[14:17], v[142:145], v[246:249], v[14:17]
	v_mfma_f32_16x16x32_bf16 v[10:13], v[154:157], v[246:249], v[10:13]
	v_mfma_f32_16x16x32_bf16 v[70:73], v[162:165], v[194:197], v[70:73]
	v_mfma_f32_16x16x32_bf16 v[66:69], v[174:177], v[194:197], v[66:69]
	v_mfma_f32_16x16x32_bf16 v[54:57], v[162:165], v[202:205], v[54:57]
	v_mfma_f32_16x16x32_bf16 v[50:53], v[174:177], v[202:205], v[50:53]
	v_mfma_f32_16x16x32_bf16 v[38:41], v[162:165], v[210:213], v[38:41]
	v_mfma_f32_16x16x32_bf16 v[34:37], v[174:177], v[210:213], v[34:37]
	v_mfma_f32_16x16x32_bf16 v[22:25], v[162:165], v[228:231], v[22:25]
	v_mfma_f32_16x16x32_bf16 v[18:21], v[174:177], v[228:231], v[18:21]
	v_mfma_f32_16x16x32_bf16 v[6:9], v[162:165], v[242:245], v[6:9]
	v_mfma_f32_16x16x32_bf16 v[2:5], v[174:177], v[242:245], v[2:5]
	v_mfma_f32_16x16x32_bf16 v[70:73], v[170:173], v[198:201], v[70:73]
	v_mfma_f32_16x16x32_bf16 v[66:69], v[178:181], v[198:201], v[66:69]
	v_mfma_f32_16x16x32_bf16 v[54:57], v[170:173], v[206:209], v[54:57]
	v_mfma_f32_16x16x32_bf16 v[50:53], v[178:181], v[206:209], v[50:53]
	v_mfma_f32_16x16x32_bf16 v[38:41], v[170:173], v[214:217], v[38:41]
	v_mfma_f32_16x16x32_bf16 v[34:37], v[178:181], v[214:217], v[34:37]
	v_mfma_f32_16x16x32_bf16 v[22:25], v[170:173], v[238:241], v[22:25]
	v_mfma_f32_16x16x32_bf16 v[18:21], v[178:181], v[238:241], v[18:21]
	v_mfma_f32_16x16x32_bf16 v[6:9], v[170:173], v[246:249], v[6:9]
	v_mfma_f32_16x16x32_bf16 v[2:5], v[178:181], v[246:249], v[2:5]
	s_barrier
	v_add_u32_e32 v154, 0x1c000, v223
	v_add_u32_e32 v178, 0x20000, v223
	ds_read_b128 v[138:141], v154
	ds_read_b128 v[142:145], v154 offset:1024
	ds_read_b128 v[146:149], v154 offset:2048
	ds_read_b128 v[154:157], v154 offset:3072
	ds_read_b128 v[162:165], v178
	ds_read_b128 v[170:173], v178 offset:1024
	ds_read_b128 v[174:177], v178 offset:2048
	ds_read_b128 v[178:181], v178 offset:3072
	ds_read_b128 v[194:197], v221 offset:40960
	ds_read_b128 v[198:201], v221 offset:41984
	ds_read_b128 v[202:205], v221 offset:43008
	ds_read_b128 v[206:209], v221 offset:44032
	ds_read_b128 v[210:213], v221 offset:45056
	ds_read_b128 v[214:217], v221 offset:46080
	ds_read_b128 v[228:231], v221 offset:47104
	ds_read_b128 v[238:241], v221 offset:48128
	ds_read_b128 v[242:245], v221 offset:49152
	ds_read_b128 v[246:249], v221 offset:50176
	s_add_u32 s74, s10, 0xfffe0080
	s_addc_u32 s75, s11, -1
	s_add_i32 m0, s28, 0x9000
	s_nop 0
	global_load_lds_dwordx4 v0, s[74:75]
	s_add_u32 s74, s10, 0x80
	s_addc_u32 s75, s11, 0
	s_add_i32 m0, s28, 0xa000
	s_nop 0
	global_load_lds_dwordx4 v0, s[74:75]
	s_add_u32 s74, s10, 0xe0000
	s_addc_u32 s75, s11, 0
	s_add_i32 m0, s28, 0x7000
	s_nop 0
	global_load_lds_dwordx4 v0, s[74:75]
	s_add_u32 s74, s10, 0x100000
	s_addc_u32 s75, s11, 0
	s_add_i32 m0, s28, 0x8000
	s_nop 0
	global_load_lds_dwordx4 v0, s[74:75]
	s_add_u32 s74, s10, 0xc0000
	s_addc_u32 s75, s11, 0
	s_add_i32 m0, s28, 0x6000
	s_nop 0
	global_load_lds_dwordx4 v0, s[74:75]
	s_waitcnt vmcnt(9)
	s_waitcnt lgkmcnt(0)
	s_barrier
	v_mfma_f32_16x16x32_bf16 v[190:193], v[138:141], v[194:197], v[190:193]
	v_mfma_f32_16x16x32_bf16 v[186:189], v[146:149], v[194:197], v[186:189]
	v_mfma_f32_16x16x32_bf16 v[158:161], v[138:141], v[202:205], v[158:161]
	v_mfma_f32_16x16x32_bf16 v[150:153], v[146:149], v[202:205], v[150:153]
	v_mfma_f32_16x16x32_bf16 v[126:129], v[138:141], v[210:213], v[126:129]
	v_mfma_f32_16x16x32_bf16 v[122:125], v[146:149], v[210:213], v[122:125]
	v_mfma_f32_16x16x32_bf16 v[110:113], v[138:141], v[228:231], v[110:113]
	v_mfma_f32_16x16x32_bf16 v[106:109], v[146:149], v[228:231], v[106:109]
	v_mfma_f32_16x16x32_bf16 v[94:97], v[138:141], v[242:245], v[94:97]
	v_mfma_f32_16x16x32_bf16 v[90:93], v[146:149], v[242:245], v[90:93]
	v_mfma_f32_16x16x32_bf16 v[190:193], v[142:145], v[198:201], v[190:193]
	v_mfma_f32_16x16x32_bf16 v[186:189], v[154:157], v[198:201], v[186:189]
	v_mfma_f32_16x16x32_bf16 v[158:161], v[142:145], v[206:209], v[158:161]
	v_mfma_f32_16x16x32_bf16 v[150:153], v[154:157], v[206:209], v[150:153]
	v_mfma_f32_16x16x32_bf16 v[126:129], v[142:145], v[214:217], v[126:129]
	v_mfma_f32_16x16x32_bf16 v[122:125], v[154:157], v[214:217], v[122:125]
	v_mfma_f32_16x16x32_bf16 v[110:113], v[142:145], v[238:241], v[110:113]
	v_mfma_f32_16x16x32_bf16 v[106:109], v[154:157], v[238:241], v[106:109]
	v_mfma_f32_16x16x32_bf16 v[94:97], v[142:145], v[246:249], v[94:97]
	v_mfma_f32_16x16x32_bf16 v[90:93], v[154:157], v[246:249], v[90:93]
	v_mfma_f32_16x16x32_bf16 v[182:185], v[162:165], v[194:197], v[182:185]
	v_mfma_f32_16x16x32_bf16 v[166:169], v[174:177], v[194:197], v[166:169]
	v_mfma_f32_16x16x32_bf16 v[134:137], v[162:165], v[202:205], v[134:137]
	v_mfma_f32_16x16x32_bf16 v[130:133], v[174:177], v[202:205], v[130:133]
	v_mfma_f32_16x16x32_bf16 v[118:121], v[162:165], v[210:213], v[118:121]
	v_mfma_f32_16x16x32_bf16 v[114:117], v[174:177], v[210:213], v[114:117]
	v_mfma_f32_16x16x32_bf16 v[102:105], v[162:165], v[228:231], v[102:105]
	v_mfma_f32_16x16x32_bf16 v[98:101], v[174:177], v[228:231], v[98:101]
	v_mfma_f32_16x16x32_bf16 v[86:89], v[162:165], v[242:245], v[86:89]
	v_mfma_f32_16x16x32_bf16 v[82:85], v[174:177], v[242:245], v[82:85]
	v_mfma_f32_16x16x32_bf16 v[182:185], v[170:173], v[198:201], v[182:185]
	v_mfma_f32_16x16x32_bf16 v[166:169], v[178:181], v[198:201], v[166:169]
	v_mfma_f32_16x16x32_bf16 v[134:137], v[170:173], v[206:209], v[134:137]
	v_mfma_f32_16x16x32_bf16 v[130:133], v[178:181], v[206:209], v[130:133]
	v_mfma_f32_16x16x32_bf16 v[118:121], v[170:173], v[214:217], v[118:121]
	v_mfma_f32_16x16x32_bf16 v[114:117], v[178:181], v[214:217], v[114:117]
	v_mfma_f32_16x16x32_bf16 v[102:105], v[170:173], v[238:241], v[102:105]
	v_mfma_f32_16x16x32_bf16 v[98:101], v[178:181], v[238:241], v[98:101]
	v_mfma_f32_16x16x32_bf16 v[86:89], v[170:173], v[246:249], v[86:89]
	v_mfma_f32_16x16x32_bf16 v[82:85], v[178:181], v[246:249], v[82:85]
	s_barrier
	ds_read_b128 v[194:197], v221 offset:61440
	ds_read_b128 v[198:201], v221 offset:62464
	ds_read_b128 v[202:205], v221 offset:63488
	ds_read_b128 v[206:209], v221 offset:64512
	ds_read_b128 v[210:213], v222 offset:4096
	ds_read_b128 v[214:217], v222 offset:5120
	ds_read_b128 v[228:231], v222 offset:6144
	ds_read_b128 v[238:241], v222 offset:7168
	ds_read_b128 v[242:245], v222 offset:8192
	ds_read_b128 v[246:249], v222 offset:9216
	s_add_u32 s74, s22, 0x60080
	s_addc_u32 s75, s23, 0
	s_add_i32 m0, s28, 0x1f000
	s_nop 0
	global_load_lds_dwordx4 v220, s[74:75]
	s_add_u32 s74, s22, 0x80080
	s_addc_u32 s75, s23, 0
	s_add_i32 m0, s28, 0x20000
	s_nop 0
	global_load_lds_dwordx4 v220, s[74:75]
	s_add_u32 s74, s22, 0xa0080
	s_addc_u32 s75, s23, 0
	s_add_i32 m0, s28, 0x21000
	s_nop 0
	global_load_lds_dwordx4 v220, s[74:75]
	s_add_u32 s74, s22, 0xc0080
	s_addc_u32 s75, s23, 0
	s_add_i32 m0, s28, 0x22000
	s_nop 0
	global_load_lds_dwordx4 v220, s[74:75]
	s_waitcnt vmcnt(9)
	s_waitcnt lgkmcnt(0)
	s_barrier
	v_mfma_f32_16x16x32_bf16 v[78:81], v[138:141], v[194:197], v[78:81]
	v_mfma_f32_16x16x32_bf16 v[74:77], v[146:149], v[194:197], v[74:77]
	v_mfma_f32_16x16x32_bf16 v[62:65], v[138:141], v[202:205], v[62:65]
	v_mfma_f32_16x16x32_bf16 v[58:61], v[146:149], v[202:205], v[58:61]
	v_mfma_f32_16x16x32_bf16 v[46:49], v[138:141], v[210:213], v[46:49]
	v_mfma_f32_16x16x32_bf16 v[42:45], v[146:149], v[210:213], v[42:45]
	v_mfma_f32_16x16x32_bf16 v[30:33], v[138:141], v[228:231], v[30:33]
	v_mfma_f32_16x16x32_bf16 v[26:29], v[146:149], v[228:231], v[26:29]
	v_mfma_f32_16x16x32_bf16 v[14:17], v[138:141], v[242:245], v[14:17]
	v_mfma_f32_16x16x32_bf16 v[10:13], v[146:149], v[242:245], v[10:13]
	v_mfma_f32_16x16x32_bf16 v[78:81], v[142:145], v[198:201], v[78:81]
	v_mfma_f32_16x16x32_bf16 v[74:77], v[154:157], v[198:201], v[74:77]
	v_mfma_f32_16x16x32_bf16 v[62:65], v[142:145], v[206:209], v[62:65]
	v_mfma_f32_16x16x32_bf16 v[58:61], v[154:157], v[206:209], v[58:61]
	v_mfma_f32_16x16x32_bf16 v[46:49], v[142:145], v[214:217], v[46:49]
	v_mfma_f32_16x16x32_bf16 v[42:45], v[154:157], v[214:217], v[42:45]
	v_mfma_f32_16x16x32_bf16 v[30:33], v[142:145], v[238:241], v[30:33]
	v_mfma_f32_16x16x32_bf16 v[26:29], v[154:157], v[238:241], v[26:29]
	v_mfma_f32_16x16x32_bf16 v[14:17], v[142:145], v[246:249], v[14:17]
	v_mfma_f32_16x16x32_bf16 v[10:13], v[154:157], v[246:249], v[10:13]
	v_mfma_f32_16x16x32_bf16 v[70:73], v[162:165], v[194:197], v[70:73]
	v_mfma_f32_16x16x32_bf16 v[66:69], v[174:177], v[194:197], v[66:69]
	v_mfma_f32_16x16x32_bf16 v[54:57], v[162:165], v[202:205], v[54:57]
	v_mfma_f32_16x16x32_bf16 v[50:53], v[174:177], v[202:205], v[50:53]
	v_mfma_f32_16x16x32_bf16 v[38:41], v[162:165], v[210:213], v[38:41]
	v_mfma_f32_16x16x32_bf16 v[34:37], v[174:177], v[210:213], v[34:37]
	v_mfma_f32_16x16x32_bf16 v[22:25], v[162:165], v[228:231], v[22:25]
	v_mfma_f32_16x16x32_bf16 v[18:21], v[174:177], v[228:231], v[18:21]
	v_mfma_f32_16x16x32_bf16 v[6:9], v[162:165], v[242:245], v[6:9]
	v_mfma_f32_16x16x32_bf16 v[2:5], v[174:177], v[242:245], v[2:5]
	v_mfma_f32_16x16x32_bf16 v[70:73], v[170:173], v[198:201], v[70:73]
	v_mfma_f32_16x16x32_bf16 v[66:69], v[178:181], v[198:201], v[66:69]
	v_mfma_f32_16x16x32_bf16 v[54:57], v[170:173], v[206:209], v[54:57]
	v_mfma_f32_16x16x32_bf16 v[50:53], v[178:181], v[206:209], v[50:53]
	v_mfma_f32_16x16x32_bf16 v[38:41], v[170:173], v[214:217], v[38:41]
	v_mfma_f32_16x16x32_bf16 v[34:37], v[178:181], v[214:217], v[34:37]
	v_mfma_f32_16x16x32_bf16 v[22:25], v[170:173], v[238:241], v[22:25]
	v_mfma_f32_16x16x32_bf16 v[18:21], v[178:181], v[238:241], v[18:21]
	v_mfma_f32_16x16x32_bf16 v[6:9], v[170:173], v[246:249], v[6:9]
	v_mfma_f32_16x16x32_bf16 v[2:5], v[178:181], v[246:249], v[2:5]
	s_barrier
	s_add_i32 s70, s70, 2
	s_add_u32 s6, s6, 0x100
	s_addc_u32 s7, s7, 0
	s_add_u32 s66, s66, 0x100
	s_addc_u32 s68, s68, 0
	s_cmp_gt_u32 s70, 29
	s_cbranch_scc0 .LBB0_1522
	s_and_b64 vcc, exec, s[12:13]
	s_cbranch_vccz .LBB0_1525
	s_barrier

.LBB0_1546:
	v_add_u32_e32 v158, 0x14000, v223
	v_add_u32_e32 v178, 0x18000, v223
	ds_read_b128 v[142:145], v158
	ds_read_b128 v[146:149], v158 offset:1024
	ds_read_b128 v[154:157], v158 offset:2048
	ds_read_b128 v[158:161], v158 offset:3072
	ds_read_b128 v[166:169], v178
	ds_read_b128 v[170:173], v178 offset:1024
	ds_read_b128 v[174:177], v178 offset:2048
	ds_read_b128 v[178:181], v178 offset:3072
	s_add_u32 s10, s6, 0xfff60080
	s_addc_u32 s11, s7, -1
	s_cmp_eq_u32 s97, 28
	s_cselect_b32 s10, s18, s10
	s_cselect_b32 s11, s19, s11
	s_cselect_b32 s22, s72, s84
	s_cselect_b32 s23, s15, s92
	s_add_u32 s16, s10, 0x80
	s_addc_u32 s17, s11, 0
	ds_read_b128 v[194:197], v221
	ds_read_b128 v[198:201], v221 offset:1024
	ds_read_b128 v[202:205], v221 offset:2048
	ds_read_b128 v[206:209], v221 offset:3072
	ds_read_b128 v[210:213], v221 offset:4096
	ds_read_b128 v[214:217], v221 offset:5120
	ds_read_b128 v[228:231], v221 offset:6144
	ds_read_b128 v[238:241], v221 offset:7168
	ds_read_b128 v[242:245], v221 offset:8192
	ds_read_b128 v[246:249], v221 offset:9216
	s_add_u32 s74, s6, 0xfffc0000
	s_addc_u32 s75, s7, -1
	s_add_i32 m0, s28, 0xd000
	s_nop 0
	global_load_lds_dwordx4 v0, s[74:75]
	s_add_u32 s74, s6, 0xfffe0000
	s_addc_u32 s75, s7, -1
	s_add_i32 m0, s28, 0xe000
	s_nop 0
	global_load_lds_dwordx4 v0, s[74:75]
	s_mov_b32 s74, s6
	s_mov_b32 s75, s7
	s_add_i32 m0, s28, 0xf000
	s_nop 0
	global_load_lds_dwordx4 v0, s[74:75]
	s_add_u32 s74, s6, 0x20000
	s_addc_u32 s75, s7, 0
	s_add_i32 m0, s28, 0x10000
	s_nop 0
	global_load_lds_dwordx4 v0, s[74:75]
	s_waitcnt vmcnt(9)
	s_waitcnt lgkmcnt(0)
	s_barrier
	v_mfma_f32_16x16x32_bf16 v[190:193], v[142:145], v[194:197], v[190:193]
	v_mfma_f32_16x16x32_bf16 v[186:189], v[154:157], v[194:197], v[186:189]
	v_mfma_f32_16x16x32_bf16 v[150:153], v[142:145], v[202:205], v[150:153]
	v_mfma_f32_16x16x32_bf16 v[138:141], v[154:157], v[202:205], v[138:141]
	v_mfma_f32_16x16x32_bf16 v[126:129], v[142:145], v[210:213], v[126:129]
	v_mfma_f32_16x16x32_bf16 v[122:125], v[154:157], v[210:213], v[122:125]
	v_mfma_f32_16x16x32_bf16 v[110:113], v[142:145], v[228:231], v[110:113]
	v_mfma_f32_16x16x32_bf16 v[106:109], v[154:157], v[228:231], v[106:109]
	v_mfma_f32_16x16x32_bf16 v[94:97], v[142:145], v[242:245], v[94:97]
	v_mfma_f32_16x16x32_bf16 v[90:93], v[154:157], v[242:245], v[90:93]
	v_mfma_f32_16x16x32_bf16 v[190:193], v[146:149], v[198:201], v[190:193]
	v_mfma_f32_16x16x32_bf16 v[186:189], v[158:161], v[198:201], v[186:189]
	v_mfma_f32_16x16x32_bf16 v[150:153], v[146:149], v[206:209], v[150:153]
	v_mfma_f32_16x16x32_bf16 v[138:141], v[158:161], v[206:209], v[138:141]
	v_mfma_f32_16x16x32_bf16 v[126:129], v[146:149], v[214:217], v[126:129]
	v_mfma_f32_16x16x32_bf16 v[122:125], v[158:161], v[214:217], v[122:125]
	v_mfma_f32_16x16x32_bf16 v[110:113], v[146:149], v[238:241], v[110:113]
	v_mfma_f32_16x16x32_bf16 v[106:109], v[158:161], v[238:241], v[106:109]
	v_mfma_f32_16x16x32_bf16 v[94:97], v[146:149], v[246:249], v[94:97]
	v_mfma_f32_16x16x32_bf16 v[90:93], v[158:161], v[246:249], v[90:93]
	v_mfma_f32_16x16x32_bf16 v[182:185], v[166:169], v[194:197], v[182:185]
	v_mfma_f32_16x16x32_bf16 v[162:165], v[174:177], v[194:197], v[162:165]
	v_mfma_f32_16x16x32_bf16 v[134:137], v[166:169], v[202:205], v[134:137]
	v_mfma_f32_16x16x32_bf16 v[130:133], v[174:177], v[202:205], v[130:133]
	v_mfma_f32_16x16x32_bf16 v[118:121], v[166:169], v[210:213], v[118:121]
	v_mfma_f32_16x16x32_bf16 v[114:117], v[174:177], v[210:213], v[114:117]
	v_mfma_f32_16x16x32_bf16 v[102:105], v[166:169], v[228:231], v[102:105]
	v_mfma_f32_16x16x32_bf16 v[98:101], v[174:177], v[228:231], v[98:101]
	v_mfma_f32_16x16x32_bf16 v[86:89], v[166:169], v[242:245], v[86:89]
	v_mfma_f32_16x16x32_bf16 v[82:85], v[174:177], v[242:245], v[82:85]
	v_mfma_f32_16x16x32_bf16 v[182:185], v[170:173], v[198:201], v[182:185]
	v_mfma_f32_16x16x32_bf16 v[162:165], v[178:181], v[198:201], v[162:165]
	v_mfma_f32_16x16x32_bf16 v[134:137], v[170:173], v[206:209], v[134:137]
	v_mfma_f32_16x16x32_bf16 v[130:133], v[178:181], v[206:209], v[130:133]
	v_mfma_f32_16x16x32_bf16 v[118:121], v[170:173], v[214:217], v[118:121]
	v_mfma_f32_16x16x32_bf16 v[114:117], v[178:181], v[214:217], v[114:117]
	v_mfma_f32_16x16x32_bf16 v[102:105], v[170:173], v[238:241], v[102:105]
	v_mfma_f32_16x16x32_bf16 v[98:101], v[178:181], v[238:241], v[98:101]
	v_mfma_f32_16x16x32_bf16 v[86:89], v[170:173], v[246:249], v[86:89]
	v_mfma_f32_16x16x32_bf16 v[82:85], v[178:181], v[246:249], v[82:85]
	s_barrier
	ds_read_b128 v[194:197], v221 offset:20480
	ds_read_b128 v[198:201], v221 offset:21504
	ds_read_b128 v[202:205], v221 offset:22528
	ds_read_b128 v[206:209], v221 offset:23552
	ds_read_b128 v[210:213], v221 offset:24576
	ds_read_b128 v[214:217], v221 offset:25600
	ds_read_b128 v[228:231], v221 offset:26624
	ds_read_b128 v[238:241], v221 offset:27648
	ds_read_b128 v[242:245], v221 offset:28672
	ds_read_b128 v[246:249], v221 offset:29696
	s_mov_b32 s74, s22
	s_mov_b32 s75, s23
	s_add_i32 m0, s28, 0x14000
	s_nop 0
	global_load_lds_dwordx4 v220, s[74:75]
	s_add_u32 s74, s22, 0x20000
	s_addc_u32 s75, s23, 0
	s_add_i32 m0, s28, 0x15000
	s_nop 0
	global_load_lds_dwordx4 v220, s[74:75]
	s_add_u32 s74, s22, 0x40000
	s_addc_u32 s75, s23, 0
	s_add_i32 m0, s28, 0x16000
	s_nop 0
	global_load_lds_dwordx4 v220, s[74:75]
	s_add_u32 s74, s22, 0x60000
	s_addc_u32 s75, s23, 0
	s_add_i32 m0, s28, 0x17000
	s_nop 0
	global_load_lds_dwordx4 v220, s[74:75]
	s_add_u32 s74, s10, 0x40000
	s_addc_u32 s75, s11, 0
	s_add_i32 m0, s28, 0x2000
	s_nop 0
	global_load_lds_dwordx4 v0, s[74:75]
	s_waitcnt vmcnt(9)
	s_waitcnt lgkmcnt(0)
	s_barrier
	v_mfma_f32_16x16x32_bf16 v[78:81], v[142:145], v[194:197], v[78:81]
	v_mfma_f32_16x16x32_bf16 v[74:77], v[154:157], v[194:197], v[74:77]
	v_mfma_f32_16x16x32_bf16 v[62:65], v[142:145], v[202:205], v[62:65]
	v_mfma_f32_16x16x32_bf16 v[58:61], v[154:157], v[202:205], v[58:61]
	v_mfma_f32_16x16x32_bf16 v[46:49], v[142:145], v[210:213], v[46:49]
	v_mfma_f32_16x16x32_bf16 v[42:45], v[154:157], v[210:213], v[42:45]
	v_mfma_f32_16x16x32_bf16 v[30:33], v[142:145], v[228:231], v[30:33]
	v_mfma_f32_16x16x32_bf16 v[26:29], v[154:157], v[228:231], v[26:29]
	v_mfma_f32_16x16x32_bf16 v[14:17], v[142:145], v[242:245], v[14:17]
	v_mfma_f32_16x16x32_bf16 v[10:13], v[154:157], v[242:245], v[10:13]
	v_mfma_f32_16x16x32_bf16 v[78:81], v[146:149], v[198:201], v[78:81]
	v_mfma_f32_16x16x32_bf16 v[74:77], v[158:161], v[198:201], v[74:77]
	v_mfma_f32_16x16x32_bf16 v[62:65], v[146:149], v[206:209], v[62:65]
	v_mfma_f32_16x16x32_bf16 v[58:61], v[158:161], v[206:209], v[58:61]
	v_mfma_f32_16x16x32_bf16 v[46:49], v[146:149], v[214:217], v[46:49]
	v_mfma_f32_16x16x32_bf16 v[42:45], v[158:161], v[214:217], v[42:45]
	v_mfma_f32_16x16x32_bf16 v[30:33], v[146:149], v[238:241], v[30:33]
	v_mfma_f32_16x16x32_bf16 v[26:29], v[158:161], v[238:241], v[26:29]
	v_mfma_f32_16x16x32_bf16 v[14:17], v[146:149], v[246:249], v[14:17]
	v_mfma_f32_16x16x32_bf16 v[10:13], v[158:161], v[246:249], v[10:13]
	v_mfma_f32_16x16x32_bf16 v[70:73], v[166:169], v[194:197], v[70:73]
	v_mfma_f32_16x16x32_bf16 v[66:69], v[174:177], v[194:197], v[66:69]
	v_mfma_f32_16x16x32_bf16 v[54:57], v[166:169], v[202:205], v[54:57]
	v_mfma_f32_16x16x32_bf16 v[50:53], v[174:177], v[202:205], v[50:53]
	v_mfma_f32_16x16x32_bf16 v[38:41], v[166:169], v[210:213], v[38:41]
	v_mfma_f32_16x16x32_bf16 v[34:37], v[174:177], v[210:213], v[34:37]
	v_mfma_f32_16x16x32_bf16 v[22:25], v[166:169], v[228:231], v[22:25]
	v_mfma_f32_16x16x32_bf16 v[18:21], v[174:177], v[228:231], v[18:21]
	v_mfma_f32_16x16x32_bf16 v[6:9], v[166:169], v[242:245], v[6:9]
	v_mfma_f32_16x16x32_bf16 v[2:5], v[174:177], v[242:245], v[2:5]
	v_mfma_f32_16x16x32_bf16 v[70:73], v[170:173], v[198:201], v[70:73]
	v_mfma_f32_16x16x32_bf16 v[66:69], v[178:181], v[198:201], v[66:69]
	v_mfma_f32_16x16x32_bf16 v[54:57], v[170:173], v[206:209], v[54:57]
	v_mfma_f32_16x16x32_bf16 v[50:53], v[178:181], v[206:209], v[50:53]
	v_mfma_f32_16x16x32_bf16 v[38:41], v[170:173], v[214:217], v[38:41]
	v_mfma_f32_16x16x32_bf16 v[34:37], v[178:181], v[214:217], v[34:37]
	v_mfma_f32_16x16x32_bf16 v[22:25], v[170:173], v[238:241], v[22:25]
	v_mfma_f32_16x16x32_bf16 v[18:21], v[178:181], v[238:241], v[18:21]
	v_mfma_f32_16x16x32_bf16 v[6:9], v[170:173], v[246:249], v[6:9]
	v_mfma_f32_16x16x32_bf16 v[2:5], v[178:181], v[246:249], v[2:5]
	s_barrier
	v_add_u32_e32 v158, 0x1c000, v223
	v_add_u32_e32 v178, 0x20000, v223
	ds_read_b128 v[142:145], v158
	ds_read_b128 v[146:149], v158 offset:1024
	ds_read_b128 v[154:157], v158 offset:2048
	ds_read_b128 v[158:161], v158 offset:3072
	ds_read_b128 v[166:169], v178
	ds_read_b128 v[170:173], v178 offset:1024
	ds_read_b128 v[174:177], v178 offset:2048
	ds_read_b128 v[178:181], v178 offset:3072
	ds_read_b128 v[194:197], v221 offset:40960
	ds_read_b128 v[198:201], v221 offset:41984
	ds_read_b128 v[202:205], v221 offset:43008
	ds_read_b128 v[206:209], v221 offset:44032
	ds_read_b128 v[210:213], v221 offset:45056
	ds_read_b128 v[214:217], v221 offset:46080
	ds_read_b128 v[228:231], v221 offset:47104
	ds_read_b128 v[238:241], v221 offset:48128
	ds_read_b128 v[242:245], v221 offset:49152
	ds_read_b128 v[246:249], v221 offset:50176
	s_add_u32 s74, s10, 0x60000
	s_addc_u32 s75, s11, 0
	s_add_i32 m0, s28, 0x3000
	s_nop 0
	global_load_lds_dwordx4 v0, s[74:75]
	s_add_u32 s74, s10, 0x80000
	s_addc_u32 s75, s11, 0
	s_add_i32 m0, s28, 0x4000
	s_nop 0
	global_load_lds_dwordx4 v0, s[74:75]
	s_add_u32 s74, s10, 0xa0000
	s_addc_u32 s75, s11, 0
	s_add_i32 m0, s28, 0x5000
	s_nop 0
	global_load_lds_dwordx4 v0, s[74:75]
	s_add_u32 s74, s10, 0xc0000
	s_addc_u32 s75, s11, 0
	s_add_i32 m0, s28, 0x6000
	s_nop 0
	global_load_lds_dwordx4 v0, s[74:75]
	s_waitcnt vmcnt(9)
	s_waitcnt lgkmcnt(0)
	s_barrier
	v_mfma_f32_16x16x32_bf16 v[190:193], v[142:145], v[194:197], v[190:193]
	v_mfma_f32_16x16x32_bf16 v[186:189], v[154:157], v[194:197], v[186:189]
	v_mfma_f32_16x16x32_bf16 v[150:153], v[142:145], v[202:205], v[150:153]
	v_mfma_f32_16x16x32_bf16 v[138:141], v[154:157], v[202:205], v[138:141]
	v_mfma_f32_16x16x32_bf16 v[126:129], v[142:145], v[210:213], v[126:129]
	v_mfma_f32_16x16x32_bf16 v[122:125], v[154:157], v[210:213], v[122:125]
	v_mfma_f32_16x16x32_bf16 v[110:113], v[142:145], v[228:231], v[110:113]
	v_mfma_f32_16x16x32_bf16 v[106:109], v[154:157], v[228:231], v[106:109]
	v_mfma_f32_16x16x32_bf16 v[94:97], v[142:145], v[242:245], v[94:97]
	v_mfma_f32_16x16x32_bf16 v[90:93], v[154:157], v[242:245], v[90:93]
	v_mfma_f32_16x16x32_bf16 v[190:193], v[146:149], v[198:201], v[190:193]
	v_mfma_f32_16x16x32_bf16 v[186:189], v[158:161], v[198:201], v[186:189]
	v_mfma_f32_16x16x32_bf16 v[150:153], v[146:149], v[206:209], v[150:153]
	v_mfma_f32_16x16x32_bf16 v[138:141], v[158:161], v[206:209], v[138:141]
	v_mfma_f32_16x16x32_bf16 v[126:129], v[146:149], v[214:217], v[126:129]
	v_mfma_f32_16x16x32_bf16 v[122:125], v[158:161], v[214:217], v[122:125]
	v_mfma_f32_16x16x32_bf16 v[110:113], v[146:149], v[238:241], v[110:113]
	v_mfma_f32_16x16x32_bf16 v[106:109], v[158:161], v[238:241], v[106:109]
	v_mfma_f32_16x16x32_bf16 v[94:97], v[146:149], v[246:249], v[94:97]
	v_mfma_f32_16x16x32_bf16 v[90:93], v[158:161], v[246:249], v[90:93]
	v_mfma_f32_16x16x32_bf16 v[182:185], v[166:169], v[194:197], v[182:185]
	v_mfma_f32_16x16x32_bf16 v[162:165], v[174:177], v[194:197], v[162:165]
	v_mfma_f32_16x16x32_bf16 v[134:137], v[166:169], v[202:205], v[134:137]
	v_mfma_f32_16x16x32_bf16 v[130:133], v[174:177], v[202:205], v[130:133]
	v_mfma_f32_16x16x32_bf16 v[118:121], v[166:169], v[210:213], v[118:121]
	v_mfma_f32_16x16x32_bf16 v[114:117], v[174:177], v[210:213], v[114:117]
	v_mfma_f32_16x16x32_bf16 v[102:105], v[166:169], v[228:231], v[102:105]
	v_mfma_f32_16x16x32_bf16 v[98:101], v[174:177], v[228:231], v[98:101]
	v_mfma_f32_16x16x32_bf16 v[86:89], v[166:169], v[242:245], v[86:89]
	v_mfma_f32_16x16x32_bf16 v[82:85], v[174:177], v[242:245], v[82:85]
	v_mfma_f32_16x16x32_bf16 v[182:185], v[170:173], v[198:201], v[182:185]
	v_mfma_f32_16x16x32_bf16 v[162:165], v[178:181], v[198:201], v[162:165]
	v_mfma_f32_16x16x32_bf16 v[134:137], v[170:173], v[206:209], v[134:137]
	v_mfma_f32_16x16x32_bf16 v[130:133], v[178:181], v[206:209], v[130:133]
	v_mfma_f32_16x16x32_bf16 v[118:121], v[170:173], v[214:217], v[118:121]
	v_mfma_f32_16x16x32_bf16 v[114:117], v[178:181], v[214:217], v[114:117]
	v_mfma_f32_16x16x32_bf16 v[102:105], v[170:173], v[238:241], v[102:105]
	v_mfma_f32_16x16x32_bf16 v[98:101], v[178:181], v[238:241], v[98:101]
	v_mfma_f32_16x16x32_bf16 v[86:89], v[170:173], v[246:249], v[86:89]
	v_mfma_f32_16x16x32_bf16 v[82:85], v[178:181], v[246:249], v[82:85]
	s_barrier
	ds_read_b128 v[194:197], v221 offset:61440
	ds_read_b128 v[198:201], v221 offset:62464
	ds_read_b128 v[202:205], v221 offset:63488
	ds_read_b128 v[206:209], v221 offset:64512
	ds_read_b128 v[210:213], v222 offset:4096
	ds_read_b128 v[214:217], v222 offset:5120
	ds_read_b128 v[228:231], v222 offset:6144
	ds_read_b128 v[238:241], v222 offset:7168
	ds_read_b128 v[242:245], v222 offset:8192
	ds_read_b128 v[246:249], v222 offset:9216
	s_add_u32 s16, s10, 0x40080
	s_addc_u32 s17, s11, 0
	s_add_u32 s74, s22, 0x80
	s_addc_u32 s75, s23, 0
	s_add_i32 m0, s28, 0x1c000
	s_nop 0
	global_load_lds_dwordx4 v220, s[74:75]
	s_add_u32 s74, s22, 0x20080
	s_addc_u32 s75, s23, 0
	s_add_i32 m0, s28, 0x1d000
	s_nop 0
	global_load_lds_dwordx4 v220, s[74:75]
	s_add_u32 s74, s22, 0x40080
	s_addc_u32 s75, s23, 0
	s_add_i32 m0, s28, 0x1e000
	s_nop 0
	global_load_lds_dwordx4 v220, s[74:75]
	s_add_u32 s74, s22, 0x60080
	s_addc_u32 s75, s23, 0
	s_add_i32 m0, s28, 0x1f000
	s_nop 0
	global_load_lds_dwordx4 v220, s[74:75]
	s_add_u32 s74, s10, 0x40080
	s_addc_u32 s75, s11, 0
	s_add_i32 m0, s28, 0xc000
	s_nop 0
	global_load_lds_dwordx4 v0, s[74:75]
	s_waitcnt vmcnt(9)
	s_waitcnt lgkmcnt(0)
	s_barrier
	v_mfma_f32_16x16x32_bf16 v[78:81], v[142:145], v[194:197], v[78:81]
	v_mfma_f32_16x16x32_bf16 v[74:77], v[154:157], v[194:197], v[74:77]
	v_mfma_f32_16x16x32_bf16 v[62:65], v[142:145], v[202:205], v[62:65]
	v_mfma_f32_16x16x32_bf16 v[58:61], v[154:157], v[202:205], v[58:61]
	v_mfma_f32_16x16x32_bf16 v[46:49], v[142:145], v[210:213], v[46:49]
	v_mfma_f32_16x16x32_bf16 v[42:45], v[154:157], v[210:213], v[42:45]
	v_mfma_f32_16x16x32_bf16 v[30:33], v[142:145], v[228:231], v[30:33]
	v_mfma_f32_16x16x32_bf16 v[26:29], v[154:157], v[228:231], v[26:29]
	v_mfma_f32_16x16x32_bf16 v[14:17], v[142:145], v[242:245], v[14:17]
	v_mfma_f32_16x16x32_bf16 v[10:13], v[154:157], v[242:245], v[10:13]
	v_mfma_f32_16x16x32_bf16 v[78:81], v[146:149], v[198:201], v[78:81]
	v_mfma_f32_16x16x32_bf16 v[74:77], v[158:161], v[198:201], v[74:77]
	v_mfma_f32_16x16x32_bf16 v[62:65], v[146:149], v[206:209], v[62:65]
	v_mfma_f32_16x16x32_bf16 v[58:61], v[158:161], v[206:209], v[58:61]
	v_mfma_f32_16x16x32_bf16 v[46:49], v[146:149], v[214:217], v[46:49]
	v_mfma_f32_16x16x32_bf16 v[42:45], v[158:161], v[214:217], v[42:45]
	v_mfma_f32_16x16x32_bf16 v[30:33], v[146:149], v[238:241], v[30:33]
	v_mfma_f32_16x16x32_bf16 v[26:29], v[158:161], v[238:241], v[26:29]
	v_mfma_f32_16x16x32_bf16 v[14:17], v[146:149], v[246:249], v[14:17]
	v_mfma_f32_16x16x32_bf16 v[10:13], v[158:161], v[246:249], v[10:13]
	v_mfma_f32_16x16x32_bf16 v[70:73], v[166:169], v[194:197], v[70:73]
	v_mfma_f32_16x16x32_bf16 v[66:69], v[174:177], v[194:197], v[66:69]
	v_mfma_f32_16x16x32_bf16 v[54:57], v[166:169], v[202:205], v[54:57]
	v_mfma_f32_16x16x32_bf16 v[50:53], v[174:177], v[202:205], v[50:53]
	v_mfma_f32_16x16x32_bf16 v[38:41], v[166:169], v[210:213], v[38:41]
	v_mfma_f32_16x16x32_bf16 v[34:37], v[174:177], v[210:213], v[34:37]
	v_mfma_f32_16x16x32_bf16 v[22:25], v[166:169], v[228:231], v[22:25]
	v_mfma_f32_16x16x32_bf16 v[18:21], v[174:177], v[228:231], v[18:21]
	v_mfma_f32_16x16x32_bf16 v[6:9], v[166:169], v[242:245], v[6:9]
	v_mfma_f32_16x16x32_bf16 v[2:5], v[174:177], v[242:245], v[2:5]
	v_mfma_f32_16x16x32_bf16 v[70:73], v[170:173], v[198:201], v[70:73]
	v_mfma_f32_16x16x32_bf16 v[66:69], v[178:181], v[198:201], v[66:69]
	v_mfma_f32_16x16x32_bf16 v[54:57], v[170:173], v[206:209], v[54:57]
	v_mfma_f32_16x16x32_bf16 v[50:53], v[178:181], v[206:209], v[50:53]
	v_mfma_f32_16x16x32_bf16 v[38:41], v[170:173], v[214:217], v[38:41]
	v_mfma_f32_16x16x32_bf16 v[34:37], v[178:181], v[214:217], v[34:37]
	v_mfma_f32_16x16x32_bf16 v[22:25], v[170:173], v[238:241], v[22:25]
	v_mfma_f32_16x16x32_bf16 v[18:21], v[178:181], v[238:241], v[18:21]
	v_mfma_f32_16x16x32_bf16 v[6:9], v[170:173], v[246:249], v[6:9]
	v_mfma_f32_16x16x32_bf16 v[2:5], v[178:181], v[246:249], v[2:5]
	s_barrier
	s_add_i32 s97, s97, 2
	s_add_u32 s6, s6, 0x100
	s_addc_u32 s7, s7, 0
	s_add_u32 s84, s84, 0x100
	s_addc_u32 s92, s92, 0
	s_cmp_gt_u32 s97, 29
	s_cbranch_scc0 .LBB0_1546
	s_and_b64 vcc, exec, s[12:13]
	s_cbranch_vccz .LBB0_1549
	s_barrier

.LBB0_1789:
	v_add_u32_e32 v174, 0x14000, v244
	v_add_u32_e32 v190, 0x18000, v244
	ds_read_b128 v[162:165], v174
	ds_read_b128 v[166:169], v174 offset:1024
	ds_read_b128 v[170:173], v174 offset:2048
	ds_read_b128 v[174:177], v174 offset:3072
	ds_read_b128 v[178:181], v190
	ds_read_b128 v[182:185], v190 offset:1024
	ds_read_b128 v[186:189], v190 offset:2048
	ds_read_b128 v[190:193], v190 offset:3072
	s_add_u32 s16, s14, 0xffe52080
	s_addc_u32 s17, s15, -1
	s_cmpk_eq_i32 s66, 0x52
	s_cselect_b32 s16, s6, s16
	s_cselect_b32 s17, s7, s17
	s_cselect_b32 s20, s12, s62
	s_cselect_b32 s21, s13, s64
	s_add_u32 s18, s16, 0x80
	s_addc_u32 s19, s17, 0
	ds_read_b128 v[194:197], v242
	ds_read_b128 v[198:201], v242 offset:1024
	ds_read_b128 v[202:205], v242 offset:2048
	ds_read_b128 v[206:209], v242 offset:3072
	ds_read_b128 v[210:213], v242 offset:4096
	ds_read_b128 v[214:217], v242 offset:5120
	ds_read_b128 v[218:221], v242 offset:6144
	ds_read_b128 v[228:231], v242 offset:7168
	ds_read_b128 v[236:239], v242 offset:8192
	ds_read_b128 v[246:249], v242 offset:9216
	s_add_u32 s74, s16, 0xfffaa000
	s_addc_u32 s75, s17, -1
	s_add_i32 m0, s26, 0xfffff000
	s_nop 0
	global_load_lds_dwordx4 v0, s[74:75]
	s_mov_b32 s74, s16
	s_mov_b32 s75, s17
	s_mov_b32 m0, s26
	s_nop 0
	global_load_lds_dwordx4 v0, s[74:75]
	s_add_u32 s74, s14, 0xac000
	s_addc_u32 s75, s15, 0
	s_add_i32 m0, s26, 0x11000
	s_nop 0
	global_load_lds_dwordx4 v0, s[74:75]
	s_add_u32 s74, s14, 0x102000
	s_addc_u32 s75, s15, 0
	s_add_i32 m0, s26, 0x12000
	s_nop 0
	global_load_lds_dwordx4 v0, s[74:75]
	s_add_u32 s74, s14, 0x56000
	s_addc_u32 s75, s15, 0
	s_add_i32 m0, s26, 0x10000
	s_nop 0
	global_load_lds_dwordx4 v0, s[74:75]
	s_waitcnt vmcnt(9)
	s_waitcnt lgkmcnt(0)
	s_barrier
	v_mfma_f32_16x16x32_bf16 v[158:161], v[162:165], v[194:197], v[158:161]
	v_mfma_f32_16x16x32_bf16 v[154:157], v[170:173], v[194:197], v[154:157]
	v_mfma_f32_16x16x32_bf16 v[142:145], v[162:165], v[202:205], v[142:145]
	v_mfma_f32_16x16x32_bf16 v[138:141], v[170:173], v[202:205], v[138:141]
	v_mfma_f32_16x16x32_bf16 v[126:129], v[162:165], v[210:213], v[126:129]
	v_mfma_f32_16x16x32_bf16 v[122:125], v[170:173], v[210:213], v[122:125]
	v_mfma_f32_16x16x32_bf16 v[110:113], v[162:165], v[218:221], v[110:113]
	v_mfma_f32_16x16x32_bf16 v[106:109], v[170:173], v[218:221], v[106:109]
	v_mfma_f32_16x16x32_bf16 v[94:97], v[162:165], v[236:239], v[94:97]
	v_mfma_f32_16x16x32_bf16 v[90:93], v[170:173], v[236:239], v[90:93]
	v_mfma_f32_16x16x32_bf16 v[158:161], v[166:169], v[198:201], v[158:161]
	v_mfma_f32_16x16x32_bf16 v[154:157], v[174:177], v[198:201], v[154:157]
	v_mfma_f32_16x16x32_bf16 v[142:145], v[166:169], v[206:209], v[142:145]
	v_mfma_f32_16x16x32_bf16 v[138:141], v[174:177], v[206:209], v[138:141]
	v_mfma_f32_16x16x32_bf16 v[126:129], v[166:169], v[214:217], v[126:129]
	v_mfma_f32_16x16x32_bf16 v[122:125], v[174:177], v[214:217], v[122:125]
	v_mfma_f32_16x16x32_bf16 v[110:113], v[166:169], v[228:231], v[110:113]
	v_mfma_f32_16x16x32_bf16 v[106:109], v[174:177], v[228:231], v[106:109]
	v_mfma_f32_16x16x32_bf16 v[94:97], v[166:169], v[246:249], v[94:97]
	v_mfma_f32_16x16x32_bf16 v[90:93], v[174:177], v[246:249], v[90:93]
	v_mfma_f32_16x16x32_bf16 v[150:153], v[178:181], v[194:197], v[150:153]
	v_mfma_f32_16x16x32_bf16 v[146:149], v[186:189], v[194:197], v[146:149]
	v_mfma_f32_16x16x32_bf16 v[134:137], v[178:181], v[202:205], v[134:137]
	v_mfma_f32_16x16x32_bf16 v[130:133], v[186:189], v[202:205], v[130:133]
	v_mfma_f32_16x16x32_bf16 v[118:121], v[178:181], v[210:213], v[118:121]
	v_mfma_f32_16x16x32_bf16 v[114:117], v[186:189], v[210:213], v[114:117]
	v_mfma_f32_16x16x32_bf16 v[102:105], v[178:181], v[218:221], v[102:105]
	v_mfma_f32_16x16x32_bf16 v[98:101], v[186:189], v[218:221], v[98:101]
	v_mfma_f32_16x16x32_bf16 v[86:89], v[178:181], v[236:239], v[86:89]
	v_mfma_f32_16x16x32_bf16 v[82:85], v[186:189], v[236:239], v[82:85]
	v_mfma_f32_16x16x32_bf16 v[150:153], v[182:185], v[198:201], v[150:153]
	v_mfma_f32_16x16x32_bf16 v[146:149], v[190:193], v[198:201], v[146:149]
	v_mfma_f32_16x16x32_bf16 v[134:137], v[182:185], v[206:209], v[134:137]
	v_mfma_f32_16x16x32_bf16 v[130:133], v[190:193], v[206:209], v[130:133]
	v_mfma_f32_16x16x32_bf16 v[118:121], v[182:185], v[214:217], v[118:121]
	v_mfma_f32_16x16x32_bf16 v[114:117], v[190:193], v[214:217], v[114:117]
	v_mfma_f32_16x16x32_bf16 v[102:105], v[182:185], v[228:231], v[102:105]
	v_mfma_f32_16x16x32_bf16 v[98:101], v[190:193], v[228:231], v[98:101]
	v_mfma_f32_16x16x32_bf16 v[86:89], v[182:185], v[246:249], v[86:89]
	v_mfma_f32_16x16x32_bf16 v[82:85], v[190:193], v[246:249], v[82:85]
	s_barrier
	ds_read_b128 v[194:197], v242 offset:20480
	ds_read_b128 v[198:201], v242 offset:21504
	ds_read_b128 v[202:205], v242 offset:22528
	ds_read_b128 v[206:209], v242 offset:23552
	ds_read_b128 v[210:213], v242 offset:24576
	ds_read_b128 v[214:217], v242 offset:25600
	ds_read_b128 v[218:221], v242 offset:26624
	ds_read_b128 v[228:231], v242 offset:27648
	ds_read_b128 v[236:239], v242 offset:28672
	ds_read_b128 v[246:249], v242 offset:29696
	s_add_u32 s74, s20, 0x102000
	s_addc_u32 s75, s21, 0
	s_add_i32 m0, s26, 0x17000
	s_nop 0
	global_load_lds_dwordx4 v241, s[74:75]
	s_add_u32 s74, s20, 0x158000
	s_addc_u32 s75, s21, 0
	s_add_i32 m0, s26, 0x18000
	s_nop 0
	global_load_lds_dwordx4 v241, s[74:75]
	s_add_u32 s74, s20, 0x1ae000
	s_addc_u32 s75, s21, 0
	s_add_i32 m0, s26, 0x19000
	s_nop 0
	global_load_lds_dwordx4 v241, s[74:75]
	s_add_u32 s74, s20, 0x204000
	s_addc_u32 s75, s21, 0
	s_add_i32 m0, s26, 0x1a000
	s_nop 0
	global_load_lds_dwordx4 v241, s[74:75]
	s_waitcnt vmcnt(9)
	s_waitcnt lgkmcnt(0)
	s_barrier
	v_mfma_f32_16x16x32_bf16 v[78:81], v[162:165], v[194:197], v[78:81]
	v_mfma_f32_16x16x32_bf16 v[74:77], v[170:173], v[194:197], v[74:77]
	v_mfma_f32_16x16x32_bf16 v[62:65], v[162:165], v[202:205], v[62:65]
	v_mfma_f32_16x16x32_bf16 v[58:61], v[170:173], v[202:205], v[58:61]
	v_mfma_f32_16x16x32_bf16 v[46:49], v[162:165], v[210:213], v[46:49]
	v_mfma_f32_16x16x32_bf16 v[42:45], v[170:173], v[210:213], v[42:45]
	v_mfma_f32_16x16x32_bf16 v[30:33], v[162:165], v[218:221], v[30:33]
	v_mfma_f32_16x16x32_bf16 v[26:29], v[170:173], v[218:221], v[26:29]
	v_mfma_f32_16x16x32_bf16 v[14:17], v[162:165], v[236:239], v[14:17]
	v_mfma_f32_16x16x32_bf16 v[10:13], v[170:173], v[236:239], v[10:13]
	v_mfma_f32_16x16x32_bf16 v[78:81], v[166:169], v[198:201], v[78:81]
	v_mfma_f32_16x16x32_bf16 v[74:77], v[174:177], v[198:201], v[74:77]
	v_mfma_f32_16x16x32_bf16 v[62:65], v[166:169], v[206:209], v[62:65]
	v_mfma_f32_16x16x32_bf16 v[58:61], v[174:177], v[206:209], v[58:61]
	v_mfma_f32_16x16x32_bf16 v[46:49], v[166:169], v[214:217], v[46:49]
	v_mfma_f32_16x16x32_bf16 v[42:45], v[174:177], v[214:217], v[42:45]
	v_mfma_f32_16x16x32_bf16 v[30:33], v[166:169], v[228:231], v[30:33]
	v_mfma_f32_16x16x32_bf16 v[26:29], v[174:177], v[228:231], v[26:29]
	v_mfma_f32_16x16x32_bf16 v[14:17], v[166:169], v[246:249], v[14:17]
	v_mfma_f32_16x16x32_bf16 v[10:13], v[174:177], v[246:249], v[10:13]
	v_mfma_f32_16x16x32_bf16 v[70:73], v[178:181], v[194:197], v[70:73]
	v_mfma_f32_16x16x32_bf16 v[66:69], v[186:189], v[194:197], v[66:69]
	v_mfma_f32_16x16x32_bf16 v[54:57], v[178:181], v[202:205], v[54:57]
	v_mfma_f32_16x16x32_bf16 v[50:53], v[186:189], v[202:205], v[50:53]
	v_mfma_f32_16x16x32_bf16 v[38:41], v[178:181], v[210:213], v[38:41]
	v_mfma_f32_16x16x32_bf16 v[34:37], v[186:189], v[210:213], v[34:37]
	v_mfma_f32_16x16x32_bf16 v[22:25], v[178:181], v[218:221], v[22:25]
	v_mfma_f32_16x16x32_bf16 v[18:21], v[186:189], v[218:221], v[18:21]
	v_mfma_f32_16x16x32_bf16 v[6:9], v[178:181], v[236:239], v[6:9]
	v_mfma_f32_16x16x32_bf16 v[2:5], v[186:189], v[236:239], v[2:5]
	v_mfma_f32_16x16x32_bf16 v[70:73], v[182:185], v[198:201], v[70:73]
	v_mfma_f32_16x16x32_bf16 v[66:69], v[190:193], v[198:201], v[66:69]
	v_mfma_f32_16x16x32_bf16 v[54:57], v[182:185], v[206:209], v[54:57]
	v_mfma_f32_16x16x32_bf16 v[50:53], v[190:193], v[206:209], v[50:53]
	v_mfma_f32_16x16x32_bf16 v[38:41], v[182:185], v[214:217], v[38:41]
	v_mfma_f32_16x16x32_bf16 v[34:37], v[190:193], v[214:217], v[34:37]
	v_mfma_f32_16x16x32_bf16 v[22:25], v[182:185], v[228:231], v[22:25]
	v_mfma_f32_16x16x32_bf16 v[18:21], v[190:193], v[228:231], v[18:21]
	v_mfma_f32_16x16x32_bf16 v[6:9], v[182:185], v[246:249], v[6:9]
	v_mfma_f32_16x16x32_bf16 v[2:5], v[190:193], v[246:249], v[2:5]
	s_barrier
	v_add_u32_e32 v174, 0x1c000, v244
	v_add_u32_e32 v190, 0x20000, v244
	ds_read_b128 v[162:165], v174
	ds_read_b128 v[166:169], v174 offset:1024
	ds_read_b128 v[170:173], v174 offset:2048
	ds_read_b128 v[174:177], v174 offset:3072
	ds_read_b128 v[178:181], v190
	ds_read_b128 v[182:185], v190 offset:1024
	ds_read_b128 v[186:189], v190 offset:2048
	ds_read_b128 v[190:193], v190 offset:3072
	ds_read_b128 v[194:197], v242 offset:40960
	ds_read_b128 v[198:201], v242 offset:41984
	ds_read_b128 v[202:205], v242 offset:43008
	ds_read_b128 v[206:209], v242 offset:44032
	ds_read_b128 v[210:213], v242 offset:45056
	ds_read_b128 v[214:217], v242 offset:46080
	ds_read_b128 v[218:221], v242 offset:47104
	ds_read_b128 v[228:231], v242 offset:48128
	ds_read_b128 v[236:239], v242 offset:49152
	ds_read_b128 v[246:249], v242 offset:50176
	s_add_u32 s74, s16, 0xfffaa080
	s_addc_u32 s75, s17, -1
	s_add_i32 m0, s26, 0x9000
	s_nop 0
	global_load_lds_dwordx4 v0, s[74:75]
	s_add_u32 s74, s16, 0x80
	s_addc_u32 s75, s17, 0
	s_add_i32 m0, s26, 0xa000
	s_nop 0
	global_load_lds_dwordx4 v0, s[74:75]
	s_add_u32 s74, s16, 0x25a000
	s_addc_u32 s75, s17, 0
	s_add_i32 m0, s26, 0x7000
	s_nop 0
	global_load_lds_dwordx4 v0, s[74:75]
	s_add_u32 s74, s16, 0x2b0000
	s_addc_u32 s75, s17, 0
	s_add_i32 m0, s26, 0x8000
	s_nop 0
	global_load_lds_dwordx4 v0, s[74:75]
	s_add_u32 s74, s16, 0x204000
	s_addc_u32 s75, s17, 0
	s_add_i32 m0, s26, 0x6000
	s_nop 0
	global_load_lds_dwordx4 v0, s[74:75]
	s_waitcnt vmcnt(9)
	s_waitcnt lgkmcnt(0)
	s_barrier
	v_mfma_f32_16x16x32_bf16 v[158:161], v[162:165], v[194:197], v[158:161]
	v_mfma_f32_16x16x32_bf16 v[154:157], v[170:173], v[194:197], v[154:157]
	v_mfma_f32_16x16x32_bf16 v[142:145], v[162:165], v[202:205], v[142:145]
	v_mfma_f32_16x16x32_bf16 v[138:141], v[170:173], v[202:205], v[138:141]
	v_mfma_f32_16x16x32_bf16 v[126:129], v[162:165], v[210:213], v[126:129]
	v_mfma_f32_16x16x32_bf16 v[122:125], v[170:173], v[210:213], v[122:125]
	v_mfma_f32_16x16x32_bf16 v[110:113], v[162:165], v[218:221], v[110:113]
	v_mfma_f32_16x16x32_bf16 v[106:109], v[170:173], v[218:221], v[106:109]
	v_mfma_f32_16x16x32_bf16 v[94:97], v[162:165], v[236:239], v[94:97]
	v_mfma_f32_16x16x32_bf16 v[90:93], v[170:173], v[236:239], v[90:93]
	v_mfma_f32_16x16x32_bf16 v[158:161], v[166:169], v[198:201], v[158:161]
	v_mfma_f32_16x16x32_bf16 v[154:157], v[174:177], v[198:201], v[154:157]
	v_mfma_f32_16x16x32_bf16 v[142:145], v[166:169], v[206:209], v[142:145]
	v_mfma_f32_16x16x32_bf16 v[138:141], v[174:177], v[206:209], v[138:141]
	v_mfma_f32_16x16x32_bf16 v[126:129], v[166:169], v[214:217], v[126:129]
	v_mfma_f32_16x16x32_bf16 v[122:125], v[174:177], v[214:217], v[122:125]
	v_mfma_f32_16x16x32_bf16 v[110:113], v[166:169], v[228:231], v[110:113]
	v_mfma_f32_16x16x32_bf16 v[106:109], v[174:177], v[228:231], v[106:109]
	v_mfma_f32_16x16x32_bf16 v[94:97], v[166:169], v[246:249], v[94:97]
	v_mfma_f32_16x16x32_bf16 v[90:93], v[174:177], v[246:249], v[90:93]
	v_mfma_f32_16x16x32_bf16 v[150:153], v[178:181], v[194:197], v[150:153]
	v_mfma_f32_16x16x32_bf16 v[146:149], v[186:189], v[194:197], v[146:149]
	v_mfma_f32_16x16x32_bf16 v[134:137], v[178:181], v[202:205], v[134:137]
	v_mfma_f32_16x16x32_bf16 v[130:133], v[186:189], v[202:205], v[130:133]
	v_mfma_f32_16x16x32_bf16 v[118:121], v[178:181], v[210:213], v[118:121]
	v_mfma_f32_16x16x32_bf16 v[114:117], v[186:189], v[210:213], v[114:117]
	v_mfma_f32_16x16x32_bf16 v[102:105], v[178:181], v[218:221], v[102:105]
	v_mfma_f32_16x16x32_bf16 v[98:101], v[186:189], v[218:221], v[98:101]
	v_mfma_f32_16x16x32_bf16 v[86:89], v[178:181], v[236:239], v[86:89]
	v_mfma_f32_16x16x32_bf16 v[82:85], v[186:189], v[236:239], v[82:85]
	v_mfma_f32_16x16x32_bf16 v[150:153], v[182:185], v[198:201], v[150:153]
	v_mfma_f32_16x16x32_bf16 v[146:149], v[190:193], v[198:201], v[146:149]
	v_mfma_f32_16x16x32_bf16 v[134:137], v[182:185], v[206:209], v[134:137]
	v_mfma_f32_16x16x32_bf16 v[130:133], v[190:193], v[206:209], v[130:133]
	v_mfma_f32_16x16x32_bf16 v[118:121], v[182:185], v[214:217], v[118:121]
	v_mfma_f32_16x16x32_bf16 v[114:117], v[190:193], v[214:217], v[114:117]
	v_mfma_f32_16x16x32_bf16 v[102:105], v[182:185], v[228:231], v[102:105]
	v_mfma_f32_16x16x32_bf16 v[98:101], v[190:193], v[228:231], v[98:101]
	v_mfma_f32_16x16x32_bf16 v[86:89], v[182:185], v[246:249], v[86:89]
	v_mfma_f32_16x16x32_bf16 v[82:85], v[190:193], v[246:249], v[82:85]
	s_barrier
	ds_read_b128 v[194:197], v242 offset:61440
	ds_read_b128 v[198:201], v242 offset:62464
	ds_read_b128 v[202:205], v242 offset:63488
	ds_read_b128 v[206:209], v242 offset:64512
	ds_read_b128 v[210:213], v243 offset:4096
	ds_read_b128 v[214:217], v243 offset:5120
	ds_read_b128 v[218:221], v243 offset:6144
	ds_read_b128 v[228:231], v243 offset:7168
	ds_read_b128 v[236:239], v243 offset:8192
	ds_read_b128 v[246:249], v243 offset:9216
	s_add_u32 s74, s20, 0x102080
	s_addc_u32 s75, s21, 0
	s_add_i32 m0, s26, 0x1f000
	s_nop 0
	global_load_lds_dwordx4 v241, s[74:75]
	s_add_u32 s74, s20, 0x158080
	s_addc_u32 s75, s21, 0
	s_add_i32 m0, s26, 0x20000
	s_nop 0
	global_load_lds_dwordx4 v241, s[74:75]
	s_add_u32 s74, s20, 0x1ae080
	s_addc_u32 s75, s21, 0
	s_add_i32 m0, s26, 0x21000
	s_nop 0
	global_load_lds_dwordx4 v241, s[74:75]
	s_add_u32 s74, s20, 0x204080
	s_addc_u32 s75, s21, 0
	s_add_i32 m0, s26, 0x22000
	s_nop 0
	global_load_lds_dwordx4 v241, s[74:75]
	s_waitcnt vmcnt(9)
	s_waitcnt lgkmcnt(0)
	s_barrier
	v_mfma_f32_16x16x32_bf16 v[78:81], v[162:165], v[194:197], v[78:81]
	v_mfma_f32_16x16x32_bf16 v[74:77], v[170:173], v[194:197], v[74:77]
	v_mfma_f32_16x16x32_bf16 v[62:65], v[162:165], v[202:205], v[62:65]
	v_mfma_f32_16x16x32_bf16 v[58:61], v[170:173], v[202:205], v[58:61]
	v_mfma_f32_16x16x32_bf16 v[46:49], v[162:165], v[210:213], v[46:49]
	v_mfma_f32_16x16x32_bf16 v[42:45], v[170:173], v[210:213], v[42:45]
	v_mfma_f32_16x16x32_bf16 v[30:33], v[162:165], v[218:221], v[30:33]
	v_mfma_f32_16x16x32_bf16 v[26:29], v[170:173], v[218:221], v[26:29]
	v_mfma_f32_16x16x32_bf16 v[14:17], v[162:165], v[236:239], v[14:17]
	v_mfma_f32_16x16x32_bf16 v[10:13], v[170:173], v[236:239], v[10:13]
	v_mfma_f32_16x16x32_bf16 v[78:81], v[166:169], v[198:201], v[78:81]
	v_mfma_f32_16x16x32_bf16 v[74:77], v[174:177], v[198:201], v[74:77]
	v_mfma_f32_16x16x32_bf16 v[62:65], v[166:169], v[206:209], v[62:65]
	v_mfma_f32_16x16x32_bf16 v[58:61], v[174:177], v[206:209], v[58:61]
	v_mfma_f32_16x16x32_bf16 v[46:49], v[166:169], v[214:217], v[46:49]
	v_mfma_f32_16x16x32_bf16 v[42:45], v[174:177], v[214:217], v[42:45]
	v_mfma_f32_16x16x32_bf16 v[30:33], v[166:169], v[228:231], v[30:33]
	v_mfma_f32_16x16x32_bf16 v[26:29], v[174:177], v[228:231], v[26:29]
	v_mfma_f32_16x16x32_bf16 v[14:17], v[166:169], v[246:249], v[14:17]
	v_mfma_f32_16x16x32_bf16 v[10:13], v[174:177], v[246:249], v[10:13]
	v_mfma_f32_16x16x32_bf16 v[70:73], v[178:181], v[194:197], v[70:73]
	v_mfma_f32_16x16x32_bf16 v[66:69], v[186:189], v[194:197], v[66:69]
	v_mfma_f32_16x16x32_bf16 v[54:57], v[178:181], v[202:205], v[54:57]
	v_mfma_f32_16x16x32_bf16 v[50:53], v[186:189], v[202:205], v[50:53]
	v_mfma_f32_16x16x32_bf16 v[38:41], v[178:181], v[210:213], v[38:41]
	v_mfma_f32_16x16x32_bf16 v[34:37], v[186:189], v[210:213], v[34:37]
	v_mfma_f32_16x16x32_bf16 v[22:25], v[178:181], v[218:221], v[22:25]
	v_mfma_f32_16x16x32_bf16 v[18:21], v[186:189], v[218:221], v[18:21]
	v_mfma_f32_16x16x32_bf16 v[6:9], v[178:181], v[236:239], v[6:9]
	v_mfma_f32_16x16x32_bf16 v[2:5], v[186:189], v[236:239], v[2:5]
	v_mfma_f32_16x16x32_bf16 v[70:73], v[182:185], v[198:201], v[70:73]
	v_mfma_f32_16x16x32_bf16 v[66:69], v[190:193], v[198:201], v[66:69]
	v_mfma_f32_16x16x32_bf16 v[54:57], v[182:185], v[206:209], v[54:57]
	v_mfma_f32_16x16x32_bf16 v[50:53], v[190:193], v[206:209], v[50:53]
	v_mfma_f32_16x16x32_bf16 v[38:41], v[182:185], v[214:217], v[38:41]
	v_mfma_f32_16x16x32_bf16 v[34:37], v[190:193], v[214:217], v[34:37]
	v_mfma_f32_16x16x32_bf16 v[22:25], v[182:185], v[228:231], v[22:25]
	v_mfma_f32_16x16x32_bf16 v[18:21], v[190:193], v[228:231], v[18:21]
	v_mfma_f32_16x16x32_bf16 v[6:9], v[182:185], v[246:249], v[6:9]
	v_mfma_f32_16x16x32_bf16 v[2:5], v[190:193], v[246:249], v[2:5]
	s_barrier
	s_add_i32 s66, s66, 2
	s_add_u32 s14, s14, 0x100
	s_addc_u32 s15, s15, 0
	s_add_u32 s62, s62, 0x100
	s_addc_u32 s64, s64, 0
	s_cmpk_gt_u32 s66, 0x53
	s_cbranch_scc0 .LBB0_1789
	s_and_b64 vcc, exec, s[10:11]
	s_cbranch_vccz .LBB0_1792
	s_barrier

.LBB0_1815:
	v_add_u32_e32 v174, 0x14000, v244
	v_add_u32_e32 v190, 0x18000, v244
	ds_read_b128 v[162:165], v174
	ds_read_b128 v[166:169], v174 offset:1024
	ds_read_b128 v[170:173], v174 offset:2048
	ds_read_b128 v[174:177], v174 offset:3072
	ds_read_b128 v[178:181], v190
	ds_read_b128 v[182:185], v190 offset:1024
	ds_read_b128 v[186:189], v190 offset:2048
	ds_read_b128 v[190:193], v190 offset:3072
	s_add_u32 s16, s14, 0xffe52080
	s_addc_u32 s17, s15, -1
	s_cmpk_eq_i32 s84, 0x52
	s_cselect_b32 s16, s4, s16
	s_cselect_b32 s17, s5, s17
	s_cselect_b32 s20, s12, s70
	s_cselect_b32 s21, s13, s72
	s_add_u32 s18, s16, 0x80
	s_addc_u32 s19, s17, 0
	ds_read_b128 v[194:197], v242
	ds_read_b128 v[198:201], v242 offset:1024
	ds_read_b128 v[202:205], v242 offset:2048
	ds_read_b128 v[206:209], v242 offset:3072
	ds_read_b128 v[210:213], v242 offset:4096
	ds_read_b128 v[214:217], v242 offset:5120
	ds_read_b128 v[218:221], v242 offset:6144
	ds_read_b128 v[228:231], v242 offset:7168
	ds_read_b128 v[246:249], v242 offset:8192
	ds_read_b128 v[236:239], v242 offset:9216
	s_add_u32 s74, s14, 0xfff54000
	s_addc_u32 s75, s15, -1
	s_add_i32 m0, s26, 0xd000
	s_nop 0
	global_load_lds_dwordx4 v0, s[74:75]
	s_add_u32 s74, s14, 0xfffaa000
	s_addc_u32 s75, s15, -1
	s_add_i32 m0, s26, 0xe000
	s_nop 0
	global_load_lds_dwordx4 v0, s[74:75]
	s_mov_b32 s74, s14
	s_mov_b32 s75, s15
	s_add_i32 m0, s26, 0xf000
	s_nop 0
	global_load_lds_dwordx4 v0, s[74:75]
	s_add_u32 s74, s14, 0x56000
	s_addc_u32 s75, s15, 0
	s_add_i32 m0, s26, 0x10000
	s_nop 0
	global_load_lds_dwordx4 v0, s[74:75]
	s_waitcnt vmcnt(9)
	s_waitcnt lgkmcnt(0)
	s_barrier
	v_mfma_f32_16x16x32_bf16 v[158:161], v[162:165], v[194:197], v[158:161]
	v_mfma_f32_16x16x32_bf16 v[154:157], v[170:173], v[194:197], v[154:157]
	v_mfma_f32_16x16x32_bf16 v[142:145], v[162:165], v[202:205], v[142:145]
	v_mfma_f32_16x16x32_bf16 v[138:141], v[170:173], v[202:205], v[138:141]
	v_mfma_f32_16x16x32_bf16 v[126:129], v[162:165], v[210:213], v[126:129]
	v_mfma_f32_16x16x32_bf16 v[122:125], v[170:173], v[210:213], v[122:125]
	v_mfma_f32_16x16x32_bf16 v[110:113], v[162:165], v[218:221], v[110:113]
	v_mfma_f32_16x16x32_bf16 v[106:109], v[170:173], v[218:221], v[106:109]
	v_mfma_f32_16x16x32_bf16 v[94:97], v[162:165], v[246:249], v[94:97]
	v_mfma_f32_16x16x32_bf16 v[90:93], v[170:173], v[246:249], v[90:93]
	v_mfma_f32_16x16x32_bf16 v[158:161], v[166:169], v[198:201], v[158:161]
	v_mfma_f32_16x16x32_bf16 v[154:157], v[174:177], v[198:201], v[154:157]
	v_mfma_f32_16x16x32_bf16 v[142:145], v[166:169], v[206:209], v[142:145]
	v_mfma_f32_16x16x32_bf16 v[138:141], v[174:177], v[206:209], v[138:141]
	v_mfma_f32_16x16x32_bf16 v[126:129], v[166:169], v[214:217], v[126:129]
	v_mfma_f32_16x16x32_bf16 v[122:125], v[174:177], v[214:217], v[122:125]
	v_mfma_f32_16x16x32_bf16 v[110:113], v[166:169], v[228:231], v[110:113]
	v_mfma_f32_16x16x32_bf16 v[106:109], v[174:177], v[228:231], v[106:109]
	v_mfma_f32_16x16x32_bf16 v[94:97], v[166:169], v[236:239], v[94:97]
	v_mfma_f32_16x16x32_bf16 v[90:93], v[174:177], v[236:239], v[90:93]
	v_mfma_f32_16x16x32_bf16 v[150:153], v[178:181], v[194:197], v[150:153]
	v_mfma_f32_16x16x32_bf16 v[146:149], v[186:189], v[194:197], v[146:149]
	v_mfma_f32_16x16x32_bf16 v[134:137], v[178:181], v[202:205], v[134:137]
	v_mfma_f32_16x16x32_bf16 v[130:133], v[186:189], v[202:205], v[130:133]
	v_mfma_f32_16x16x32_bf16 v[118:121], v[178:181], v[210:213], v[118:121]
	v_mfma_f32_16x16x32_bf16 v[114:117], v[186:189], v[210:213], v[114:117]
	v_mfma_f32_16x16x32_bf16 v[102:105], v[178:181], v[218:221], v[102:105]
	v_mfma_f32_16x16x32_bf16 v[98:101], v[186:189], v[218:221], v[98:101]
	v_mfma_f32_16x16x32_bf16 v[86:89], v[178:181], v[246:249], v[86:89]
	v_mfma_f32_16x16x32_bf16 v[82:85], v[186:189], v[246:249], v[82:85]
	v_mfma_f32_16x16x32_bf16 v[150:153], v[182:185], v[198:201], v[150:153]
	v_mfma_f32_16x16x32_bf16 v[146:149], v[190:193], v[198:201], v[146:149]
	v_mfma_f32_16x16x32_bf16 v[134:137], v[182:185], v[206:209], v[134:137]
	v_mfma_f32_16x16x32_bf16 v[130:133], v[190:193], v[206:209], v[130:133]
	v_mfma_f32_16x16x32_bf16 v[118:121], v[182:185], v[214:217], v[118:121]
	v_mfma_f32_16x16x32_bf16 v[114:117], v[190:193], v[214:217], v[114:117]
	v_mfma_f32_16x16x32_bf16 v[102:105], v[182:185], v[228:231], v[102:105]
	v_mfma_f32_16x16x32_bf16 v[98:101], v[190:193], v[228:231], v[98:101]
	v_mfma_f32_16x16x32_bf16 v[86:89], v[182:185], v[236:239], v[86:89]
	v_mfma_f32_16x16x32_bf16 v[82:85], v[190:193], v[236:239], v[82:85]
	s_barrier
	ds_read_b128 v[194:197], v242 offset:20480
	ds_read_b128 v[198:201], v242 offset:21504
	ds_read_b128 v[202:205], v242 offset:22528
	ds_read_b128 v[206:209], v242 offset:23552
	ds_read_b128 v[210:213], v242 offset:24576
	ds_read_b128 v[214:217], v242 offset:25600
	ds_read_b128 v[218:221], v242 offset:26624
	ds_read_b128 v[228:231], v242 offset:27648
	ds_read_b128 v[236:239], v242 offset:28672
	ds_read_b128 v[246:249], v242 offset:29696
	s_mov_b32 s74, s20
	s_mov_b32 s75, s21
	s_add_i32 m0, s26, 0x14000
	s_nop 0
	global_load_lds_dwordx4 v241, s[74:75]
	s_add_u32 s74, s20, 0x56000
	s_addc_u32 s75, s21, 0
	s_add_i32 m0, s26, 0x15000
	s_nop 0
	global_load_lds_dwordx4 v241, s[74:75]
	s_add_u32 s74, s20, 0xac000
	s_addc_u32 s75, s21, 0
	s_add_i32 m0, s26, 0x16000
	s_nop 0
	global_load_lds_dwordx4 v241, s[74:75]
	s_add_u32 s74, s20, 0x102000
	s_addc_u32 s75, s21, 0
	s_add_i32 m0, s26, 0x17000
	s_nop 0
	global_load_lds_dwordx4 v241, s[74:75]
	s_add_u32 s74, s16, 0xac000
	s_addc_u32 s75, s17, 0
	s_add_i32 m0, s26, 0x2000
	s_nop 0
	global_load_lds_dwordx4 v0, s[74:75]
	s_waitcnt vmcnt(9)
	s_waitcnt lgkmcnt(0)
	s_barrier
	v_mfma_f32_16x16x32_bf16 v[78:81], v[162:165], v[194:197], v[78:81]
	v_mfma_f32_16x16x32_bf16 v[74:77], v[170:173], v[194:197], v[74:77]
	v_mfma_f32_16x16x32_bf16 v[62:65], v[162:165], v[202:205], v[62:65]
	v_mfma_f32_16x16x32_bf16 v[58:61], v[170:173], v[202:205], v[58:61]
	v_mfma_f32_16x16x32_bf16 v[46:49], v[162:165], v[210:213], v[46:49]
	v_mfma_f32_16x16x32_bf16 v[42:45], v[170:173], v[210:213], v[42:45]
	v_mfma_f32_16x16x32_bf16 v[30:33], v[162:165], v[218:221], v[30:33]
	v_mfma_f32_16x16x32_bf16 v[26:29], v[170:173], v[218:221], v[26:29]
	v_mfma_f32_16x16x32_bf16 v[14:17], v[162:165], v[236:239], v[14:17]
	v_mfma_f32_16x16x32_bf16 v[10:13], v[170:173], v[236:239], v[10:13]
	v_mfma_f32_16x16x32_bf16 v[78:81], v[166:169], v[198:201], v[78:81]
	v_mfma_f32_16x16x32_bf16 v[74:77], v[174:177], v[198:201], v[74:77]
	v_mfma_f32_16x16x32_bf16 v[62:65], v[166:169], v[206:209], v[62:65]
	v_mfma_f32_16x16x32_bf16 v[58:61], v[174:177], v[206:209], v[58:61]
	v_mfma_f32_16x16x32_bf16 v[46:49], v[166:169], v[214:217], v[46:49]
	v_mfma_f32_16x16x32_bf16 v[42:45], v[174:177], v[214:217], v[42:45]
	v_mfma_f32_16x16x32_bf16 v[30:33], v[166:169], v[228:231], v[30:33]
	v_mfma_f32_16x16x32_bf16 v[26:29], v[174:177], v[228:231], v[26:29]
	v_mfma_f32_16x16x32_bf16 v[14:17], v[166:169], v[246:249], v[14:17]
	v_mfma_f32_16x16x32_bf16 v[10:13], v[174:177], v[246:249], v[10:13]
	v_mfma_f32_16x16x32_bf16 v[70:73], v[178:181], v[194:197], v[70:73]
	v_mfma_f32_16x16x32_bf16 v[66:69], v[186:189], v[194:197], v[66:69]
	v_mfma_f32_16x16x32_bf16 v[54:57], v[178:181], v[202:205], v[54:57]
	v_mfma_f32_16x16x32_bf16 v[50:53], v[186:189], v[202:205], v[50:53]
	v_mfma_f32_16x16x32_bf16 v[38:41], v[178:181], v[210:213], v[38:41]
	v_mfma_f32_16x16x32_bf16 v[34:37], v[186:189], v[210:213], v[34:37]
	v_mfma_f32_16x16x32_bf16 v[22:25], v[178:181], v[218:221], v[22:25]
	v_mfma_f32_16x16x32_bf16 v[18:21], v[186:189], v[218:221], v[18:21]
	v_mfma_f32_16x16x32_bf16 v[6:9], v[178:181], v[236:239], v[6:9]
	v_mfma_f32_16x16x32_bf16 v[2:5], v[186:189], v[236:239], v[2:5]
	v_mfma_f32_16x16x32_bf16 v[70:73], v[182:185], v[198:201], v[70:73]
	v_mfma_f32_16x16x32_bf16 v[66:69], v[190:193], v[198:201], v[66:69]
	v_mfma_f32_16x16x32_bf16 v[54:57], v[182:185], v[206:209], v[54:57]
	v_mfma_f32_16x16x32_bf16 v[50:53], v[190:193], v[206:209], v[50:53]
	v_mfma_f32_16x16x32_bf16 v[38:41], v[182:185], v[214:217], v[38:41]
	v_mfma_f32_16x16x32_bf16 v[34:37], v[190:193], v[214:217], v[34:37]
	v_mfma_f32_16x16x32_bf16 v[22:25], v[182:185], v[228:231], v[22:25]
	v_mfma_f32_16x16x32_bf16 v[18:21], v[190:193], v[228:231], v[18:21]
	v_mfma_f32_16x16x32_bf16 v[6:9], v[182:185], v[246:249], v[6:9]
	v_mfma_f32_16x16x32_bf16 v[2:5], v[190:193], v[246:249], v[2:5]
	s_barrier
	v_add_u32_e32 v174, 0x1c000, v244
	v_add_u32_e32 v190, 0x20000, v244
	ds_read_b128 v[162:165], v174
	ds_read_b128 v[166:169], v174 offset:1024
	ds_read_b128 v[170:173], v174 offset:2048
	ds_read_b128 v[174:177], v174 offset:3072
	ds_read_b128 v[178:181], v190
	ds_read_b128 v[182:185], v190 offset:1024
	ds_read_b128 v[186:189], v190 offset:2048
	ds_read_b128 v[190:193], v190 offset:3072
	ds_read_b128 v[194:197], v242 offset:40960
	ds_read_b128 v[198:201], v242 offset:41984
	ds_read_b128 v[202:205], v242 offset:43008
	ds_read_b128 v[206:209], v242 offset:44032
	ds_read_b128 v[210:213], v242 offset:45056
	ds_read_b128 v[214:217], v242 offset:46080
	ds_read_b128 v[218:221], v242 offset:47104
	ds_read_b128 v[228:231], v242 offset:48128
	ds_read_b128 v[236:239], v242 offset:49152
	ds_read_b128 v[246:249], v242 offset:50176
	s_add_u32 s74, s16, 0x102000
	s_addc_u32 s75, s17, 0
	s_add_i32 m0, s26, 0x3000
	s_nop 0
	global_load_lds_dwordx4 v0, s[74:75]
	s_add_u32 s74, s16, 0x158000
	s_addc_u32 s75, s17, 0
	s_add_i32 m0, s26, 0x4000
	s_nop 0
	global_load_lds_dwordx4 v0, s[74:75]
	s_add_u32 s74, s16, 0x1ae000
	s_addc_u32 s75, s17, 0
	s_add_i32 m0, s26, 0x5000
	s_nop 0
	global_load_lds_dwordx4 v0, s[74:75]
	s_add_u32 s74, s16, 0x204000
	s_addc_u32 s75, s17, 0
	s_add_i32 m0, s26, 0x6000
	s_nop 0
	global_load_lds_dwordx4 v0, s[74:75]
	s_waitcnt vmcnt(9)
	s_waitcnt lgkmcnt(0)
	s_barrier
	v_mfma_f32_16x16x32_bf16 v[158:161], v[162:165], v[194:197], v[158:161]
	v_mfma_f32_16x16x32_bf16 v[154:157], v[170:173], v[194:197], v[154:157]
	v_mfma_f32_16x16x32_bf16 v[142:145], v[162:165], v[202:205], v[142:145]
	v_mfma_f32_16x16x32_bf16 v[138:141], v[170:173], v[202:205], v[138:141]
	v_mfma_f32_16x16x32_bf16 v[126:129], v[162:165], v[210:213], v[126:129]
	v_mfma_f32_16x16x32_bf16 v[122:125], v[170:173], v[210:213], v[122:125]
	v_mfma_f32_16x16x32_bf16 v[110:113], v[162:165], v[218:221], v[110:113]
	v_mfma_f32_16x16x32_bf16 v[106:109], v[170:173], v[218:221], v[106:109]
	v_mfma_f32_16x16x32_bf16 v[94:97], v[162:165], v[236:239], v[94:97]
	v_mfma_f32_16x16x32_bf16 v[90:93], v[170:173], v[236:239], v[90:93]
	v_mfma_f32_16x16x32_bf16 v[158:161], v[166:169], v[198:201], v[158:161]
	v_mfma_f32_16x16x32_bf16 v[154:157], v[174:177], v[198:201], v[154:157]
	v_mfma_f32_16x16x32_bf16 v[142:145], v[166:169], v[206:209], v[142:145]
	v_mfma_f32_16x16x32_bf16 v[138:141], v[174:177], v[206:209], v[138:141]
	v_mfma_f32_16x16x32_bf16 v[126:129], v[166:169], v[214:217], v[126:129]
	v_mfma_f32_16x16x32_bf16 v[122:125], v[174:177], v[214:217], v[122:125]
	v_mfma_f32_16x16x32_bf16 v[110:113], v[166:169], v[228:231], v[110:113]
	v_mfma_f32_16x16x32_bf16 v[106:109], v[174:177], v[228:231], v[106:109]
	v_mfma_f32_16x16x32_bf16 v[94:97], v[166:169], v[246:249], v[94:97]
	v_mfma_f32_16x16x32_bf16 v[90:93], v[174:177], v[246:249], v[90:93]
	v_mfma_f32_16x16x32_bf16 v[150:153], v[178:181], v[194:197], v[150:153]
	v_mfma_f32_16x16x32_bf16 v[146:149], v[186:189], v[194:197], v[146:149]
	v_mfma_f32_16x16x32_bf16 v[134:137], v[178:181], v[202:205], v[134:137]
	v_mfma_f32_16x16x32_bf16 v[130:133], v[186:189], v[202:205], v[130:133]
	v_mfma_f32_16x16x32_bf16 v[118:121], v[178:181], v[210:213], v[118:121]
	v_mfma_f32_16x16x32_bf16 v[114:117], v[186:189], v[210:213], v[114:117]
	v_mfma_f32_16x16x32_bf16 v[102:105], v[178:181], v[218:221], v[102:105]
	v_mfma_f32_16x16x32_bf16 v[98:101], v[186:189], v[218:221], v[98:101]
	v_mfma_f32_16x16x32_bf16 v[86:89], v[178:181], v[236:239], v[86:89]
	v_mfma_f32_16x16x32_bf16 v[82:85], v[186:189], v[236:239], v[82:85]
	v_mfma_f32_16x16x32_bf16 v[150:153], v[182:185], v[198:201], v[150:153]
	v_mfma_f32_16x16x32_bf16 v[146:149], v[190:193], v[198:201], v[146:149]
	v_mfma_f32_16x16x32_bf16 v[134:137], v[182:185], v[206:209], v[134:137]
	v_mfma_f32_16x16x32_bf16 v[130:133], v[190:193], v[206:209], v[130:133]
	v_mfma_f32_16x16x32_bf16 v[118:121], v[182:185], v[214:217], v[118:121]
	v_mfma_f32_16x16x32_bf16 v[114:117], v[190:193], v[214:217], v[114:117]
	v_mfma_f32_16x16x32_bf16 v[102:105], v[182:185], v[228:231], v[102:105]
	v_mfma_f32_16x16x32_bf16 v[98:101], v[190:193], v[228:231], v[98:101]
	v_mfma_f32_16x16x32_bf16 v[86:89], v[182:185], v[246:249], v[86:89]
	v_mfma_f32_16x16x32_bf16 v[82:85], v[190:193], v[246:249], v[82:85]
	s_barrier
	ds_read_b128 v[194:197], v242 offset:61440
	ds_read_b128 v[198:201], v242 offset:62464
	ds_read_b128 v[202:205], v242 offset:63488
	ds_read_b128 v[206:209], v242 offset:64512
	ds_read_b128 v[210:213], v243 offset:4096
	ds_read_b128 v[214:217], v243 offset:5120
	ds_read_b128 v[218:221], v243 offset:6144
	ds_read_b128 v[228:231], v243 offset:7168
	ds_read_b128 v[236:239], v243 offset:8192
	ds_read_b128 v[246:249], v243 offset:9216
	s_add_u32 s18, s16, 0xac080
	s_addc_u32 s19, s17, 0
	s_add_u32 s74, s20, 0x80
	s_addc_u32 s75, s21, 0
	s_add_i32 m0, s26, 0x1c000
	s_nop 0
	global_load_lds_dwordx4 v241, s[74:75]
	s_add_u32 s74, s20, 0x56080
	s_addc_u32 s75, s21, 0
	s_add_i32 m0, s26, 0x1d000
	s_nop 0
	global_load_lds_dwordx4 v241, s[74:75]
	s_add_u32 s74, s20, 0xac080
	s_addc_u32 s75, s21, 0
	s_add_i32 m0, s26, 0x1e000
	s_nop 0
	global_load_lds_dwordx4 v241, s[74:75]
	s_add_u32 s74, s20, 0x102080
	s_addc_u32 s75, s21, 0
	s_add_i32 m0, s26, 0x1f000
	s_nop 0
	global_load_lds_dwordx4 v241, s[74:75]
	s_add_u32 s74, s16, 0xac080
	s_addc_u32 s75, s17, 0
	s_add_i32 m0, s26, 0xc000
	s_nop 0
	global_load_lds_dwordx4 v0, s[74:75]
	s_waitcnt vmcnt(9)
	s_waitcnt lgkmcnt(0)
	s_barrier
	v_mfma_f32_16x16x32_bf16 v[78:81], v[162:165], v[194:197], v[78:81]
	v_mfma_f32_16x16x32_bf16 v[74:77], v[170:173], v[194:197], v[74:77]
	v_mfma_f32_16x16x32_bf16 v[62:65], v[162:165], v[202:205], v[62:65]
	v_mfma_f32_16x16x32_bf16 v[58:61], v[170:173], v[202:205], v[58:61]
	v_mfma_f32_16x16x32_bf16 v[46:49], v[162:165], v[210:213], v[46:49]
	v_mfma_f32_16x16x32_bf16 v[42:45], v[170:173], v[210:213], v[42:45]
	v_mfma_f32_16x16x32_bf16 v[30:33], v[162:165], v[218:221], v[30:33]
	v_mfma_f32_16x16x32_bf16 v[26:29], v[170:173], v[218:221], v[26:29]
	v_mfma_f32_16x16x32_bf16 v[14:17], v[162:165], v[236:239], v[14:17]
	v_mfma_f32_16x16x32_bf16 v[10:13], v[170:173], v[236:239], v[10:13]
	v_mfma_f32_16x16x32_bf16 v[78:81], v[166:169], v[198:201], v[78:81]
	v_mfma_f32_16x16x32_bf16 v[74:77], v[174:177], v[198:201], v[74:77]
	v_mfma_f32_16x16x32_bf16 v[62:65], v[166:169], v[206:209], v[62:65]
	v_mfma_f32_16x16x32_bf16 v[58:61], v[174:177], v[206:209], v[58:61]
	v_mfma_f32_16x16x32_bf16 v[46:49], v[166:169], v[214:217], v[46:49]
	v_mfma_f32_16x16x32_bf16 v[42:45], v[174:177], v[214:217], v[42:45]
	v_mfma_f32_16x16x32_bf16 v[30:33], v[166:169], v[228:231], v[30:33]
	v_mfma_f32_16x16x32_bf16 v[26:29], v[174:177], v[228:231], v[26:29]
	v_mfma_f32_16x16x32_bf16 v[14:17], v[166:169], v[246:249], v[14:17]
	v_mfma_f32_16x16x32_bf16 v[10:13], v[174:177], v[246:249], v[10:13]
	v_mfma_f32_16x16x32_bf16 v[70:73], v[178:181], v[194:197], v[70:73]
	v_mfma_f32_16x16x32_bf16 v[66:69], v[186:189], v[194:197], v[66:69]
	v_mfma_f32_16x16x32_bf16 v[54:57], v[178:181], v[202:205], v[54:57]
	v_mfma_f32_16x16x32_bf16 v[50:53], v[186:189], v[202:205], v[50:53]
	v_mfma_f32_16x16x32_bf16 v[38:41], v[178:181], v[210:213], v[38:41]
	v_mfma_f32_16x16x32_bf16 v[34:37], v[186:189], v[210:213], v[34:37]
	v_mfma_f32_16x16x32_bf16 v[22:25], v[178:181], v[218:221], v[22:25]
	v_mfma_f32_16x16x32_bf16 v[18:21], v[186:189], v[218:221], v[18:21]
	v_mfma_f32_16x16x32_bf16 v[6:9], v[178:181], v[236:239], v[6:9]
	v_mfma_f32_16x16x32_bf16 v[2:5], v[186:189], v[236:239], v[2:5]
	v_mfma_f32_16x16x32_bf16 v[70:73], v[182:185], v[198:201], v[70:73]
	v_mfma_f32_16x16x32_bf16 v[66:69], v[190:193], v[198:201], v[66:69]
	v_mfma_f32_16x16x32_bf16 v[54:57], v[182:185], v[206:209], v[54:57]
	v_mfma_f32_16x16x32_bf16 v[50:53], v[190:193], v[206:209], v[50:53]
	v_mfma_f32_16x16x32_bf16 v[38:41], v[182:185], v[214:217], v[38:41]
	v_mfma_f32_16x16x32_bf16 v[34:37], v[190:193], v[214:217], v[34:37]
	v_mfma_f32_16x16x32_bf16 v[22:25], v[182:185], v[228:231], v[22:25]
	v_mfma_f32_16x16x32_bf16 v[18:21], v[190:193], v[228:231], v[18:21]
	v_mfma_f32_16x16x32_bf16 v[6:9], v[182:185], v[246:249], v[6:9]
	v_mfma_f32_16x16x32_bf16 v[2:5], v[190:193], v[246:249], v[2:5]
	s_barrier
	s_add_i32 s84, s84, 2
	s_add_u32 s14, s14, 0x100
	s_addc_u32 s15, s15, 0
	s_add_u32 s70, s70, 0x100
	s_addc_u32 s72, s72, 0
	s_cmpk_gt_u32 s84, 0x53
	s_cbranch_scc0 .LBB0_1815
	s_and_b64 vcc, exec, s[10:11]
	s_cbranch_vccz .LBB0_1818
	s_barrier
